# token-owned PEER gather (3 tokens per round, 8 expert ranges, sorted LDS work list, two streaming passes) plus the G1/G4 mainloop edits
# speedup vs baseline: 1.7496x; 1.0019x over previous
.LBB1_31:
	s_movk_i32 s58, 0x41ff
	s_mov_b64 s[30:31], -1
	s_mov_b64 s[38:39], 0
	s_cmp_lt_i32 s26, 7
	s_mov_b64 s[28:29], 0
	s_cbranch_scc1 .LBB1_93
	s_cmp_gt_i32 s26, 8
	s_cbranch_scc0 .LBB1_76
	s_cmp_gt_i32 s26, 9
	s_cbranch_scc0 .LBB1_70
	s_cmp_gt_i32 s26, 11
	s_mov_b64 s[40:41], -1
	s_cbranch_scc0 .LBB1_49
	s_mov_b64 exec, -1
	v_lshrrev_b32_e32 v138, 6, v162
	v_readlane_b32 s2, v242, 0
	v_readlane_b32 s59, v241, 24
	v_readfirstlane_b32 s54, v138
	s_load_dwordx4 s[92:95], s[0:1], 0xc0
	s_load_dwordx4 s[88:91], s[0:1], 0x1a8
	s_mul_i32 s17, s54, 0x2000
	s_add_u32 s17, s17, 16
	s_lshl_b32 s2, s2, 2
	s_add_u32 s54, s54, s2
	v_lshlrev_b32_e32 v158, 2, v168
	v_lshlrev_b32_e32 v157, 4, v168
	v_lshlrev_b32_e32 v159, 5, v168
	v_lshlrev_b32_e32 v160, 6, v168
	v_add_u32_e32 v161, s17, v158
	v_readlane_b32 s44, v240, 6
	v_readlane_b32 s45, v240, 7
	v_readlane_b32 s40, v240, 8
	v_readlane_b32 s41, v240, 9
	v_readlane_b32 s42, v240, 10
	v_readlane_b32 s43, v240, 11
	s_lshl_b32 s19, s27, 1
	s_waitcnt lgkmcnt(0)
	s_nop 4
.Lgx_round_1:
	s_mov_b32 s2, s54
	s_min_u32 s2, s2, 0x41ff
	s_lshl_b32 s50, s2, 9
	s_add_u32 s52, s88, s50
	s_addc_u32 s53, s89, 0
	global_load_dword v188, v158, s[52:53]
	global_load_dword v189, v158, s[52:53] offset:256
	s_add_u32 s52, s90, s50
	s_addc_u32 s53, s91, 0
	global_load_dword v200, v158, s[52:53]
	global_load_dword v201, v158, s[52:53] offset:256
	s_lshl_b32 s50, s2, 11
	s_add_u32 s52, s74, s50
	s_addc_u32 s53, s75, 0
	global_load_dwordx4 v[216:219], v159, s[52:53]
	global_load_dwordx4 v[220:223], v159, s[52:53] offset:16
	s_add_u32 s2, s54, s59
	s_min_u32 s2, s2, 0x41ff
	s_lshl_b32 s50, s2, 9
	s_add_u32 s52, s88, s50
	s_addc_u32 s53, s89, 0
	global_load_dword v190, v158, s[52:53]
	global_load_dword v191, v158, s[52:53] offset:256
	s_add_u32 s52, s90, s50
	s_addc_u32 s53, s91, 0
	global_load_dword v202, v158, s[52:53]
	global_load_dword v203, v158, s[52:53] offset:256
	s_lshl_b32 s50, s2, 11
	s_add_u32 s52, s74, s50
	s_addc_u32 s53, s75, 0
	global_load_dwordx4 v[224:227], v159, s[52:53]
	global_load_dwordx4 v[228:231], v159, s[52:53] offset:16
	s_add_u32 s2, s54, s59
	s_add_u32 s2, s2, s59
	s_min_u32 s2, s2, 0x41ff
	s_lshl_b32 s50, s2, 9
	s_add_u32 s52, s88, s50
	s_addc_u32 s53, s89, 0
	global_load_dword v192, v158, s[52:53]
	global_load_dword v193, v158, s[52:53] offset:256
	s_add_u32 s52, s90, s50
	s_addc_u32 s53, s91, 0
	global_load_dword v204, v158, s[52:53]
	global_load_dword v205, v158, s[52:53] offset:256
	s_lshl_b32 s50, s2, 11
	s_add_u32 s52, s74, s50
	s_addc_u32 s53, s75, 0
	global_load_dwordx4 v[232:235], v159, s[52:53]
	global_load_dwordx4 v[236:239], v159, s[52:53] offset:16
	s_add_u32 s50, s44, 0x10000
	s_addc_u32 s51, s45, 0
	s_waitcnt vmcnt(16)
	v_lshlrev_b32_e32 v138, 2, v188
	v_lshlrev_b32_e32 v139, 2, v189
	global_load_dword v194, v138, s[44:45]
	global_load_dword v206, v138, s[50:51]
	global_load_dword v195, v139, s[44:45]
	global_load_dword v207, v139, s[50:51]
	s_waitcnt vmcnt(14)
	v_lshlrev_b32_e32 v138, 2, v190
	v_lshlrev_b32_e32 v139, 2, v191
	global_load_dword v196, v138, s[44:45]
	global_load_dword v208, v138, s[50:51]
	global_load_dword v197, v139, s[44:45]
	global_load_dword v209, v139, s[50:51]
	s_waitcnt vmcnt(12)
	v_lshlrev_b32_e32 v138, 2, v192
	v_lshlrev_b32_e32 v139, 2, v193
	global_load_dword v198, v138, s[44:45]
	global_load_dword v210, v138, s[50:51]
	global_load_dword v199, v139, s[44:45]
	global_load_dword v211, v139, s[50:51]
	s_waitcnt vmcnt(0)
	v_lshlrev_b32_e32 v0, 16, v216
	v_and_b32_e32 v1, 0xffff0000, v216
	v_lshlrev_b32_e32 v2, 16, v217
	v_and_b32_e32 v3, 0xffff0000, v217
	v_lshlrev_b32_e32 v4, 16, v218
	v_and_b32_e32 v5, 0xffff0000, v218
	v_lshlrev_b32_e32 v6, 16, v219
	v_and_b32_e32 v7, 0xffff0000, v219
	v_lshlrev_b32_e32 v8, 16, v220
	v_and_b32_e32 v9, 0xffff0000, v220
	v_lshlrev_b32_e32 v10, 16, v221
	v_and_b32_e32 v11, 0xffff0000, v221
	v_lshlrev_b32_e32 v12, 16, v222
	v_and_b32_e32 v13, 0xffff0000, v222
	v_lshlrev_b32_e32 v14, 16, v223
	v_and_b32_e32 v15, 0xffff0000, v223
	v_lshlrev_b32_e32 v16, 16, v224
	v_and_b32_e32 v17, 0xffff0000, v224
	v_lshlrev_b32_e32 v18, 16, v225
	v_and_b32_e32 v19, 0xffff0000, v225
	v_lshlrev_b32_e32 v20, 16, v226
	v_and_b32_e32 v21, 0xffff0000, v226
	v_lshlrev_b32_e32 v22, 16, v227
	v_and_b32_e32 v23, 0xffff0000, v227
	v_lshlrev_b32_e32 v24, 16, v228
	v_and_b32_e32 v25, 0xffff0000, v228
	v_lshlrev_b32_e32 v26, 16, v229
	v_and_b32_e32 v27, 0xffff0000, v229
	v_lshlrev_b32_e32 v28, 16, v230
	v_and_b32_e32 v29, 0xffff0000, v230
	v_lshlrev_b32_e32 v30, 16, v231
	v_and_b32_e32 v31, 0xffff0000, v231
	v_lshlrev_b32_e32 v32, 16, v232
	v_and_b32_e32 v33, 0xffff0000, v232
	v_lshlrev_b32_e32 v34, 16, v233
	v_and_b32_e32 v35, 0xffff0000, v233
	v_lshlrev_b32_e32 v36, 16, v234
	v_and_b32_e32 v37, 0xffff0000, v234
	v_lshlrev_b32_e32 v38, 16, v235
	v_and_b32_e32 v39, 0xffff0000, v235
	v_lshlrev_b32_e32 v40, 16, v236
	v_and_b32_e32 v41, 0xffff0000, v236
	v_lshlrev_b32_e32 v42, 16, v237
	v_and_b32_e32 v43, 0xffff0000, v237
	v_lshlrev_b32_e32 v44, 16, v238
	v_and_b32_e32 v45, 0xffff0000, v238
	v_lshlrev_b32_e32 v46, 16, v239
	v_and_b32_e32 v47, 0xffff0000, v239
	v_mul_f32_e32 v200, v200, v206
	v_mul_f32_e32 v201, v201, v207
	v_mul_f32_e32 v202, v202, v208
	v_mul_f32_e32 v203, v203, v209
	v_mul_f32_e32 v204, v204, v210
	v_mul_f32_e32 v205, v205, v211
	v_lshrrev_b32_e32 v206, 11, v188
	v_lshrrev_b32_e32 v207, 11, v189
	v_lshrrev_b32_e32 v208, 11, v190
	v_lshrrev_b32_e32 v209, 11, v191
	s_add_u32 s2, s54, s59
	s_cmp_lt_u32 s2, 0x4200
	s_cbranch_scc1 .Lgx_kvalid_2
	v_mov_b32_e32 v208, 8
	v_mov_b32_e32 v209, 8
.Lgx_kvalid_2:
	v_lshrrev_b32_e32 v210, 11, v192
	v_lshrrev_b32_e32 v211, 11, v193
	s_add_u32 s2, s54, s59
	s_add_u32 s2, s2, s59
	s_cmp_lt_u32 s2, 0x4200
	s_cbranch_scc1 .Lgx_kvalid_3
	v_mov_b32_e32 v210, 8
	v_mov_b32_e32 v211, 8
.Lgx_kvalid_3:
	s_mov_b32 s32, 0
	s_mov_b32 s98, 0
	s_mov_b32 s99, 0
	s_mov_b32 s15, 0
.Lgx_sortk_4:
	v_cmp_eq_u32_e64 s[4:5], s99, v206
	v_cmp_eq_u32_e64 s[6:7], s99, v207
	s_bcnt1_i32_b64 s8, s[4:5]
	s_bcnt1_i32_b64 s9, s[6:7]
	s_add_u32 s10, s8, s9
	s_cmp_eq_u32 s10, 0
	s_cbranch_scc1 .Lgx_sortskip_5
	v_mbcnt_lo_u32_b32 v138, s4, 0
	v_mbcnt_hi_u32_b32 v138, s5, v138
	v_mbcnt_lo_u32_b32 v139, s6, 0
	v_mbcnt_hi_u32_b32 v139, s7, v139
	s_add_u32 s11, s32, s8
	v_add_u32_e32 v138, s32, v138
	v_add_u32_e32 v139, s11, v139
	v_lshl_add_u32 v138, v138, 2, s17
	v_lshl_add_u32 v139, v139, 2, s17
	v_lshlrev_b32_e32 v140, 10, v188
	v_lshlrev_b32_e32 v141, 10, v189
	s_mov_b64 exec, s[4:5]
	ds_write_b32 v138, v140 offset:0
	ds_write_b32 v138, v194 offset:2368
	ds_write_b32 v138, v200 offset:4736
	s_mov_b64 exec, s[6:7]
	ds_write_b32 v139, v141 offset:0
	ds_write_b32 v139, v195 offset:2368
	ds_write_b32 v139, v201 offset:4736
	s_sub_u32 s12, 0, s10
	s_and_b32 s12, s12, 7
	s_add_u32 s13, s32, s10
	s_lshl_b32 s14, 1, s12
	s_sub_u32 s14, s14, 1
	s_mov_b64 exec, s[14:15]
	v_add_u32_e32 v142, s13, v168
	v_lshl_add_u32 v142, v142, 2, s17
	ds_write_b32 v142, v129 offset:0
	ds_write_b32 v142, v129 offset:2368
	ds_write_b32 v142, v129 offset:4736
	s_add_u32 s16, s10, 7
	s_lshr_b32 s16, s16, 3
	s_lshl_b32 s14, 1, s16
	s_sub_u32 s14, s14, 1
	s_mov_b64 exec, s[14:15]
	v_add_u32_e32 v143, s98, v168
	v_lshl_add_u32 v143, v143, 2, s17
	v_mov_b32_e32 v144, 0
	ds_write_b32 v143, v144 offset:7104
	s_mov_b64 exec, -1
	s_add_u32 s32, s13, s12
	s_add_u32 s98, s98, s16
.Lgx_sortskip_5:
	v_cmp_eq_u32_e64 s[4:5], s99, v208
	v_cmp_eq_u32_e64 s[6:7], s99, v209
	s_bcnt1_i32_b64 s8, s[4:5]
	s_bcnt1_i32_b64 s9, s[6:7]
	s_add_u32 s10, s8, s9
	s_cmp_eq_u32 s10, 0
	s_cbranch_scc1 .Lgx_sortskip_6
	v_mbcnt_lo_u32_b32 v138, s4, 0
	v_mbcnt_hi_u32_b32 v138, s5, v138
	v_mbcnt_lo_u32_b32 v139, s6, 0
	v_mbcnt_hi_u32_b32 v139, s7, v139
	s_add_u32 s11, s32, s8
	v_add_u32_e32 v138, s32, v138
	v_add_u32_e32 v139, s11, v139
	v_lshl_add_u32 v138, v138, 2, s17
	v_lshl_add_u32 v139, v139, 2, s17
	v_lshlrev_b32_e32 v140, 10, v190
	v_lshlrev_b32_e32 v141, 10, v191
	s_mov_b64 exec, s[4:5]
	ds_write_b32 v138, v140 offset:0
	ds_write_b32 v138, v196 offset:2368
	ds_write_b32 v138, v202 offset:4736
	s_mov_b64 exec, s[6:7]
	ds_write_b32 v139, v141 offset:0
	ds_write_b32 v139, v197 offset:2368
	ds_write_b32 v139, v203 offset:4736
	s_sub_u32 s12, 0, s10
	s_and_b32 s12, s12, 7
	s_add_u32 s13, s32, s10
	s_lshl_b32 s14, 1, s12
	s_sub_u32 s14, s14, 1
	s_mov_b64 exec, s[14:15]
	v_add_u32_e32 v142, s13, v168
	v_lshl_add_u32 v142, v142, 2, s17
	ds_write_b32 v142, v129 offset:0
	ds_write_b32 v142, v129 offset:2368
	ds_write_b32 v142, v129 offset:4736
	s_add_u32 s16, s10, 7
	s_lshr_b32 s16, s16, 3
	s_lshl_b32 s14, 1, s16
	s_sub_u32 s14, s14, 1
	s_mov_b64 exec, s[14:15]
	v_add_u32_e32 v143, s98, v168
	v_lshl_add_u32 v143, v143, 2, s17
	v_mov_b32_e32 v144, 1
	ds_write_b32 v143, v144 offset:7104
	s_mov_b64 exec, -1
	s_add_u32 s32, s13, s12
	s_add_u32 s98, s98, s16
.Lgx_sortskip_6:
	v_cmp_eq_u32_e64 s[4:5], s99, v210
	v_cmp_eq_u32_e64 s[6:7], s99, v211
	s_bcnt1_i32_b64 s8, s[4:5]
	s_bcnt1_i32_b64 s9, s[6:7]
	s_add_u32 s10, s8, s9
	s_cmp_eq_u32 s10, 0
	s_cbranch_scc1 .Lgx_sortskip_7
	v_mbcnt_lo_u32_b32 v138, s4, 0
	v_mbcnt_hi_u32_b32 v138, s5, v138
	v_mbcnt_lo_u32_b32 v139, s6, 0
	v_mbcnt_hi_u32_b32 v139, s7, v139
	s_add_u32 s11, s32, s8
	v_add_u32_e32 v138, s32, v138
	v_add_u32_e32 v139, s11, v139
	v_lshl_add_u32 v138, v138, 2, s17
	v_lshl_add_u32 v139, v139, 2, s17
	v_lshlrev_b32_e32 v140, 10, v192
	v_lshlrev_b32_e32 v141, 10, v193
	s_mov_b64 exec, s[4:5]
	ds_write_b32 v138, v140 offset:0
	ds_write_b32 v138, v198 offset:2368
	ds_write_b32 v138, v204 offset:4736
	s_mov_b64 exec, s[6:7]
	ds_write_b32 v139, v141 offset:0
	ds_write_b32 v139, v199 offset:2368
	ds_write_b32 v139, v205 offset:4736
	s_sub_u32 s12, 0, s10
	s_and_b32 s12, s12, 7
	s_add_u32 s13, s32, s10
	s_lshl_b32 s14, 1, s12
	s_sub_u32 s14, s14, 1
	s_mov_b64 exec, s[14:15]
	v_add_u32_e32 v142, s13, v168
	v_lshl_add_u32 v142, v142, 2, s17
	ds_write_b32 v142, v129 offset:0
	ds_write_b32 v142, v129 offset:2368
	ds_write_b32 v142, v129 offset:4736
	s_add_u32 s16, s10, 7
	s_lshr_b32 s16, s16, 3
	s_lshl_b32 s14, 1, s16
	s_sub_u32 s14, s14, 1
	s_mov_b64 exec, s[14:15]
	v_add_u32_e32 v143, s98, v168
	v_lshl_add_u32 v143, v143, 2, s17
	v_mov_b32_e32 v144, 2
	ds_write_b32 v143, v144 offset:7104
	s_mov_b64 exec, -1
	s_add_u32 s32, s13, s12
	s_add_u32 s98, s98, s16
.Lgx_sortskip_7:
	s_add_u32 s99, s99, 1
	s_cmp_lt_u32 s99, 8
	s_cbranch_scc1 .Lgx_sortk_4
	s_mov_b32 s14, -1
	s_mov_b64 exec, s[14:15]
	v_add_u32_e32 v142, s32, v168
	v_lshl_add_u32 v142, v142, 2, s17
	ds_write_b32 v142, v129 offset:0
	ds_write_b32 v142, v129 offset:2368
	ds_write_b32 v142, v129 offset:4736
	s_mov_b32 s14, 15
	s_mov_b64 exec, s[14:15]
	v_add_u32_e32 v143, s98, v168
	v_lshl_add_u32 v143, v143, 2, s17
	ds_write_b32 v143, v129 offset:7104
	s_mov_b64 exec, -1
	s_add_u32 s28, s98, 1
	s_and_b32 s28, s28, -2
	s_waitcnt lgkmcnt(0)
	ds_read_b32 v138, v161 offset:0
	v_and_b32_e32 v154, 7, v168
	v_lshrrev_b32_e32 v155, 3, v168
	v_mov_b32_e32 v156, s17
	v_lshl_add_u32 v154, v154, 2, s17
	v_lshl_add_u32 v155, v155, 2, s17
	s_waitcnt lgkmcnt(0)
	v_readlane_b32 s2, v138, 0
	s_add_u32 s46, s40, s2
	s_addc_u32 s47, s41, 0
	global_load_dwordx4 v[48:51], v157, s[46:47]
	v_readlane_b32 s2, v138, 1
	s_add_u32 s46, s40, s2
	s_addc_u32 s47, s41, 0
	global_load_dwordx4 v[52:55], v157, s[46:47]
	v_readlane_b32 s2, v138, 2
	s_add_u32 s46, s40, s2
	s_addc_u32 s47, s41, 0
	global_load_dwordx4 v[56:59], v157, s[46:47]
	v_readlane_b32 s2, v138, 3
	s_add_u32 s46, s40, s2
	s_addc_u32 s47, s41, 0
	global_load_dwordx4 v[60:63], v157, s[46:47]
	v_readlane_b32 s2, v138, 4
	s_add_u32 s46, s40, s2
	s_addc_u32 s47, s41, 0
	global_load_dwordx4 v[64:67], v157, s[46:47]
	v_readlane_b32 s2, v138, 5
	s_add_u32 s46, s40, s2
	s_addc_u32 s47, s41, 0
	global_load_dwordx4 v[68:71], v157, s[46:47]
	v_readlane_b32 s2, v138, 6
	s_add_u32 s46, s40, s2
	s_addc_u32 s47, s41, 0
	global_load_dwordx4 v[72:75], v157, s[46:47]
	v_readlane_b32 s2, v138, 7
	s_add_u32 s46, s40, s2
	s_addc_u32 s47, s41, 0
	global_load_dwordx4 v[76:79], v157, s[46:47]
	v_readlane_b32 s2, v138, 8
	s_add_u32 s46, s40, s2
	s_addc_u32 s47, s41, 0
	global_load_dwordx4 v[80:83], v157, s[46:47]
	v_readlane_b32 s2, v138, 9
	s_add_u32 s46, s40, s2
	s_addc_u32 s47, s41, 0
	global_load_dwordx4 v[84:87], v157, s[46:47]
	v_readlane_b32 s2, v138, 10
	s_add_u32 s46, s40, s2
	s_addc_u32 s47, s41, 0
	global_load_dwordx4 v[88:91], v157, s[46:47]
	v_readlane_b32 s2, v138, 11
	s_add_u32 s46, s40, s2
	s_addc_u32 s47, s41, 0
	global_load_dwordx4 v[92:95], v157, s[46:47]
	v_readlane_b32 s2, v138, 12
	s_add_u32 s46, s40, s2
	s_addc_u32 s47, s41, 0
	global_load_dwordx4 v[96:99], v157, s[46:47]
	v_readlane_b32 s2, v138, 13
	s_add_u32 s46, s40, s2
	s_addc_u32 s47, s41, 0
	global_load_dwordx4 v[100:103], v157, s[46:47]
	v_readlane_b32 s2, v138, 14
	s_add_u32 s46, s40, s2
	s_addc_u32 s47, s41, 0
	global_load_dwordx4 v[104:107], v157, s[46:47]
	v_readlane_b32 s2, v138, 15
	s_add_u32 s46, s40, s2
	s_addc_u32 s47, s41, 0
	global_load_dwordx4 v[108:111], v157, s[46:47]
	ds_read_b32 v146, v154 offset:64
	ds_read_b32 v148, v155 offset:2368
	ds_read_b32 v149, v155 offset:4736
	ds_read_b32 v152, v156 offset:7104
	s_mov_b32 s96, 0
.Lgx_p1loop_8:
	s_waitcnt lgkmcnt(0)
	v_readfirstlane_b32 s29, v152
	ds_read_b32 v147, v154 offset:96
	ds_read_b32 v150, v155 offset:2400
	ds_read_b32 v151, v155 offset:4768
	ds_read_b32 v153, v156 offset:7108
	s_cmp_eq_u32 s29, 1
	s_cbranch_scc1 .Lgx_p1g1_11
	s_cmp_eq_u32 s29, 2
	s_cbranch_scc1 .Lgx_p1g2_12
	s_waitcnt vmcnt(15)
	v_cvt_pk_f32_fp8_e32 v[112:113], v48
	v_cvt_pk_f32_fp8_sdwa v[114:115], v48 src0_sel:WORD_1
	v_cvt_pk_f32_fp8_e32 v[116:117], v49
	v_cvt_pk_f32_fp8_sdwa v[118:119], v49 src0_sel:WORD_1
	v_cvt_pk_f32_fp8_e32 v[120:121], v50
	v_cvt_pk_f32_fp8_sdwa v[122:123], v50 src0_sel:WORD_1
	v_cvt_pk_f32_fp8_e32 v[124:125], v51
	v_cvt_pk_f32_fp8_sdwa v[126:127], v51 src0_sel:WORD_1
	v_readlane_b32 s2, v146, 0
	s_add_u32 s46, s40, s2
	s_addc_u32 s47, s41, 0
	global_load_dwordx4 v[48:51], v157, s[46:47]
	v_pk_mul_f32 v[138:139], v[112:113], v[0:1]
	v_pk_mul_f32 v[140:141], v[114:115], v[2:3]
	v_pk_fma_f32 v[138:139], v[116:117], v[4:5], v[138:139]
	v_pk_fma_f32 v[140:141], v[118:119], v[6:7], v[140:141]
	v_pk_fma_f32 v[138:139], v[120:121], v[8:9], v[138:139]
	v_pk_fma_f32 v[140:141], v[122:123], v[10:11], v[140:141]
	v_pk_fma_f32 v[138:139], v[124:125], v[12:13], v[138:139]
	v_pk_fma_f32 v[140:141], v[126:127], v[14:15], v[140:141]
	s_nop 0
	v_pk_add_f32 v[138:139], v[138:139], v[140:141]
	s_waitcnt vmcnt(15)
	v_add_f32_e32 v130, v138, v139
	v_cvt_pk_f32_fp8_e32 v[112:113], v52
	v_cvt_pk_f32_fp8_sdwa v[114:115], v52 src0_sel:WORD_1
	v_cvt_pk_f32_fp8_e32 v[116:117], v53
	v_cvt_pk_f32_fp8_sdwa v[118:119], v53 src0_sel:WORD_1
	v_cvt_pk_f32_fp8_e32 v[120:121], v54
	v_cvt_pk_f32_fp8_sdwa v[122:123], v54 src0_sel:WORD_1
	v_cvt_pk_f32_fp8_e32 v[124:125], v55
	v_cvt_pk_f32_fp8_sdwa v[126:127], v55 src0_sel:WORD_1
	v_readlane_b32 s2, v146, 1
	s_add_u32 s46, s40, s2
	s_addc_u32 s47, s41, 0
	global_load_dwordx4 v[52:55], v157, s[46:47]
	v_pk_mul_f32 v[138:139], v[112:113], v[0:1]
	v_pk_mul_f32 v[140:141], v[114:115], v[2:3]
	v_pk_fma_f32 v[138:139], v[116:117], v[4:5], v[138:139]
	v_pk_fma_f32 v[140:141], v[118:119], v[6:7], v[140:141]
	v_pk_fma_f32 v[138:139], v[120:121], v[8:9], v[138:139]
	v_pk_fma_f32 v[140:141], v[122:123], v[10:11], v[140:141]
	v_pk_fma_f32 v[138:139], v[124:125], v[12:13], v[138:139]
	v_pk_fma_f32 v[140:141], v[126:127], v[14:15], v[140:141]
	s_nop 0
	v_pk_add_f32 v[138:139], v[138:139], v[140:141]
	s_waitcnt vmcnt(15)
	v_add_f32_e32 v131, v138, v139
	v_cvt_pk_f32_fp8_e32 v[112:113], v56
	v_cvt_pk_f32_fp8_sdwa v[114:115], v56 src0_sel:WORD_1
	v_cvt_pk_f32_fp8_e32 v[116:117], v57
	v_cvt_pk_f32_fp8_sdwa v[118:119], v57 src0_sel:WORD_1
	v_cvt_pk_f32_fp8_e32 v[120:121], v58
	v_cvt_pk_f32_fp8_sdwa v[122:123], v58 src0_sel:WORD_1
	v_cvt_pk_f32_fp8_e32 v[124:125], v59
	v_cvt_pk_f32_fp8_sdwa v[126:127], v59 src0_sel:WORD_1
	v_readlane_b32 s2, v146, 2
	s_add_u32 s46, s40, s2
	s_addc_u32 s47, s41, 0
	global_load_dwordx4 v[56:59], v157, s[46:47]
	v_pk_mul_f32 v[138:139], v[112:113], v[0:1]
	v_pk_mul_f32 v[140:141], v[114:115], v[2:3]
	v_pk_fma_f32 v[138:139], v[116:117], v[4:5], v[138:139]
	v_pk_fma_f32 v[140:141], v[118:119], v[6:7], v[140:141]
	v_pk_fma_f32 v[138:139], v[120:121], v[8:9], v[138:139]
	v_pk_fma_f32 v[140:141], v[122:123], v[10:11], v[140:141]
	v_pk_fma_f32 v[138:139], v[124:125], v[12:13], v[138:139]
	v_pk_fma_f32 v[140:141], v[126:127], v[14:15], v[140:141]
	s_nop 0
	v_pk_add_f32 v[138:139], v[138:139], v[140:141]
	s_waitcnt vmcnt(15)
	v_add_f32_e32 v132, v138, v139
	v_cvt_pk_f32_fp8_e32 v[112:113], v60
	v_cvt_pk_f32_fp8_sdwa v[114:115], v60 src0_sel:WORD_1
	v_cvt_pk_f32_fp8_e32 v[116:117], v61
	v_cvt_pk_f32_fp8_sdwa v[118:119], v61 src0_sel:WORD_1
	v_cvt_pk_f32_fp8_e32 v[120:121], v62
	v_cvt_pk_f32_fp8_sdwa v[122:123], v62 src0_sel:WORD_1
	v_cvt_pk_f32_fp8_e32 v[124:125], v63
	v_cvt_pk_f32_fp8_sdwa v[126:127], v63 src0_sel:WORD_1
	v_readlane_b32 s2, v146, 3
	s_add_u32 s46, s40, s2
	s_addc_u32 s47, s41, 0
	global_load_dwordx4 v[60:63], v157, s[46:47]
	v_pk_mul_f32 v[138:139], v[112:113], v[0:1]
	v_pk_mul_f32 v[140:141], v[114:115], v[2:3]
	v_pk_fma_f32 v[138:139], v[116:117], v[4:5], v[138:139]
	v_pk_fma_f32 v[140:141], v[118:119], v[6:7], v[140:141]
	v_pk_fma_f32 v[138:139], v[120:121], v[8:9], v[138:139]
	v_pk_fma_f32 v[140:141], v[122:123], v[10:11], v[140:141]
	v_pk_fma_f32 v[138:139], v[124:125], v[12:13], v[138:139]
	v_pk_fma_f32 v[140:141], v[126:127], v[14:15], v[140:141]
	s_nop 0
	v_pk_add_f32 v[138:139], v[138:139], v[140:141]
	s_waitcnt vmcnt(15)
	v_add_f32_e32 v133, v138, v139
	v_cvt_pk_f32_fp8_e32 v[112:113], v64
	v_cvt_pk_f32_fp8_sdwa v[114:115], v64 src0_sel:WORD_1
	v_cvt_pk_f32_fp8_e32 v[116:117], v65
	v_cvt_pk_f32_fp8_sdwa v[118:119], v65 src0_sel:WORD_1
	v_cvt_pk_f32_fp8_e32 v[120:121], v66
	v_cvt_pk_f32_fp8_sdwa v[122:123], v66 src0_sel:WORD_1
	v_cvt_pk_f32_fp8_e32 v[124:125], v67
	v_cvt_pk_f32_fp8_sdwa v[126:127], v67 src0_sel:WORD_1
	v_readlane_b32 s2, v146, 4
	s_add_u32 s46, s40, s2
	s_addc_u32 s47, s41, 0
	global_load_dwordx4 v[64:67], v157, s[46:47]
	v_pk_mul_f32 v[138:139], v[112:113], v[0:1]
	v_pk_mul_f32 v[140:141], v[114:115], v[2:3]
	v_pk_fma_f32 v[138:139], v[116:117], v[4:5], v[138:139]
	v_pk_fma_f32 v[140:141], v[118:119], v[6:7], v[140:141]
	v_pk_fma_f32 v[138:139], v[120:121], v[8:9], v[138:139]
	v_pk_fma_f32 v[140:141], v[122:123], v[10:11], v[140:141]
	v_pk_fma_f32 v[138:139], v[124:125], v[12:13], v[138:139]
	v_pk_fma_f32 v[140:141], v[126:127], v[14:15], v[140:141]
	s_nop 0
	v_pk_add_f32 v[138:139], v[138:139], v[140:141]
	s_waitcnt vmcnt(15)
	v_add_f32_e32 v134, v138, v139
	v_cvt_pk_f32_fp8_e32 v[112:113], v68
	v_cvt_pk_f32_fp8_sdwa v[114:115], v68 src0_sel:WORD_1
	v_cvt_pk_f32_fp8_e32 v[116:117], v69
	v_cvt_pk_f32_fp8_sdwa v[118:119], v69 src0_sel:WORD_1
	v_cvt_pk_f32_fp8_e32 v[120:121], v70
	v_cvt_pk_f32_fp8_sdwa v[122:123], v70 src0_sel:WORD_1
	v_cvt_pk_f32_fp8_e32 v[124:125], v71
	v_cvt_pk_f32_fp8_sdwa v[126:127], v71 src0_sel:WORD_1
	v_readlane_b32 s2, v146, 5
	s_add_u32 s46, s40, s2
	s_addc_u32 s47, s41, 0
	global_load_dwordx4 v[68:71], v157, s[46:47]
	v_pk_mul_f32 v[138:139], v[112:113], v[0:1]
	v_pk_mul_f32 v[140:141], v[114:115], v[2:3]
	v_pk_fma_f32 v[138:139], v[116:117], v[4:5], v[138:139]
	v_pk_fma_f32 v[140:141], v[118:119], v[6:7], v[140:141]
	v_pk_fma_f32 v[138:139], v[120:121], v[8:9], v[138:139]
	v_pk_fma_f32 v[140:141], v[122:123], v[10:11], v[140:141]
	v_pk_fma_f32 v[138:139], v[124:125], v[12:13], v[138:139]
	v_pk_fma_f32 v[140:141], v[126:127], v[14:15], v[140:141]
	s_nop 0
	v_pk_add_f32 v[138:139], v[138:139], v[140:141]
	s_waitcnt vmcnt(15)
	v_add_f32_e32 v135, v138, v139
	v_cvt_pk_f32_fp8_e32 v[112:113], v72
	v_cvt_pk_f32_fp8_sdwa v[114:115], v72 src0_sel:WORD_1
	v_cvt_pk_f32_fp8_e32 v[116:117], v73
	v_cvt_pk_f32_fp8_sdwa v[118:119], v73 src0_sel:WORD_1
	v_cvt_pk_f32_fp8_e32 v[120:121], v74
	v_cvt_pk_f32_fp8_sdwa v[122:123], v74 src0_sel:WORD_1
	v_cvt_pk_f32_fp8_e32 v[124:125], v75
	v_cvt_pk_f32_fp8_sdwa v[126:127], v75 src0_sel:WORD_1
	v_readlane_b32 s2, v146, 6
	s_add_u32 s46, s40, s2
	s_addc_u32 s47, s41, 0
	global_load_dwordx4 v[72:75], v157, s[46:47]
	v_pk_mul_f32 v[138:139], v[112:113], v[0:1]
	v_pk_mul_f32 v[140:141], v[114:115], v[2:3]
	v_pk_fma_f32 v[138:139], v[116:117], v[4:5], v[138:139]
	v_pk_fma_f32 v[140:141], v[118:119], v[6:7], v[140:141]
	v_pk_fma_f32 v[138:139], v[120:121], v[8:9], v[138:139]
	v_pk_fma_f32 v[140:141], v[122:123], v[10:11], v[140:141]
	v_pk_fma_f32 v[138:139], v[124:125], v[12:13], v[138:139]
	v_pk_fma_f32 v[140:141], v[126:127], v[14:15], v[140:141]
	s_nop 0
	v_pk_add_f32 v[138:139], v[138:139], v[140:141]
	s_waitcnt vmcnt(15)
	v_add_f32_e32 v136, v138, v139
	v_cvt_pk_f32_fp8_e32 v[112:113], v76
	v_cvt_pk_f32_fp8_sdwa v[114:115], v76 src0_sel:WORD_1
	v_cvt_pk_f32_fp8_e32 v[116:117], v77
	v_cvt_pk_f32_fp8_sdwa v[118:119], v77 src0_sel:WORD_1
	v_cvt_pk_f32_fp8_e32 v[120:121], v78
	v_cvt_pk_f32_fp8_sdwa v[122:123], v78 src0_sel:WORD_1
	v_cvt_pk_f32_fp8_e32 v[124:125], v79
	v_cvt_pk_f32_fp8_sdwa v[126:127], v79 src0_sel:WORD_1
	v_readlane_b32 s2, v146, 7
	s_add_u32 s46, s40, s2
	s_addc_u32 s47, s41, 0
	global_load_dwordx4 v[76:79], v157, s[46:47]
	v_pk_mul_f32 v[138:139], v[112:113], v[0:1]
	v_pk_mul_f32 v[140:141], v[114:115], v[2:3]
	v_pk_fma_f32 v[138:139], v[116:117], v[4:5], v[138:139]
	v_pk_fma_f32 v[140:141], v[118:119], v[6:7], v[140:141]
	v_pk_fma_f32 v[138:139], v[120:121], v[8:9], v[138:139]
	v_pk_fma_f32 v[140:141], v[122:123], v[10:11], v[140:141]
	v_pk_fma_f32 v[138:139], v[124:125], v[12:13], v[138:139]
	v_pk_fma_f32 v[140:141], v[126:127], v[14:15], v[140:141]
	s_nop 0
	v_pk_add_f32 v[138:139], v[138:139], v[140:141]
	s_nop 0
	v_add_f32_e32 v137, v138, v139
	s_branch .Lgx_p1end_9
.Lgx_p1g1_11:
	s_waitcnt vmcnt(15)
	v_cvt_pk_f32_fp8_e32 v[112:113], v48
	v_cvt_pk_f32_fp8_sdwa v[114:115], v48 src0_sel:WORD_1
	v_cvt_pk_f32_fp8_e32 v[116:117], v49
	v_cvt_pk_f32_fp8_sdwa v[118:119], v49 src0_sel:WORD_1
	v_cvt_pk_f32_fp8_e32 v[120:121], v50
	v_cvt_pk_f32_fp8_sdwa v[122:123], v50 src0_sel:WORD_1
	v_cvt_pk_f32_fp8_e32 v[124:125], v51
	v_cvt_pk_f32_fp8_sdwa v[126:127], v51 src0_sel:WORD_1
	v_readlane_b32 s2, v146, 0
	s_add_u32 s46, s40, s2
	s_addc_u32 s47, s41, 0
	global_load_dwordx4 v[48:51], v157, s[46:47]
	v_pk_mul_f32 v[138:139], v[112:113], v[16:17]
	v_pk_mul_f32 v[140:141], v[114:115], v[18:19]
	v_pk_fma_f32 v[138:139], v[116:117], v[20:21], v[138:139]
	v_pk_fma_f32 v[140:141], v[118:119], v[22:23], v[140:141]
	v_pk_fma_f32 v[138:139], v[120:121], v[24:25], v[138:139]
	v_pk_fma_f32 v[140:141], v[122:123], v[26:27], v[140:141]
	v_pk_fma_f32 v[138:139], v[124:125], v[28:29], v[138:139]
	v_pk_fma_f32 v[140:141], v[126:127], v[30:31], v[140:141]
	s_nop 0
	v_pk_add_f32 v[138:139], v[138:139], v[140:141]
	s_waitcnt vmcnt(15)
	v_add_f32_e32 v130, v138, v139
	v_cvt_pk_f32_fp8_e32 v[112:113], v52
	v_cvt_pk_f32_fp8_sdwa v[114:115], v52 src0_sel:WORD_1
	v_cvt_pk_f32_fp8_e32 v[116:117], v53
	v_cvt_pk_f32_fp8_sdwa v[118:119], v53 src0_sel:WORD_1
	v_cvt_pk_f32_fp8_e32 v[120:121], v54
	v_cvt_pk_f32_fp8_sdwa v[122:123], v54 src0_sel:WORD_1
	v_cvt_pk_f32_fp8_e32 v[124:125], v55
	v_cvt_pk_f32_fp8_sdwa v[126:127], v55 src0_sel:WORD_1
	v_readlane_b32 s2, v146, 1
	s_add_u32 s46, s40, s2
	s_addc_u32 s47, s41, 0
	global_load_dwordx4 v[52:55], v157, s[46:47]
	v_pk_mul_f32 v[138:139], v[112:113], v[16:17]
	v_pk_mul_f32 v[140:141], v[114:115], v[18:19]
	v_pk_fma_f32 v[138:139], v[116:117], v[20:21], v[138:139]
	v_pk_fma_f32 v[140:141], v[118:119], v[22:23], v[140:141]
	v_pk_fma_f32 v[138:139], v[120:121], v[24:25], v[138:139]
	v_pk_fma_f32 v[140:141], v[122:123], v[26:27], v[140:141]
	v_pk_fma_f32 v[138:139], v[124:125], v[28:29], v[138:139]
	v_pk_fma_f32 v[140:141], v[126:127], v[30:31], v[140:141]
	s_nop 0
	v_pk_add_f32 v[138:139], v[138:139], v[140:141]
	s_waitcnt vmcnt(15)
	v_add_f32_e32 v131, v138, v139
	v_cvt_pk_f32_fp8_e32 v[112:113], v56
	v_cvt_pk_f32_fp8_sdwa v[114:115], v56 src0_sel:WORD_1
	v_cvt_pk_f32_fp8_e32 v[116:117], v57
	v_cvt_pk_f32_fp8_sdwa v[118:119], v57 src0_sel:WORD_1
	v_cvt_pk_f32_fp8_e32 v[120:121], v58
	v_cvt_pk_f32_fp8_sdwa v[122:123], v58 src0_sel:WORD_1
	v_cvt_pk_f32_fp8_e32 v[124:125], v59
	v_cvt_pk_f32_fp8_sdwa v[126:127], v59 src0_sel:WORD_1
	v_readlane_b32 s2, v146, 2
	s_add_u32 s46, s40, s2
	s_addc_u32 s47, s41, 0
	global_load_dwordx4 v[56:59], v157, s[46:47]
	v_pk_mul_f32 v[138:139], v[112:113], v[16:17]
	v_pk_mul_f32 v[140:141], v[114:115], v[18:19]
	v_pk_fma_f32 v[138:139], v[116:117], v[20:21], v[138:139]
	v_pk_fma_f32 v[140:141], v[118:119], v[22:23], v[140:141]
	v_pk_fma_f32 v[138:139], v[120:121], v[24:25], v[138:139]
	v_pk_fma_f32 v[140:141], v[122:123], v[26:27], v[140:141]
	v_pk_fma_f32 v[138:139], v[124:125], v[28:29], v[138:139]
	v_pk_fma_f32 v[140:141], v[126:127], v[30:31], v[140:141]
	s_nop 0
	v_pk_add_f32 v[138:139], v[138:139], v[140:141]
	s_waitcnt vmcnt(15)
	v_add_f32_e32 v132, v138, v139
	v_cvt_pk_f32_fp8_e32 v[112:113], v60
	v_cvt_pk_f32_fp8_sdwa v[114:115], v60 src0_sel:WORD_1
	v_cvt_pk_f32_fp8_e32 v[116:117], v61
	v_cvt_pk_f32_fp8_sdwa v[118:119], v61 src0_sel:WORD_1
	v_cvt_pk_f32_fp8_e32 v[120:121], v62
	v_cvt_pk_f32_fp8_sdwa v[122:123], v62 src0_sel:WORD_1
	v_cvt_pk_f32_fp8_e32 v[124:125], v63
	v_cvt_pk_f32_fp8_sdwa v[126:127], v63 src0_sel:WORD_1
	v_readlane_b32 s2, v146, 3
	s_add_u32 s46, s40, s2
	s_addc_u32 s47, s41, 0
	global_load_dwordx4 v[60:63], v157, s[46:47]
	v_pk_mul_f32 v[138:139], v[112:113], v[16:17]
	v_pk_mul_f32 v[140:141], v[114:115], v[18:19]
	v_pk_fma_f32 v[138:139], v[116:117], v[20:21], v[138:139]
	v_pk_fma_f32 v[140:141], v[118:119], v[22:23], v[140:141]
	v_pk_fma_f32 v[138:139], v[120:121], v[24:25], v[138:139]
	v_pk_fma_f32 v[140:141], v[122:123], v[26:27], v[140:141]
	v_pk_fma_f32 v[138:139], v[124:125], v[28:29], v[138:139]
	v_pk_fma_f32 v[140:141], v[126:127], v[30:31], v[140:141]
	s_nop 0
	v_pk_add_f32 v[138:139], v[138:139], v[140:141]
	s_waitcnt vmcnt(15)
	v_add_f32_e32 v133, v138, v139
	v_cvt_pk_f32_fp8_e32 v[112:113], v64
	v_cvt_pk_f32_fp8_sdwa v[114:115], v64 src0_sel:WORD_1
	v_cvt_pk_f32_fp8_e32 v[116:117], v65
	v_cvt_pk_f32_fp8_sdwa v[118:119], v65 src0_sel:WORD_1
	v_cvt_pk_f32_fp8_e32 v[120:121], v66
	v_cvt_pk_f32_fp8_sdwa v[122:123], v66 src0_sel:WORD_1
	v_cvt_pk_f32_fp8_e32 v[124:125], v67
	v_cvt_pk_f32_fp8_sdwa v[126:127], v67 src0_sel:WORD_1
	v_readlane_b32 s2, v146, 4
	s_add_u32 s46, s40, s2
	s_addc_u32 s47, s41, 0
	global_load_dwordx4 v[64:67], v157, s[46:47]
	v_pk_mul_f32 v[138:139], v[112:113], v[16:17]
	v_pk_mul_f32 v[140:141], v[114:115], v[18:19]
	v_pk_fma_f32 v[138:139], v[116:117], v[20:21], v[138:139]
	v_pk_fma_f32 v[140:141], v[118:119], v[22:23], v[140:141]
	v_pk_fma_f32 v[138:139], v[120:121], v[24:25], v[138:139]
	v_pk_fma_f32 v[140:141], v[122:123], v[26:27], v[140:141]
	v_pk_fma_f32 v[138:139], v[124:125], v[28:29], v[138:139]
	v_pk_fma_f32 v[140:141], v[126:127], v[30:31], v[140:141]
	s_nop 0
	v_pk_add_f32 v[138:139], v[138:139], v[140:141]
	s_waitcnt vmcnt(15)
	v_add_f32_e32 v134, v138, v139
	v_cvt_pk_f32_fp8_e32 v[112:113], v68
	v_cvt_pk_f32_fp8_sdwa v[114:115], v68 src0_sel:WORD_1
	v_cvt_pk_f32_fp8_e32 v[116:117], v69
	v_cvt_pk_f32_fp8_sdwa v[118:119], v69 src0_sel:WORD_1
	v_cvt_pk_f32_fp8_e32 v[120:121], v70
	v_cvt_pk_f32_fp8_sdwa v[122:123], v70 src0_sel:WORD_1
	v_cvt_pk_f32_fp8_e32 v[124:125], v71
	v_cvt_pk_f32_fp8_sdwa v[126:127], v71 src0_sel:WORD_1
	v_readlane_b32 s2, v146, 5
	s_add_u32 s46, s40, s2
	s_addc_u32 s47, s41, 0
	global_load_dwordx4 v[68:71], v157, s[46:47]
	v_pk_mul_f32 v[138:139], v[112:113], v[16:17]
	v_pk_mul_f32 v[140:141], v[114:115], v[18:19]
	v_pk_fma_f32 v[138:139], v[116:117], v[20:21], v[138:139]
	v_pk_fma_f32 v[140:141], v[118:119], v[22:23], v[140:141]
	v_pk_fma_f32 v[138:139], v[120:121], v[24:25], v[138:139]
	v_pk_fma_f32 v[140:141], v[122:123], v[26:27], v[140:141]
	v_pk_fma_f32 v[138:139], v[124:125], v[28:29], v[138:139]
	v_pk_fma_f32 v[140:141], v[126:127], v[30:31], v[140:141]
	s_nop 0
	v_pk_add_f32 v[138:139], v[138:139], v[140:141]
	s_waitcnt vmcnt(15)
	v_add_f32_e32 v135, v138, v139
	v_cvt_pk_f32_fp8_e32 v[112:113], v72
	v_cvt_pk_f32_fp8_sdwa v[114:115], v72 src0_sel:WORD_1
	v_cvt_pk_f32_fp8_e32 v[116:117], v73
	v_cvt_pk_f32_fp8_sdwa v[118:119], v73 src0_sel:WORD_1
	v_cvt_pk_f32_fp8_e32 v[120:121], v74
	v_cvt_pk_f32_fp8_sdwa v[122:123], v74 src0_sel:WORD_1
	v_cvt_pk_f32_fp8_e32 v[124:125], v75
	v_cvt_pk_f32_fp8_sdwa v[126:127], v75 src0_sel:WORD_1
	v_readlane_b32 s2, v146, 6
	s_add_u32 s46, s40, s2
	s_addc_u32 s47, s41, 0
	global_load_dwordx4 v[72:75], v157, s[46:47]
	v_pk_mul_f32 v[138:139], v[112:113], v[16:17]
	v_pk_mul_f32 v[140:141], v[114:115], v[18:19]
	v_pk_fma_f32 v[138:139], v[116:117], v[20:21], v[138:139]
	v_pk_fma_f32 v[140:141], v[118:119], v[22:23], v[140:141]
	v_pk_fma_f32 v[138:139], v[120:121], v[24:25], v[138:139]
	v_pk_fma_f32 v[140:141], v[122:123], v[26:27], v[140:141]
	v_pk_fma_f32 v[138:139], v[124:125], v[28:29], v[138:139]
	v_pk_fma_f32 v[140:141], v[126:127], v[30:31], v[140:141]
	s_nop 0
	v_pk_add_f32 v[138:139], v[138:139], v[140:141]
	s_waitcnt vmcnt(15)
	v_add_f32_e32 v136, v138, v139
	v_cvt_pk_f32_fp8_e32 v[112:113], v76
	v_cvt_pk_f32_fp8_sdwa v[114:115], v76 src0_sel:WORD_1
	v_cvt_pk_f32_fp8_e32 v[116:117], v77
	v_cvt_pk_f32_fp8_sdwa v[118:119], v77 src0_sel:WORD_1
	v_cvt_pk_f32_fp8_e32 v[120:121], v78
	v_cvt_pk_f32_fp8_sdwa v[122:123], v78 src0_sel:WORD_1
	v_cvt_pk_f32_fp8_e32 v[124:125], v79
	v_cvt_pk_f32_fp8_sdwa v[126:127], v79 src0_sel:WORD_1
	v_readlane_b32 s2, v146, 7
	s_add_u32 s46, s40, s2
	s_addc_u32 s47, s41, 0
	global_load_dwordx4 v[76:79], v157, s[46:47]
	v_pk_mul_f32 v[138:139], v[112:113], v[16:17]
	v_pk_mul_f32 v[140:141], v[114:115], v[18:19]
	v_pk_fma_f32 v[138:139], v[116:117], v[20:21], v[138:139]
	v_pk_fma_f32 v[140:141], v[118:119], v[22:23], v[140:141]
	v_pk_fma_f32 v[138:139], v[120:121], v[24:25], v[138:139]
	v_pk_fma_f32 v[140:141], v[122:123], v[26:27], v[140:141]
	v_pk_fma_f32 v[138:139], v[124:125], v[28:29], v[138:139]
	v_pk_fma_f32 v[140:141], v[126:127], v[30:31], v[140:141]
	s_nop 0
	v_pk_add_f32 v[138:139], v[138:139], v[140:141]
	s_nop 0
	v_add_f32_e32 v137, v138, v139
	s_branch .Lgx_p1end_9
.Lgx_p1g2_12:
	s_waitcnt vmcnt(15)
	v_cvt_pk_f32_fp8_e32 v[112:113], v48
	v_cvt_pk_f32_fp8_sdwa v[114:115], v48 src0_sel:WORD_1
	v_cvt_pk_f32_fp8_e32 v[116:117], v49
	v_cvt_pk_f32_fp8_sdwa v[118:119], v49 src0_sel:WORD_1
	v_cvt_pk_f32_fp8_e32 v[120:121], v50
	v_cvt_pk_f32_fp8_sdwa v[122:123], v50 src0_sel:WORD_1
	v_cvt_pk_f32_fp8_e32 v[124:125], v51
	v_cvt_pk_f32_fp8_sdwa v[126:127], v51 src0_sel:WORD_1
	v_readlane_b32 s2, v146, 0
	s_add_u32 s46, s40, s2
	s_addc_u32 s47, s41, 0
	global_load_dwordx4 v[48:51], v157, s[46:47]
	v_pk_mul_f32 v[138:139], v[112:113], v[32:33]
	v_pk_mul_f32 v[140:141], v[114:115], v[34:35]
	v_pk_fma_f32 v[138:139], v[116:117], v[36:37], v[138:139]
	v_pk_fma_f32 v[140:141], v[118:119], v[38:39], v[140:141]
	v_pk_fma_f32 v[138:139], v[120:121], v[40:41], v[138:139]
	v_pk_fma_f32 v[140:141], v[122:123], v[42:43], v[140:141]
	v_pk_fma_f32 v[138:139], v[124:125], v[44:45], v[138:139]
	v_pk_fma_f32 v[140:141], v[126:127], v[46:47], v[140:141]
	s_nop 0
	v_pk_add_f32 v[138:139], v[138:139], v[140:141]
	s_waitcnt vmcnt(15)
	v_add_f32_e32 v130, v138, v139
	v_cvt_pk_f32_fp8_e32 v[112:113], v52
	v_cvt_pk_f32_fp8_sdwa v[114:115], v52 src0_sel:WORD_1
	v_cvt_pk_f32_fp8_e32 v[116:117], v53
	v_cvt_pk_f32_fp8_sdwa v[118:119], v53 src0_sel:WORD_1
	v_cvt_pk_f32_fp8_e32 v[120:121], v54
	v_cvt_pk_f32_fp8_sdwa v[122:123], v54 src0_sel:WORD_1
	v_cvt_pk_f32_fp8_e32 v[124:125], v55
	v_cvt_pk_f32_fp8_sdwa v[126:127], v55 src0_sel:WORD_1
	v_readlane_b32 s2, v146, 1
	s_add_u32 s46, s40, s2
	s_addc_u32 s47, s41, 0
	global_load_dwordx4 v[52:55], v157, s[46:47]
	v_pk_mul_f32 v[138:139], v[112:113], v[32:33]
	v_pk_mul_f32 v[140:141], v[114:115], v[34:35]
	v_pk_fma_f32 v[138:139], v[116:117], v[36:37], v[138:139]
	v_pk_fma_f32 v[140:141], v[118:119], v[38:39], v[140:141]
	v_pk_fma_f32 v[138:139], v[120:121], v[40:41], v[138:139]
	v_pk_fma_f32 v[140:141], v[122:123], v[42:43], v[140:141]
	v_pk_fma_f32 v[138:139], v[124:125], v[44:45], v[138:139]
	v_pk_fma_f32 v[140:141], v[126:127], v[46:47], v[140:141]
	s_nop 0
	v_pk_add_f32 v[138:139], v[138:139], v[140:141]
	s_waitcnt vmcnt(15)
	v_add_f32_e32 v131, v138, v139
	v_cvt_pk_f32_fp8_e32 v[112:113], v56
	v_cvt_pk_f32_fp8_sdwa v[114:115], v56 src0_sel:WORD_1
	v_cvt_pk_f32_fp8_e32 v[116:117], v57
	v_cvt_pk_f32_fp8_sdwa v[118:119], v57 src0_sel:WORD_1
	v_cvt_pk_f32_fp8_e32 v[120:121], v58
	v_cvt_pk_f32_fp8_sdwa v[122:123], v58 src0_sel:WORD_1
	v_cvt_pk_f32_fp8_e32 v[124:125], v59
	v_cvt_pk_f32_fp8_sdwa v[126:127], v59 src0_sel:WORD_1
	v_readlane_b32 s2, v146, 2
	s_add_u32 s46, s40, s2
	s_addc_u32 s47, s41, 0
	global_load_dwordx4 v[56:59], v157, s[46:47]
	v_pk_mul_f32 v[138:139], v[112:113], v[32:33]
	v_pk_mul_f32 v[140:141], v[114:115], v[34:35]
	v_pk_fma_f32 v[138:139], v[116:117], v[36:37], v[138:139]
	v_pk_fma_f32 v[140:141], v[118:119], v[38:39], v[140:141]
	v_pk_fma_f32 v[138:139], v[120:121], v[40:41], v[138:139]
	v_pk_fma_f32 v[140:141], v[122:123], v[42:43], v[140:141]
	v_pk_fma_f32 v[138:139], v[124:125], v[44:45], v[138:139]
	v_pk_fma_f32 v[140:141], v[126:127], v[46:47], v[140:141]
	s_nop 0
	v_pk_add_f32 v[138:139], v[138:139], v[140:141]
	s_waitcnt vmcnt(15)
	v_add_f32_e32 v132, v138, v139
	v_cvt_pk_f32_fp8_e32 v[112:113], v60
	v_cvt_pk_f32_fp8_sdwa v[114:115], v60 src0_sel:WORD_1
	v_cvt_pk_f32_fp8_e32 v[116:117], v61
	v_cvt_pk_f32_fp8_sdwa v[118:119], v61 src0_sel:WORD_1
	v_cvt_pk_f32_fp8_e32 v[120:121], v62
	v_cvt_pk_f32_fp8_sdwa v[122:123], v62 src0_sel:WORD_1
	v_cvt_pk_f32_fp8_e32 v[124:125], v63
	v_cvt_pk_f32_fp8_sdwa v[126:127], v63 src0_sel:WORD_1
	v_readlane_b32 s2, v146, 3
	s_add_u32 s46, s40, s2
	s_addc_u32 s47, s41, 0
	global_load_dwordx4 v[60:63], v157, s[46:47]
	v_pk_mul_f32 v[138:139], v[112:113], v[32:33]
	v_pk_mul_f32 v[140:141], v[114:115], v[34:35]
	v_pk_fma_f32 v[138:139], v[116:117], v[36:37], v[138:139]
	v_pk_fma_f32 v[140:141], v[118:119], v[38:39], v[140:141]
	v_pk_fma_f32 v[138:139], v[120:121], v[40:41], v[138:139]
	v_pk_fma_f32 v[140:141], v[122:123], v[42:43], v[140:141]
	v_pk_fma_f32 v[138:139], v[124:125], v[44:45], v[138:139]
	v_pk_fma_f32 v[140:141], v[126:127], v[46:47], v[140:141]
	s_nop 0
	v_pk_add_f32 v[138:139], v[138:139], v[140:141]
	s_waitcnt vmcnt(15)
	v_add_f32_e32 v133, v138, v139
	v_cvt_pk_f32_fp8_e32 v[112:113], v64
	v_cvt_pk_f32_fp8_sdwa v[114:115], v64 src0_sel:WORD_1
	v_cvt_pk_f32_fp8_e32 v[116:117], v65
	v_cvt_pk_f32_fp8_sdwa v[118:119], v65 src0_sel:WORD_1
	v_cvt_pk_f32_fp8_e32 v[120:121], v66
	v_cvt_pk_f32_fp8_sdwa v[122:123], v66 src0_sel:WORD_1
	v_cvt_pk_f32_fp8_e32 v[124:125], v67
	v_cvt_pk_f32_fp8_sdwa v[126:127], v67 src0_sel:WORD_1
	v_readlane_b32 s2, v146, 4
	s_add_u32 s46, s40, s2
	s_addc_u32 s47, s41, 0
	global_load_dwordx4 v[64:67], v157, s[46:47]
	v_pk_mul_f32 v[138:139], v[112:113], v[32:33]
	v_pk_mul_f32 v[140:141], v[114:115], v[34:35]
	v_pk_fma_f32 v[138:139], v[116:117], v[36:37], v[138:139]
	v_pk_fma_f32 v[140:141], v[118:119], v[38:39], v[140:141]
	v_pk_fma_f32 v[138:139], v[120:121], v[40:41], v[138:139]
	v_pk_fma_f32 v[140:141], v[122:123], v[42:43], v[140:141]
	v_pk_fma_f32 v[138:139], v[124:125], v[44:45], v[138:139]
	v_pk_fma_f32 v[140:141], v[126:127], v[46:47], v[140:141]
	s_nop 0
	v_pk_add_f32 v[138:139], v[138:139], v[140:141]
	s_waitcnt vmcnt(15)
	v_add_f32_e32 v134, v138, v139
	v_cvt_pk_f32_fp8_e32 v[112:113], v68
	v_cvt_pk_f32_fp8_sdwa v[114:115], v68 src0_sel:WORD_1
	v_cvt_pk_f32_fp8_e32 v[116:117], v69
	v_cvt_pk_f32_fp8_sdwa v[118:119], v69 src0_sel:WORD_1
	v_cvt_pk_f32_fp8_e32 v[120:121], v70
	v_cvt_pk_f32_fp8_sdwa v[122:123], v70 src0_sel:WORD_1
	v_cvt_pk_f32_fp8_e32 v[124:125], v71
	v_cvt_pk_f32_fp8_sdwa v[126:127], v71 src0_sel:WORD_1
	v_readlane_b32 s2, v146, 5
	s_add_u32 s46, s40, s2
	s_addc_u32 s47, s41, 0
	global_load_dwordx4 v[68:71], v157, s[46:47]
	v_pk_mul_f32 v[138:139], v[112:113], v[32:33]
	v_pk_mul_f32 v[140:141], v[114:115], v[34:35]
	v_pk_fma_f32 v[138:139], v[116:117], v[36:37], v[138:139]
	v_pk_fma_f32 v[140:141], v[118:119], v[38:39], v[140:141]
	v_pk_fma_f32 v[138:139], v[120:121], v[40:41], v[138:139]
	v_pk_fma_f32 v[140:141], v[122:123], v[42:43], v[140:141]
	v_pk_fma_f32 v[138:139], v[124:125], v[44:45], v[138:139]
	v_pk_fma_f32 v[140:141], v[126:127], v[46:47], v[140:141]
	s_nop 0
	v_pk_add_f32 v[138:139], v[138:139], v[140:141]
	s_waitcnt vmcnt(15)
	v_add_f32_e32 v135, v138, v139
	v_cvt_pk_f32_fp8_e32 v[112:113], v72
	v_cvt_pk_f32_fp8_sdwa v[114:115], v72 src0_sel:WORD_1
	v_cvt_pk_f32_fp8_e32 v[116:117], v73
	v_cvt_pk_f32_fp8_sdwa v[118:119], v73 src0_sel:WORD_1
	v_cvt_pk_f32_fp8_e32 v[120:121], v74
	v_cvt_pk_f32_fp8_sdwa v[122:123], v74 src0_sel:WORD_1
	v_cvt_pk_f32_fp8_e32 v[124:125], v75
	v_cvt_pk_f32_fp8_sdwa v[126:127], v75 src0_sel:WORD_1
	v_readlane_b32 s2, v146, 6
	s_add_u32 s46, s40, s2
	s_addc_u32 s47, s41, 0
	global_load_dwordx4 v[72:75], v157, s[46:47]
	v_pk_mul_f32 v[138:139], v[112:113], v[32:33]
	v_pk_mul_f32 v[140:141], v[114:115], v[34:35]
	v_pk_fma_f32 v[138:139], v[116:117], v[36:37], v[138:139]
	v_pk_fma_f32 v[140:141], v[118:119], v[38:39], v[140:141]
	v_pk_fma_f32 v[138:139], v[120:121], v[40:41], v[138:139]
	v_pk_fma_f32 v[140:141], v[122:123], v[42:43], v[140:141]
	v_pk_fma_f32 v[138:139], v[124:125], v[44:45], v[138:139]
	v_pk_fma_f32 v[140:141], v[126:127], v[46:47], v[140:141]
	s_nop 0
	v_pk_add_f32 v[138:139], v[138:139], v[140:141]
	s_waitcnt vmcnt(15)
	v_add_f32_e32 v136, v138, v139
	v_cvt_pk_f32_fp8_e32 v[112:113], v76
	v_cvt_pk_f32_fp8_sdwa v[114:115], v76 src0_sel:WORD_1
	v_cvt_pk_f32_fp8_e32 v[116:117], v77
	v_cvt_pk_f32_fp8_sdwa v[118:119], v77 src0_sel:WORD_1
	v_cvt_pk_f32_fp8_e32 v[120:121], v78
	v_cvt_pk_f32_fp8_sdwa v[122:123], v78 src0_sel:WORD_1
	v_cvt_pk_f32_fp8_e32 v[124:125], v79
	v_cvt_pk_f32_fp8_sdwa v[126:127], v79 src0_sel:WORD_1
	v_readlane_b32 s2, v146, 7
	s_add_u32 s46, s40, s2
	s_addc_u32 s47, s41, 0
	global_load_dwordx4 v[76:79], v157, s[46:47]
	v_pk_mul_f32 v[138:139], v[112:113], v[32:33]
	v_pk_mul_f32 v[140:141], v[114:115], v[34:35]
	v_pk_fma_f32 v[138:139], v[116:117], v[36:37], v[138:139]
	v_pk_fma_f32 v[140:141], v[118:119], v[38:39], v[140:141]
	v_pk_fma_f32 v[138:139], v[120:121], v[40:41], v[138:139]
	v_pk_fma_f32 v[140:141], v[122:123], v[42:43], v[140:141]
	v_pk_fma_f32 v[138:139], v[124:125], v[44:45], v[138:139]
	v_pk_fma_f32 v[140:141], v[126:127], v[46:47], v[140:141]
	s_nop 0
	v_pk_add_f32 v[138:139], v[138:139], v[140:141]
	s_nop 0
	v_add_f32_e32 v137, v138, v139
.Lgx_p1end_9:
	s_nop 1
	v_permlane32_swap_b32_e32 v130, v134
	v_permlane32_swap_b32_e32 v131, v135
	v_permlane32_swap_b32_e32 v132, v136
	v_permlane32_swap_b32_e32 v133, v137
	v_add_f32_e32 v130, v130, v134
	v_add_f32_e32 v131, v131, v135
	v_add_f32_e32 v132, v132, v136
	v_add_f32_e32 v133, v133, v137
	s_nop 1
	v_permlane16_swap_b32_e32 v130, v132
	v_permlane16_swap_b32_e32 v131, v133
	v_add_f32_e32 v130, v130, v132
	v_add_f32_e32 v131, v131, v133
	s_nop 1
	v_add_f32_dpp v142, v130, v130 row_ror:8 row_mask:0xf bank_mask:0x3
	v_add_f32_dpp v142, v131, v131 row_ror:8 row_mask:0xf bank_mask:0xc
	s_nop 1
	v_add_f32_dpp v142, v142, v142 quad_perm:[1,0,3,2] row_mask:0xf bank_mask:0xf
	s_nop 1
	v_add_f32_dpp v142, v142, v142 quad_perm:[2,3,0,1] row_mask:0xf bank_mask:0xf
	s_nop 1
	v_add_f32_dpp v142, v142, v142 row_half_mirror row_mask:0xf bank_mask:0xf
	v_mul_f32_e32 v143, v148, v142
	v_mul_f32_e32 v144, 0x3d372713, v143
	v_mul_f32_e32 v144, v143, v144
	v_fma_f32 v144, v143, v144, v143
	v_mul_f32_e32 v144, 0x3f4c422a, v144
	v_mul_f32_e32 v144, -2.0, v144
	v_mul_f32_e32 v144, 0x3fb8aa3b, v144
	v_exp_f32_e32 v144, v144
	s_nop 0
	v_add_f32_e32 v144, 1.0, v144
	v_rcp_f32_e32 v144, v144
	s_nop 0
	v_mul_f32_e32 v143, v143, v144
	v_mul_f32_e32 v145, v149, v143
	ds_write_b32 v155, v145 offset:4736
	v_add_u32_e32 v155, 32, v155
	v_add_u32_e32 v154, 32, v154
	v_add_u32_e32 v156, 4, v156
	s_waitcnt lgkmcnt(0)
	v_readfirstlane_b32 s29, v153
	ds_read_b32 v146, v154 offset:96
	ds_read_b32 v148, v155 offset:2400
	ds_read_b32 v149, v155 offset:4768
	ds_read_b32 v152, v156 offset:7108
	s_cmp_eq_u32 s29, 1
	s_cbranch_scc1 .Lgx_p1g1_15
	s_cmp_eq_u32 s29, 2
	s_cbranch_scc1 .Lgx_p1g2_16
	s_waitcnt vmcnt(15)
	v_cvt_pk_f32_fp8_e32 v[112:113], v80
	v_cvt_pk_f32_fp8_sdwa v[114:115], v80 src0_sel:WORD_1
	v_cvt_pk_f32_fp8_e32 v[116:117], v81
	v_cvt_pk_f32_fp8_sdwa v[118:119], v81 src0_sel:WORD_1
	v_cvt_pk_f32_fp8_e32 v[120:121], v82
	v_cvt_pk_f32_fp8_sdwa v[122:123], v82 src0_sel:WORD_1
	v_cvt_pk_f32_fp8_e32 v[124:125], v83
	v_cvt_pk_f32_fp8_sdwa v[126:127], v83 src0_sel:WORD_1
	v_readlane_b32 s2, v147, 0
	s_add_u32 s46, s40, s2
	s_addc_u32 s47, s41, 0
	global_load_dwordx4 v[80:83], v157, s[46:47]
	v_pk_mul_f32 v[138:139], v[112:113], v[0:1]
	v_pk_mul_f32 v[140:141], v[114:115], v[2:3]
	v_pk_fma_f32 v[138:139], v[116:117], v[4:5], v[138:139]
	v_pk_fma_f32 v[140:141], v[118:119], v[6:7], v[140:141]
	v_pk_fma_f32 v[138:139], v[120:121], v[8:9], v[138:139]
	v_pk_fma_f32 v[140:141], v[122:123], v[10:11], v[140:141]
	v_pk_fma_f32 v[138:139], v[124:125], v[12:13], v[138:139]
	v_pk_fma_f32 v[140:141], v[126:127], v[14:15], v[140:141]
	s_nop 0
	v_pk_add_f32 v[138:139], v[138:139], v[140:141]
	s_waitcnt vmcnt(15)
	v_add_f32_e32 v130, v138, v139
	v_cvt_pk_f32_fp8_e32 v[112:113], v84
	v_cvt_pk_f32_fp8_sdwa v[114:115], v84 src0_sel:WORD_1
	v_cvt_pk_f32_fp8_e32 v[116:117], v85
	v_cvt_pk_f32_fp8_sdwa v[118:119], v85 src0_sel:WORD_1
	v_cvt_pk_f32_fp8_e32 v[120:121], v86
	v_cvt_pk_f32_fp8_sdwa v[122:123], v86 src0_sel:WORD_1
	v_cvt_pk_f32_fp8_e32 v[124:125], v87
	v_cvt_pk_f32_fp8_sdwa v[126:127], v87 src0_sel:WORD_1
	v_readlane_b32 s2, v147, 1
	s_add_u32 s46, s40, s2
	s_addc_u32 s47, s41, 0
	global_load_dwordx4 v[84:87], v157, s[46:47]
	v_pk_mul_f32 v[138:139], v[112:113], v[0:1]
	v_pk_mul_f32 v[140:141], v[114:115], v[2:3]
	v_pk_fma_f32 v[138:139], v[116:117], v[4:5], v[138:139]
	v_pk_fma_f32 v[140:141], v[118:119], v[6:7], v[140:141]
	v_pk_fma_f32 v[138:139], v[120:121], v[8:9], v[138:139]
	v_pk_fma_f32 v[140:141], v[122:123], v[10:11], v[140:141]
	v_pk_fma_f32 v[138:139], v[124:125], v[12:13], v[138:139]
	v_pk_fma_f32 v[140:141], v[126:127], v[14:15], v[140:141]
	s_nop 0
	v_pk_add_f32 v[138:139], v[138:139], v[140:141]
	s_waitcnt vmcnt(15)
	v_add_f32_e32 v131, v138, v139
	v_cvt_pk_f32_fp8_e32 v[112:113], v88
	v_cvt_pk_f32_fp8_sdwa v[114:115], v88 src0_sel:WORD_1
	v_cvt_pk_f32_fp8_e32 v[116:117], v89
	v_cvt_pk_f32_fp8_sdwa v[118:119], v89 src0_sel:WORD_1
	v_cvt_pk_f32_fp8_e32 v[120:121], v90
	v_cvt_pk_f32_fp8_sdwa v[122:123], v90 src0_sel:WORD_1
	v_cvt_pk_f32_fp8_e32 v[124:125], v91
	v_cvt_pk_f32_fp8_sdwa v[126:127], v91 src0_sel:WORD_1
	v_readlane_b32 s2, v147, 2
	s_add_u32 s46, s40, s2
	s_addc_u32 s47, s41, 0
	global_load_dwordx4 v[88:91], v157, s[46:47]
	v_pk_mul_f32 v[138:139], v[112:113], v[0:1]
	v_pk_mul_f32 v[140:141], v[114:115], v[2:3]
	v_pk_fma_f32 v[138:139], v[116:117], v[4:5], v[138:139]
	v_pk_fma_f32 v[140:141], v[118:119], v[6:7], v[140:141]
	v_pk_fma_f32 v[138:139], v[120:121], v[8:9], v[138:139]
	v_pk_fma_f32 v[140:141], v[122:123], v[10:11], v[140:141]
	v_pk_fma_f32 v[138:139], v[124:125], v[12:13], v[138:139]
	v_pk_fma_f32 v[140:141], v[126:127], v[14:15], v[140:141]
	s_nop 0
	v_pk_add_f32 v[138:139], v[138:139], v[140:141]
	s_waitcnt vmcnt(15)
	v_add_f32_e32 v132, v138, v139
	v_cvt_pk_f32_fp8_e32 v[112:113], v92
	v_cvt_pk_f32_fp8_sdwa v[114:115], v92 src0_sel:WORD_1
	v_cvt_pk_f32_fp8_e32 v[116:117], v93
	v_cvt_pk_f32_fp8_sdwa v[118:119], v93 src0_sel:WORD_1
	v_cvt_pk_f32_fp8_e32 v[120:121], v94
	v_cvt_pk_f32_fp8_sdwa v[122:123], v94 src0_sel:WORD_1
	v_cvt_pk_f32_fp8_e32 v[124:125], v95
	v_cvt_pk_f32_fp8_sdwa v[126:127], v95 src0_sel:WORD_1
	v_readlane_b32 s2, v147, 3
	s_add_u32 s46, s40, s2
	s_addc_u32 s47, s41, 0
	global_load_dwordx4 v[92:95], v157, s[46:47]
	v_pk_mul_f32 v[138:139], v[112:113], v[0:1]
	v_pk_mul_f32 v[140:141], v[114:115], v[2:3]
	v_pk_fma_f32 v[138:139], v[116:117], v[4:5], v[138:139]
	v_pk_fma_f32 v[140:141], v[118:119], v[6:7], v[140:141]
	v_pk_fma_f32 v[138:139], v[120:121], v[8:9], v[138:139]
	v_pk_fma_f32 v[140:141], v[122:123], v[10:11], v[140:141]
	v_pk_fma_f32 v[138:139], v[124:125], v[12:13], v[138:139]
	v_pk_fma_f32 v[140:141], v[126:127], v[14:15], v[140:141]
	s_nop 0
	v_pk_add_f32 v[138:139], v[138:139], v[140:141]
	s_waitcnt vmcnt(15)
	v_add_f32_e32 v133, v138, v139
	v_cvt_pk_f32_fp8_e32 v[112:113], v96
	v_cvt_pk_f32_fp8_sdwa v[114:115], v96 src0_sel:WORD_1
	v_cvt_pk_f32_fp8_e32 v[116:117], v97
	v_cvt_pk_f32_fp8_sdwa v[118:119], v97 src0_sel:WORD_1
	v_cvt_pk_f32_fp8_e32 v[120:121], v98
	v_cvt_pk_f32_fp8_sdwa v[122:123], v98 src0_sel:WORD_1
	v_cvt_pk_f32_fp8_e32 v[124:125], v99
	v_cvt_pk_f32_fp8_sdwa v[126:127], v99 src0_sel:WORD_1
	v_readlane_b32 s2, v147, 4
	s_add_u32 s46, s40, s2
	s_addc_u32 s47, s41, 0
	global_load_dwordx4 v[96:99], v157, s[46:47]
	v_pk_mul_f32 v[138:139], v[112:113], v[0:1]
	v_pk_mul_f32 v[140:141], v[114:115], v[2:3]
	v_pk_fma_f32 v[138:139], v[116:117], v[4:5], v[138:139]
	v_pk_fma_f32 v[140:141], v[118:119], v[6:7], v[140:141]
	v_pk_fma_f32 v[138:139], v[120:121], v[8:9], v[138:139]
	v_pk_fma_f32 v[140:141], v[122:123], v[10:11], v[140:141]
	v_pk_fma_f32 v[138:139], v[124:125], v[12:13], v[138:139]
	v_pk_fma_f32 v[140:141], v[126:127], v[14:15], v[140:141]
	s_nop 0
	v_pk_add_f32 v[138:139], v[138:139], v[140:141]
	s_waitcnt vmcnt(15)
	v_add_f32_e32 v134, v138, v139
	v_cvt_pk_f32_fp8_e32 v[112:113], v100
	v_cvt_pk_f32_fp8_sdwa v[114:115], v100 src0_sel:WORD_1
	v_cvt_pk_f32_fp8_e32 v[116:117], v101
	v_cvt_pk_f32_fp8_sdwa v[118:119], v101 src0_sel:WORD_1
	v_cvt_pk_f32_fp8_e32 v[120:121], v102
	v_cvt_pk_f32_fp8_sdwa v[122:123], v102 src0_sel:WORD_1
	v_cvt_pk_f32_fp8_e32 v[124:125], v103
	v_cvt_pk_f32_fp8_sdwa v[126:127], v103 src0_sel:WORD_1
	v_readlane_b32 s2, v147, 5
	s_add_u32 s46, s40, s2
	s_addc_u32 s47, s41, 0
	global_load_dwordx4 v[100:103], v157, s[46:47]
	v_pk_mul_f32 v[138:139], v[112:113], v[0:1]
	v_pk_mul_f32 v[140:141], v[114:115], v[2:3]
	v_pk_fma_f32 v[138:139], v[116:117], v[4:5], v[138:139]
	v_pk_fma_f32 v[140:141], v[118:119], v[6:7], v[140:141]
	v_pk_fma_f32 v[138:139], v[120:121], v[8:9], v[138:139]
	v_pk_fma_f32 v[140:141], v[122:123], v[10:11], v[140:141]
	v_pk_fma_f32 v[138:139], v[124:125], v[12:13], v[138:139]
	v_pk_fma_f32 v[140:141], v[126:127], v[14:15], v[140:141]
	s_nop 0
	v_pk_add_f32 v[138:139], v[138:139], v[140:141]
	s_waitcnt vmcnt(15)
	v_add_f32_e32 v135, v138, v139
	v_cvt_pk_f32_fp8_e32 v[112:113], v104
	v_cvt_pk_f32_fp8_sdwa v[114:115], v104 src0_sel:WORD_1
	v_cvt_pk_f32_fp8_e32 v[116:117], v105
	v_cvt_pk_f32_fp8_sdwa v[118:119], v105 src0_sel:WORD_1
	v_cvt_pk_f32_fp8_e32 v[120:121], v106
	v_cvt_pk_f32_fp8_sdwa v[122:123], v106 src0_sel:WORD_1
	v_cvt_pk_f32_fp8_e32 v[124:125], v107
	v_cvt_pk_f32_fp8_sdwa v[126:127], v107 src0_sel:WORD_1
	v_readlane_b32 s2, v147, 6
	s_add_u32 s46, s40, s2
	s_addc_u32 s47, s41, 0
	global_load_dwordx4 v[104:107], v157, s[46:47]
	v_pk_mul_f32 v[138:139], v[112:113], v[0:1]
	v_pk_mul_f32 v[140:141], v[114:115], v[2:3]
	v_pk_fma_f32 v[138:139], v[116:117], v[4:5], v[138:139]
	v_pk_fma_f32 v[140:141], v[118:119], v[6:7], v[140:141]
	v_pk_fma_f32 v[138:139], v[120:121], v[8:9], v[138:139]
	v_pk_fma_f32 v[140:141], v[122:123], v[10:11], v[140:141]
	v_pk_fma_f32 v[138:139], v[124:125], v[12:13], v[138:139]
	v_pk_fma_f32 v[140:141], v[126:127], v[14:15], v[140:141]
	s_nop 0
	v_pk_add_f32 v[138:139], v[138:139], v[140:141]
	s_waitcnt vmcnt(15)
	v_add_f32_e32 v136, v138, v139
	v_cvt_pk_f32_fp8_e32 v[112:113], v108
	v_cvt_pk_f32_fp8_sdwa v[114:115], v108 src0_sel:WORD_1
	v_cvt_pk_f32_fp8_e32 v[116:117], v109
	v_cvt_pk_f32_fp8_sdwa v[118:119], v109 src0_sel:WORD_1
	v_cvt_pk_f32_fp8_e32 v[120:121], v110
	v_cvt_pk_f32_fp8_sdwa v[122:123], v110 src0_sel:WORD_1
	v_cvt_pk_f32_fp8_e32 v[124:125], v111
	v_cvt_pk_f32_fp8_sdwa v[126:127], v111 src0_sel:WORD_1
	v_readlane_b32 s2, v147, 7
	s_add_u32 s46, s40, s2
	s_addc_u32 s47, s41, 0
	global_load_dwordx4 v[108:111], v157, s[46:47]
	v_pk_mul_f32 v[138:139], v[112:113], v[0:1]
	v_pk_mul_f32 v[140:141], v[114:115], v[2:3]
	v_pk_fma_f32 v[138:139], v[116:117], v[4:5], v[138:139]
	v_pk_fma_f32 v[140:141], v[118:119], v[6:7], v[140:141]
	v_pk_fma_f32 v[138:139], v[120:121], v[8:9], v[138:139]
	v_pk_fma_f32 v[140:141], v[122:123], v[10:11], v[140:141]
	v_pk_fma_f32 v[138:139], v[124:125], v[12:13], v[138:139]
	v_pk_fma_f32 v[140:141], v[126:127], v[14:15], v[140:141]
	s_nop 0
	v_pk_add_f32 v[138:139], v[138:139], v[140:141]
	s_nop 0
	v_add_f32_e32 v137, v138, v139
	s_branch .Lgx_p1end_13
.Lgx_p1g1_15:
	s_waitcnt vmcnt(15)
	v_cvt_pk_f32_fp8_e32 v[112:113], v80
	v_cvt_pk_f32_fp8_sdwa v[114:115], v80 src0_sel:WORD_1
	v_cvt_pk_f32_fp8_e32 v[116:117], v81
	v_cvt_pk_f32_fp8_sdwa v[118:119], v81 src0_sel:WORD_1
	v_cvt_pk_f32_fp8_e32 v[120:121], v82
	v_cvt_pk_f32_fp8_sdwa v[122:123], v82 src0_sel:WORD_1
	v_cvt_pk_f32_fp8_e32 v[124:125], v83
	v_cvt_pk_f32_fp8_sdwa v[126:127], v83 src0_sel:WORD_1
	v_readlane_b32 s2, v147, 0
	s_add_u32 s46, s40, s2
	s_addc_u32 s47, s41, 0
	global_load_dwordx4 v[80:83], v157, s[46:47]
	v_pk_mul_f32 v[138:139], v[112:113], v[16:17]
	v_pk_mul_f32 v[140:141], v[114:115], v[18:19]
	v_pk_fma_f32 v[138:139], v[116:117], v[20:21], v[138:139]
	v_pk_fma_f32 v[140:141], v[118:119], v[22:23], v[140:141]
	v_pk_fma_f32 v[138:139], v[120:121], v[24:25], v[138:139]
	v_pk_fma_f32 v[140:141], v[122:123], v[26:27], v[140:141]
	v_pk_fma_f32 v[138:139], v[124:125], v[28:29], v[138:139]
	v_pk_fma_f32 v[140:141], v[126:127], v[30:31], v[140:141]
	s_nop 0
	v_pk_add_f32 v[138:139], v[138:139], v[140:141]
	s_waitcnt vmcnt(15)
	v_add_f32_e32 v130, v138, v139
	v_cvt_pk_f32_fp8_e32 v[112:113], v84
	v_cvt_pk_f32_fp8_sdwa v[114:115], v84 src0_sel:WORD_1
	v_cvt_pk_f32_fp8_e32 v[116:117], v85
	v_cvt_pk_f32_fp8_sdwa v[118:119], v85 src0_sel:WORD_1
	v_cvt_pk_f32_fp8_e32 v[120:121], v86
	v_cvt_pk_f32_fp8_sdwa v[122:123], v86 src0_sel:WORD_1
	v_cvt_pk_f32_fp8_e32 v[124:125], v87
	v_cvt_pk_f32_fp8_sdwa v[126:127], v87 src0_sel:WORD_1
	v_readlane_b32 s2, v147, 1
	s_add_u32 s46, s40, s2
	s_addc_u32 s47, s41, 0
	global_load_dwordx4 v[84:87], v157, s[46:47]
	v_pk_mul_f32 v[138:139], v[112:113], v[16:17]
	v_pk_mul_f32 v[140:141], v[114:115], v[18:19]
	v_pk_fma_f32 v[138:139], v[116:117], v[20:21], v[138:139]
	v_pk_fma_f32 v[140:141], v[118:119], v[22:23], v[140:141]
	v_pk_fma_f32 v[138:139], v[120:121], v[24:25], v[138:139]
	v_pk_fma_f32 v[140:141], v[122:123], v[26:27], v[140:141]
	v_pk_fma_f32 v[138:139], v[124:125], v[28:29], v[138:139]
	v_pk_fma_f32 v[140:141], v[126:127], v[30:31], v[140:141]
	s_nop 0
	v_pk_add_f32 v[138:139], v[138:139], v[140:141]
	s_waitcnt vmcnt(15)
	v_add_f32_e32 v131, v138, v139
	v_cvt_pk_f32_fp8_e32 v[112:113], v88
	v_cvt_pk_f32_fp8_sdwa v[114:115], v88 src0_sel:WORD_1
	v_cvt_pk_f32_fp8_e32 v[116:117], v89
	v_cvt_pk_f32_fp8_sdwa v[118:119], v89 src0_sel:WORD_1
	v_cvt_pk_f32_fp8_e32 v[120:121], v90
	v_cvt_pk_f32_fp8_sdwa v[122:123], v90 src0_sel:WORD_1
	v_cvt_pk_f32_fp8_e32 v[124:125], v91
	v_cvt_pk_f32_fp8_sdwa v[126:127], v91 src0_sel:WORD_1
	v_readlane_b32 s2, v147, 2
	s_add_u32 s46, s40, s2
	s_addc_u32 s47, s41, 0
	global_load_dwordx4 v[88:91], v157, s[46:47]
	v_pk_mul_f32 v[138:139], v[112:113], v[16:17]
	v_pk_mul_f32 v[140:141], v[114:115], v[18:19]
	v_pk_fma_f32 v[138:139], v[116:117], v[20:21], v[138:139]
	v_pk_fma_f32 v[140:141], v[118:119], v[22:23], v[140:141]
	v_pk_fma_f32 v[138:139], v[120:121], v[24:25], v[138:139]
	v_pk_fma_f32 v[140:141], v[122:123], v[26:27], v[140:141]
	v_pk_fma_f32 v[138:139], v[124:125], v[28:29], v[138:139]
	v_pk_fma_f32 v[140:141], v[126:127], v[30:31], v[140:141]
	s_nop 0
	v_pk_add_f32 v[138:139], v[138:139], v[140:141]
	s_waitcnt vmcnt(15)
	v_add_f32_e32 v132, v138, v139
	v_cvt_pk_f32_fp8_e32 v[112:113], v92
	v_cvt_pk_f32_fp8_sdwa v[114:115], v92 src0_sel:WORD_1
	v_cvt_pk_f32_fp8_e32 v[116:117], v93
	v_cvt_pk_f32_fp8_sdwa v[118:119], v93 src0_sel:WORD_1
	v_cvt_pk_f32_fp8_e32 v[120:121], v94
	v_cvt_pk_f32_fp8_sdwa v[122:123], v94 src0_sel:WORD_1
	v_cvt_pk_f32_fp8_e32 v[124:125], v95
	v_cvt_pk_f32_fp8_sdwa v[126:127], v95 src0_sel:WORD_1
	v_readlane_b32 s2, v147, 3
	s_add_u32 s46, s40, s2
	s_addc_u32 s47, s41, 0
	global_load_dwordx4 v[92:95], v157, s[46:47]
	v_pk_mul_f32 v[138:139], v[112:113], v[16:17]
	v_pk_mul_f32 v[140:141], v[114:115], v[18:19]
	v_pk_fma_f32 v[138:139], v[116:117], v[20:21], v[138:139]
	v_pk_fma_f32 v[140:141], v[118:119], v[22:23], v[140:141]
	v_pk_fma_f32 v[138:139], v[120:121], v[24:25], v[138:139]
	v_pk_fma_f32 v[140:141], v[122:123], v[26:27], v[140:141]
	v_pk_fma_f32 v[138:139], v[124:125], v[28:29], v[138:139]
	v_pk_fma_f32 v[140:141], v[126:127], v[30:31], v[140:141]
	s_nop 0
	v_pk_add_f32 v[138:139], v[138:139], v[140:141]
	s_waitcnt vmcnt(15)
	v_add_f32_e32 v133, v138, v139
	v_cvt_pk_f32_fp8_e32 v[112:113], v96
	v_cvt_pk_f32_fp8_sdwa v[114:115], v96 src0_sel:WORD_1
	v_cvt_pk_f32_fp8_e32 v[116:117], v97
	v_cvt_pk_f32_fp8_sdwa v[118:119], v97 src0_sel:WORD_1
	v_cvt_pk_f32_fp8_e32 v[120:121], v98
	v_cvt_pk_f32_fp8_sdwa v[122:123], v98 src0_sel:WORD_1
	v_cvt_pk_f32_fp8_e32 v[124:125], v99
	v_cvt_pk_f32_fp8_sdwa v[126:127], v99 src0_sel:WORD_1
	v_readlane_b32 s2, v147, 4
	s_add_u32 s46, s40, s2
	s_addc_u32 s47, s41, 0
	global_load_dwordx4 v[96:99], v157, s[46:47]
	v_pk_mul_f32 v[138:139], v[112:113], v[16:17]
	v_pk_mul_f32 v[140:141], v[114:115], v[18:19]
	v_pk_fma_f32 v[138:139], v[116:117], v[20:21], v[138:139]
	v_pk_fma_f32 v[140:141], v[118:119], v[22:23], v[140:141]
	v_pk_fma_f32 v[138:139], v[120:121], v[24:25], v[138:139]
	v_pk_fma_f32 v[140:141], v[122:123], v[26:27], v[140:141]
	v_pk_fma_f32 v[138:139], v[124:125], v[28:29], v[138:139]
	v_pk_fma_f32 v[140:141], v[126:127], v[30:31], v[140:141]
	s_nop 0
	v_pk_add_f32 v[138:139], v[138:139], v[140:141]
	s_waitcnt vmcnt(15)
	v_add_f32_e32 v134, v138, v139
	v_cvt_pk_f32_fp8_e32 v[112:113], v100
	v_cvt_pk_f32_fp8_sdwa v[114:115], v100 src0_sel:WORD_1
	v_cvt_pk_f32_fp8_e32 v[116:117], v101
	v_cvt_pk_f32_fp8_sdwa v[118:119], v101 src0_sel:WORD_1
	v_cvt_pk_f32_fp8_e32 v[120:121], v102
	v_cvt_pk_f32_fp8_sdwa v[122:123], v102 src0_sel:WORD_1
	v_cvt_pk_f32_fp8_e32 v[124:125], v103
	v_cvt_pk_f32_fp8_sdwa v[126:127], v103 src0_sel:WORD_1
	v_readlane_b32 s2, v147, 5
	s_add_u32 s46, s40, s2
	s_addc_u32 s47, s41, 0
	global_load_dwordx4 v[100:103], v157, s[46:47]
	v_pk_mul_f32 v[138:139], v[112:113], v[16:17]
	v_pk_mul_f32 v[140:141], v[114:115], v[18:19]
	v_pk_fma_f32 v[138:139], v[116:117], v[20:21], v[138:139]
	v_pk_fma_f32 v[140:141], v[118:119], v[22:23], v[140:141]
	v_pk_fma_f32 v[138:139], v[120:121], v[24:25], v[138:139]
	v_pk_fma_f32 v[140:141], v[122:123], v[26:27], v[140:141]
	v_pk_fma_f32 v[138:139], v[124:125], v[28:29], v[138:139]
	v_pk_fma_f32 v[140:141], v[126:127], v[30:31], v[140:141]
	s_nop 0
	v_pk_add_f32 v[138:139], v[138:139], v[140:141]
	s_waitcnt vmcnt(15)
	v_add_f32_e32 v135, v138, v139
	v_cvt_pk_f32_fp8_e32 v[112:113], v104
	v_cvt_pk_f32_fp8_sdwa v[114:115], v104 src0_sel:WORD_1
	v_cvt_pk_f32_fp8_e32 v[116:117], v105
	v_cvt_pk_f32_fp8_sdwa v[118:119], v105 src0_sel:WORD_1
	v_cvt_pk_f32_fp8_e32 v[120:121], v106
	v_cvt_pk_f32_fp8_sdwa v[122:123], v106 src0_sel:WORD_1
	v_cvt_pk_f32_fp8_e32 v[124:125], v107
	v_cvt_pk_f32_fp8_sdwa v[126:127], v107 src0_sel:WORD_1
	v_readlane_b32 s2, v147, 6
	s_add_u32 s46, s40, s2
	s_addc_u32 s47, s41, 0
	global_load_dwordx4 v[104:107], v157, s[46:47]
	v_pk_mul_f32 v[138:139], v[112:113], v[16:17]
	v_pk_mul_f32 v[140:141], v[114:115], v[18:19]
	v_pk_fma_f32 v[138:139], v[116:117], v[20:21], v[138:139]
	v_pk_fma_f32 v[140:141], v[118:119], v[22:23], v[140:141]
	v_pk_fma_f32 v[138:139], v[120:121], v[24:25], v[138:139]
	v_pk_fma_f32 v[140:141], v[122:123], v[26:27], v[140:141]
	v_pk_fma_f32 v[138:139], v[124:125], v[28:29], v[138:139]
	v_pk_fma_f32 v[140:141], v[126:127], v[30:31], v[140:141]
	s_nop 0
	v_pk_add_f32 v[138:139], v[138:139], v[140:141]
	s_waitcnt vmcnt(15)
	v_add_f32_e32 v136, v138, v139
	v_cvt_pk_f32_fp8_e32 v[112:113], v108
	v_cvt_pk_f32_fp8_sdwa v[114:115], v108 src0_sel:WORD_1
	v_cvt_pk_f32_fp8_e32 v[116:117], v109
	v_cvt_pk_f32_fp8_sdwa v[118:119], v109 src0_sel:WORD_1
	v_cvt_pk_f32_fp8_e32 v[120:121], v110
	v_cvt_pk_f32_fp8_sdwa v[122:123], v110 src0_sel:WORD_1
	v_cvt_pk_f32_fp8_e32 v[124:125], v111
	v_cvt_pk_f32_fp8_sdwa v[126:127], v111 src0_sel:WORD_1
	v_readlane_b32 s2, v147, 7
	s_add_u32 s46, s40, s2
	s_addc_u32 s47, s41, 0
	global_load_dwordx4 v[108:111], v157, s[46:47]
	v_pk_mul_f32 v[138:139], v[112:113], v[16:17]
	v_pk_mul_f32 v[140:141], v[114:115], v[18:19]
	v_pk_fma_f32 v[138:139], v[116:117], v[20:21], v[138:139]
	v_pk_fma_f32 v[140:141], v[118:119], v[22:23], v[140:141]
	v_pk_fma_f32 v[138:139], v[120:121], v[24:25], v[138:139]
	v_pk_fma_f32 v[140:141], v[122:123], v[26:27], v[140:141]
	v_pk_fma_f32 v[138:139], v[124:125], v[28:29], v[138:139]
	v_pk_fma_f32 v[140:141], v[126:127], v[30:31], v[140:141]
	s_nop 0
	v_pk_add_f32 v[138:139], v[138:139], v[140:141]
	s_nop 0
	v_add_f32_e32 v137, v138, v139
	s_branch .Lgx_p1end_13
.Lgx_p1g2_16:
	s_waitcnt vmcnt(15)
	v_cvt_pk_f32_fp8_e32 v[112:113], v80
	v_cvt_pk_f32_fp8_sdwa v[114:115], v80 src0_sel:WORD_1
	v_cvt_pk_f32_fp8_e32 v[116:117], v81
	v_cvt_pk_f32_fp8_sdwa v[118:119], v81 src0_sel:WORD_1
	v_cvt_pk_f32_fp8_e32 v[120:121], v82
	v_cvt_pk_f32_fp8_sdwa v[122:123], v82 src0_sel:WORD_1
	v_cvt_pk_f32_fp8_e32 v[124:125], v83
	v_cvt_pk_f32_fp8_sdwa v[126:127], v83 src0_sel:WORD_1
	v_readlane_b32 s2, v147, 0
	s_add_u32 s46, s40, s2
	s_addc_u32 s47, s41, 0
	global_load_dwordx4 v[80:83], v157, s[46:47]
	v_pk_mul_f32 v[138:139], v[112:113], v[32:33]
	v_pk_mul_f32 v[140:141], v[114:115], v[34:35]
	v_pk_fma_f32 v[138:139], v[116:117], v[36:37], v[138:139]
	v_pk_fma_f32 v[140:141], v[118:119], v[38:39], v[140:141]
	v_pk_fma_f32 v[138:139], v[120:121], v[40:41], v[138:139]
	v_pk_fma_f32 v[140:141], v[122:123], v[42:43], v[140:141]
	v_pk_fma_f32 v[138:139], v[124:125], v[44:45], v[138:139]
	v_pk_fma_f32 v[140:141], v[126:127], v[46:47], v[140:141]
	s_nop 0
	v_pk_add_f32 v[138:139], v[138:139], v[140:141]
	s_waitcnt vmcnt(15)
	v_add_f32_e32 v130, v138, v139
	v_cvt_pk_f32_fp8_e32 v[112:113], v84
	v_cvt_pk_f32_fp8_sdwa v[114:115], v84 src0_sel:WORD_1
	v_cvt_pk_f32_fp8_e32 v[116:117], v85
	v_cvt_pk_f32_fp8_sdwa v[118:119], v85 src0_sel:WORD_1
	v_cvt_pk_f32_fp8_e32 v[120:121], v86
	v_cvt_pk_f32_fp8_sdwa v[122:123], v86 src0_sel:WORD_1
	v_cvt_pk_f32_fp8_e32 v[124:125], v87
	v_cvt_pk_f32_fp8_sdwa v[126:127], v87 src0_sel:WORD_1
	v_readlane_b32 s2, v147, 1
	s_add_u32 s46, s40, s2
	s_addc_u32 s47, s41, 0
	global_load_dwordx4 v[84:87], v157, s[46:47]
	v_pk_mul_f32 v[138:139], v[112:113], v[32:33]
	v_pk_mul_f32 v[140:141], v[114:115], v[34:35]
	v_pk_fma_f32 v[138:139], v[116:117], v[36:37], v[138:139]
	v_pk_fma_f32 v[140:141], v[118:119], v[38:39], v[140:141]
	v_pk_fma_f32 v[138:139], v[120:121], v[40:41], v[138:139]
	v_pk_fma_f32 v[140:141], v[122:123], v[42:43], v[140:141]
	v_pk_fma_f32 v[138:139], v[124:125], v[44:45], v[138:139]
	v_pk_fma_f32 v[140:141], v[126:127], v[46:47], v[140:141]
	s_nop 0
	v_pk_add_f32 v[138:139], v[138:139], v[140:141]
	s_waitcnt vmcnt(15)
	v_add_f32_e32 v131, v138, v139
	v_cvt_pk_f32_fp8_e32 v[112:113], v88
	v_cvt_pk_f32_fp8_sdwa v[114:115], v88 src0_sel:WORD_1
	v_cvt_pk_f32_fp8_e32 v[116:117], v89
	v_cvt_pk_f32_fp8_sdwa v[118:119], v89 src0_sel:WORD_1
	v_cvt_pk_f32_fp8_e32 v[120:121], v90
	v_cvt_pk_f32_fp8_sdwa v[122:123], v90 src0_sel:WORD_1
	v_cvt_pk_f32_fp8_e32 v[124:125], v91
	v_cvt_pk_f32_fp8_sdwa v[126:127], v91 src0_sel:WORD_1
	v_readlane_b32 s2, v147, 2
	s_add_u32 s46, s40, s2
	s_addc_u32 s47, s41, 0
	global_load_dwordx4 v[88:91], v157, s[46:47]
	v_pk_mul_f32 v[138:139], v[112:113], v[32:33]
	v_pk_mul_f32 v[140:141], v[114:115], v[34:35]
	v_pk_fma_f32 v[138:139], v[116:117], v[36:37], v[138:139]
	v_pk_fma_f32 v[140:141], v[118:119], v[38:39], v[140:141]
	v_pk_fma_f32 v[138:139], v[120:121], v[40:41], v[138:139]
	v_pk_fma_f32 v[140:141], v[122:123], v[42:43], v[140:141]
	v_pk_fma_f32 v[138:139], v[124:125], v[44:45], v[138:139]
	v_pk_fma_f32 v[140:141], v[126:127], v[46:47], v[140:141]
	s_nop 0
	v_pk_add_f32 v[138:139], v[138:139], v[140:141]
	s_waitcnt vmcnt(15)
	v_add_f32_e32 v132, v138, v139
	v_cvt_pk_f32_fp8_e32 v[112:113], v92
	v_cvt_pk_f32_fp8_sdwa v[114:115], v92 src0_sel:WORD_1
	v_cvt_pk_f32_fp8_e32 v[116:117], v93
	v_cvt_pk_f32_fp8_sdwa v[118:119], v93 src0_sel:WORD_1
	v_cvt_pk_f32_fp8_e32 v[120:121], v94
	v_cvt_pk_f32_fp8_sdwa v[122:123], v94 src0_sel:WORD_1
	v_cvt_pk_f32_fp8_e32 v[124:125], v95
	v_cvt_pk_f32_fp8_sdwa v[126:127], v95 src0_sel:WORD_1
	v_readlane_b32 s2, v147, 3
	s_add_u32 s46, s40, s2
	s_addc_u32 s47, s41, 0
	global_load_dwordx4 v[92:95], v157, s[46:47]
	v_pk_mul_f32 v[138:139], v[112:113], v[32:33]
	v_pk_mul_f32 v[140:141], v[114:115], v[34:35]
	v_pk_fma_f32 v[138:139], v[116:117], v[36:37], v[138:139]
	v_pk_fma_f32 v[140:141], v[118:119], v[38:39], v[140:141]
	v_pk_fma_f32 v[138:139], v[120:121], v[40:41], v[138:139]
	v_pk_fma_f32 v[140:141], v[122:123], v[42:43], v[140:141]
	v_pk_fma_f32 v[138:139], v[124:125], v[44:45], v[138:139]
	v_pk_fma_f32 v[140:141], v[126:127], v[46:47], v[140:141]
	s_nop 0
	v_pk_add_f32 v[138:139], v[138:139], v[140:141]
	s_waitcnt vmcnt(15)
	v_add_f32_e32 v133, v138, v139
	v_cvt_pk_f32_fp8_e32 v[112:113], v96
	v_cvt_pk_f32_fp8_sdwa v[114:115], v96 src0_sel:WORD_1
	v_cvt_pk_f32_fp8_e32 v[116:117], v97
	v_cvt_pk_f32_fp8_sdwa v[118:119], v97 src0_sel:WORD_1
	v_cvt_pk_f32_fp8_e32 v[120:121], v98
	v_cvt_pk_f32_fp8_sdwa v[122:123], v98 src0_sel:WORD_1
	v_cvt_pk_f32_fp8_e32 v[124:125], v99
	v_cvt_pk_f32_fp8_sdwa v[126:127], v99 src0_sel:WORD_1
	v_readlane_b32 s2, v147, 4
	s_add_u32 s46, s40, s2
	s_addc_u32 s47, s41, 0
	global_load_dwordx4 v[96:99], v157, s[46:47]
	v_pk_mul_f32 v[138:139], v[112:113], v[32:33]
	v_pk_mul_f32 v[140:141], v[114:115], v[34:35]
	v_pk_fma_f32 v[138:139], v[116:117], v[36:37], v[138:139]
	v_pk_fma_f32 v[140:141], v[118:119], v[38:39], v[140:141]
	v_pk_fma_f32 v[138:139], v[120:121], v[40:41], v[138:139]
	v_pk_fma_f32 v[140:141], v[122:123], v[42:43], v[140:141]
	v_pk_fma_f32 v[138:139], v[124:125], v[44:45], v[138:139]
	v_pk_fma_f32 v[140:141], v[126:127], v[46:47], v[140:141]
	s_nop 0
	v_pk_add_f32 v[138:139], v[138:139], v[140:141]
	s_waitcnt vmcnt(15)
	v_add_f32_e32 v134, v138, v139
	v_cvt_pk_f32_fp8_e32 v[112:113], v100
	v_cvt_pk_f32_fp8_sdwa v[114:115], v100 src0_sel:WORD_1
	v_cvt_pk_f32_fp8_e32 v[116:117], v101
	v_cvt_pk_f32_fp8_sdwa v[118:119], v101 src0_sel:WORD_1
	v_cvt_pk_f32_fp8_e32 v[120:121], v102
	v_cvt_pk_f32_fp8_sdwa v[122:123], v102 src0_sel:WORD_1
	v_cvt_pk_f32_fp8_e32 v[124:125], v103
	v_cvt_pk_f32_fp8_sdwa v[126:127], v103 src0_sel:WORD_1
	v_readlane_b32 s2, v147, 5
	s_add_u32 s46, s40, s2
	s_addc_u32 s47, s41, 0
	global_load_dwordx4 v[100:103], v157, s[46:47]
	v_pk_mul_f32 v[138:139], v[112:113], v[32:33]
	v_pk_mul_f32 v[140:141], v[114:115], v[34:35]
	v_pk_fma_f32 v[138:139], v[116:117], v[36:37], v[138:139]
	v_pk_fma_f32 v[140:141], v[118:119], v[38:39], v[140:141]
	v_pk_fma_f32 v[138:139], v[120:121], v[40:41], v[138:139]
	v_pk_fma_f32 v[140:141], v[122:123], v[42:43], v[140:141]
	v_pk_fma_f32 v[138:139], v[124:125], v[44:45], v[138:139]
	v_pk_fma_f32 v[140:141], v[126:127], v[46:47], v[140:141]
	s_nop 0
	v_pk_add_f32 v[138:139], v[138:139], v[140:141]
	s_waitcnt vmcnt(15)
	v_add_f32_e32 v135, v138, v139
	v_cvt_pk_f32_fp8_e32 v[112:113], v104
	v_cvt_pk_f32_fp8_sdwa v[114:115], v104 src0_sel:WORD_1
	v_cvt_pk_f32_fp8_e32 v[116:117], v105
	v_cvt_pk_f32_fp8_sdwa v[118:119], v105 src0_sel:WORD_1
	v_cvt_pk_f32_fp8_e32 v[120:121], v106
	v_cvt_pk_f32_fp8_sdwa v[122:123], v106 src0_sel:WORD_1
	v_cvt_pk_f32_fp8_e32 v[124:125], v107
	v_cvt_pk_f32_fp8_sdwa v[126:127], v107 src0_sel:WORD_1
	v_readlane_b32 s2, v147, 6
	s_add_u32 s46, s40, s2
	s_addc_u32 s47, s41, 0
	global_load_dwordx4 v[104:107], v157, s[46:47]
	v_pk_mul_f32 v[138:139], v[112:113], v[32:33]
	v_pk_mul_f32 v[140:141], v[114:115], v[34:35]
	v_pk_fma_f32 v[138:139], v[116:117], v[36:37], v[138:139]
	v_pk_fma_f32 v[140:141], v[118:119], v[38:39], v[140:141]
	v_pk_fma_f32 v[138:139], v[120:121], v[40:41], v[138:139]
	v_pk_fma_f32 v[140:141], v[122:123], v[42:43], v[140:141]
	v_pk_fma_f32 v[138:139], v[124:125], v[44:45], v[138:139]
	v_pk_fma_f32 v[140:141], v[126:127], v[46:47], v[140:141]
	s_nop 0
	v_pk_add_f32 v[138:139], v[138:139], v[140:141]
	s_waitcnt vmcnt(15)
	v_add_f32_e32 v136, v138, v139
	v_cvt_pk_f32_fp8_e32 v[112:113], v108
	v_cvt_pk_f32_fp8_sdwa v[114:115], v108 src0_sel:WORD_1
	v_cvt_pk_f32_fp8_e32 v[116:117], v109
	v_cvt_pk_f32_fp8_sdwa v[118:119], v109 src0_sel:WORD_1
	v_cvt_pk_f32_fp8_e32 v[120:121], v110
	v_cvt_pk_f32_fp8_sdwa v[122:123], v110 src0_sel:WORD_1
	v_cvt_pk_f32_fp8_e32 v[124:125], v111
	v_cvt_pk_f32_fp8_sdwa v[126:127], v111 src0_sel:WORD_1
	v_readlane_b32 s2, v147, 7
	s_add_u32 s46, s40, s2
	s_addc_u32 s47, s41, 0
	global_load_dwordx4 v[108:111], v157, s[46:47]
	v_pk_mul_f32 v[138:139], v[112:113], v[32:33]
	v_pk_mul_f32 v[140:141], v[114:115], v[34:35]
	v_pk_fma_f32 v[138:139], v[116:117], v[36:37], v[138:139]
	v_pk_fma_f32 v[140:141], v[118:119], v[38:39], v[140:141]
	v_pk_fma_f32 v[138:139], v[120:121], v[40:41], v[138:139]
	v_pk_fma_f32 v[140:141], v[122:123], v[42:43], v[140:141]
	v_pk_fma_f32 v[138:139], v[124:125], v[44:45], v[138:139]
	v_pk_fma_f32 v[140:141], v[126:127], v[46:47], v[140:141]
	s_nop 0
	v_pk_add_f32 v[138:139], v[138:139], v[140:141]
	s_nop 0
	v_add_f32_e32 v137, v138, v139
.Lgx_p1end_13:
	s_nop 1
	v_permlane32_swap_b32_e32 v130, v134
	v_permlane32_swap_b32_e32 v131, v135
	v_permlane32_swap_b32_e32 v132, v136
	v_permlane32_swap_b32_e32 v133, v137
	v_add_f32_e32 v130, v130, v134
	v_add_f32_e32 v131, v131, v135
	v_add_f32_e32 v132, v132, v136
	v_add_f32_e32 v133, v133, v137
	s_nop 1
	v_permlane16_swap_b32_e32 v130, v132
	v_permlane16_swap_b32_e32 v131, v133
	v_add_f32_e32 v130, v130, v132
	v_add_f32_e32 v131, v131, v133
	s_nop 1
	v_add_f32_dpp v142, v130, v130 row_ror:8 row_mask:0xf bank_mask:0x3
	v_add_f32_dpp v142, v131, v131 row_ror:8 row_mask:0xf bank_mask:0xc
	s_nop 1
	v_add_f32_dpp v142, v142, v142 quad_perm:[1,0,3,2] row_mask:0xf bank_mask:0xf
	s_nop 1
	v_add_f32_dpp v142, v142, v142 quad_perm:[2,3,0,1] row_mask:0xf bank_mask:0xf
	s_nop 1
	v_add_f32_dpp v142, v142, v142 row_half_mirror row_mask:0xf bank_mask:0xf
	v_mul_f32_e32 v143, v150, v142
	v_mul_f32_e32 v144, 0x3d372713, v143
	v_mul_f32_e32 v144, v143, v144
	v_fma_f32 v144, v143, v144, v143
	v_mul_f32_e32 v144, 0x3f4c422a, v144
	v_mul_f32_e32 v144, -2.0, v144
	v_mul_f32_e32 v144, 0x3fb8aa3b, v144
	v_exp_f32_e32 v144, v144
	s_nop 0
	v_add_f32_e32 v144, 1.0, v144
	v_rcp_f32_e32 v144, v144
	s_nop 0
	v_mul_f32_e32 v143, v143, v144
	v_mul_f32_e32 v145, v151, v143
	ds_write_b32 v155, v145 offset:4736
	v_add_u32_e32 v155, 32, v155
	v_add_u32_e32 v154, 32, v154
	v_add_u32_e32 v156, 4, v156
	s_add_u32 s96, s96, 2
	s_cmp_lt_u32 s96, s28
	s_cbranch_scc1 .Lgx_p1loop_8
	s_waitcnt lgkmcnt(0)
	v_mov_b32_e32 v0, 0
	v_mov_b32_e32 v1, 0
	v_mov_b32_e32 v2, 0
	v_mov_b32_e32 v3, 0
	v_mov_b32_e32 v4, 0
	v_mov_b32_e32 v5, 0
	v_mov_b32_e32 v6, 0
	v_mov_b32_e32 v7, 0
	v_mov_b32_e32 v8, 0
	v_mov_b32_e32 v9, 0
	v_mov_b32_e32 v10, 0
	v_mov_b32_e32 v11, 0
	v_mov_b32_e32 v12, 0
	v_mov_b32_e32 v13, 0
	v_mov_b32_e32 v14, 0
	v_mov_b32_e32 v15, 0
	v_mov_b32_e32 v16, 0
	v_mov_b32_e32 v17, 0
	v_mov_b32_e32 v18, 0
	v_mov_b32_e32 v19, 0
	v_mov_b32_e32 v20, 0
	v_mov_b32_e32 v21, 0
	v_mov_b32_e32 v22, 0
	v_mov_b32_e32 v23, 0
	v_mov_b32_e32 v24, 0
	v_mov_b32_e32 v25, 0
	v_mov_b32_e32 v26, 0
	v_mov_b32_e32 v27, 0
	v_mov_b32_e32 v28, 0
	v_mov_b32_e32 v29, 0
	v_mov_b32_e32 v30, 0
	v_mov_b32_e32 v31, 0
	v_mov_b32_e32 v32, 0
	v_mov_b32_e32 v33, 0
	v_mov_b32_e32 v34, 0
	v_mov_b32_e32 v35, 0
	v_mov_b32_e32 v36, 0
	v_mov_b32_e32 v37, 0
	v_mov_b32_e32 v38, 0
	v_mov_b32_e32 v39, 0
	v_mov_b32_e32 v40, 0
	v_mov_b32_e32 v41, 0
	v_mov_b32_e32 v42, 0
	v_mov_b32_e32 v43, 0
	v_mov_b32_e32 v44, 0
	v_mov_b32_e32 v45, 0
	v_mov_b32_e32 v46, 0
	v_mov_b32_e32 v47, 0
	ds_read_b32 v138, v161 offset:0
	v_and_b32_e32 v154, 7, v168
	v_lshrrev_b32_e32 v155, 3, v168
	v_mov_b32_e32 v156, s17
	v_lshl_add_u32 v154, v154, 2, s17
	v_lshl_add_u32 v155, v155, 2, s17
	s_waitcnt lgkmcnt(0)
	v_readlane_b32 s2, v138, 0
	s_add_u32 s46, s42, s2
	s_addc_u32 s47, s43, 0
	global_load_dwordx4 v[48:51], v157, s[46:47]
	v_readlane_b32 s2, v138, 1
	s_add_u32 s46, s42, s2
	s_addc_u32 s47, s43, 0
	global_load_dwordx4 v[52:55], v157, s[46:47]
	v_readlane_b32 s2, v138, 2
	s_add_u32 s46, s42, s2
	s_addc_u32 s47, s43, 0
	global_load_dwordx4 v[56:59], v157, s[46:47]
	v_readlane_b32 s2, v138, 3
	s_add_u32 s46, s42, s2
	s_addc_u32 s47, s43, 0
	global_load_dwordx4 v[60:63], v157, s[46:47]
	v_readlane_b32 s2, v138, 4
	s_add_u32 s46, s42, s2
	s_addc_u32 s47, s43, 0
	global_load_dwordx4 v[64:67], v157, s[46:47]
	v_readlane_b32 s2, v138, 5
	s_add_u32 s46, s42, s2
	s_addc_u32 s47, s43, 0
	global_load_dwordx4 v[68:71], v157, s[46:47]
	v_readlane_b32 s2, v138, 6
	s_add_u32 s46, s42, s2
	s_addc_u32 s47, s43, 0
	global_load_dwordx4 v[72:75], v157, s[46:47]
	v_readlane_b32 s2, v138, 7
	s_add_u32 s46, s42, s2
	s_addc_u32 s47, s43, 0
	global_load_dwordx4 v[76:79], v157, s[46:47]
	v_readlane_b32 s2, v138, 8
	s_add_u32 s46, s42, s2
	s_addc_u32 s47, s43, 0
	global_load_dwordx4 v[80:83], v157, s[46:47]
	v_readlane_b32 s2, v138, 9
	s_add_u32 s46, s42, s2
	s_addc_u32 s47, s43, 0
	global_load_dwordx4 v[84:87], v157, s[46:47]
	v_readlane_b32 s2, v138, 10
	s_add_u32 s46, s42, s2
	s_addc_u32 s47, s43, 0
	global_load_dwordx4 v[88:91], v157, s[46:47]
	v_readlane_b32 s2, v138, 11
	s_add_u32 s46, s42, s2
	s_addc_u32 s47, s43, 0
	global_load_dwordx4 v[92:95], v157, s[46:47]
	v_readlane_b32 s2, v138, 12
	s_add_u32 s46, s42, s2
	s_addc_u32 s47, s43, 0
	global_load_dwordx4 v[96:99], v157, s[46:47]
	v_readlane_b32 s2, v138, 13
	s_add_u32 s46, s42, s2
	s_addc_u32 s47, s43, 0
	global_load_dwordx4 v[100:103], v157, s[46:47]
	v_readlane_b32 s2, v138, 14
	s_add_u32 s46, s42, s2
	s_addc_u32 s47, s43, 0
	global_load_dwordx4 v[104:107], v157, s[46:47]
	v_readlane_b32 s2, v138, 15
	s_add_u32 s46, s42, s2
	s_addc_u32 s47, s43, 0
	global_load_dwordx4 v[108:111], v157, s[46:47]
	ds_read_b32 v146, v154 offset:64
	ds_read_b32 v148, v154 offset:4736
	ds_read_b32 v152, v156 offset:7104
	s_mov_b32 s96, 0
.Lgx_p2loop_17:
	s_waitcnt lgkmcnt(0)
	v_readfirstlane_b32 s29, v152
	ds_read_b32 v147, v154 offset:96
	ds_read_b32 v150, v154 offset:4768
	ds_read_b32 v153, v156 offset:7108
	v_readlane_b32 s4, v148, 0
	v_readlane_b32 s6, v148, 1
	v_readlane_b32 s8, v148, 2
	v_readlane_b32 s10, v148, 3
	v_readlane_b32 s12, v148, 4
	v_readlane_b32 s14, v148, 5
	v_readlane_b32 s16, v148, 6
	v_readlane_b32 s18, v148, 7
	s_cmp_eq_u32 s29, 1
	s_cbranch_scc1 .Lgx_p2g1_20
	s_cmp_eq_u32 s29, 2
	s_cbranch_scc1 .Lgx_p2g2_21
	s_waitcnt vmcnt(15)
	v_cvt_pk_f32_fp8_e32 v[112:113], v48
	v_cvt_pk_f32_fp8_sdwa v[114:115], v48 src0_sel:WORD_1
	v_cvt_pk_f32_fp8_e32 v[116:117], v49
	v_cvt_pk_f32_fp8_sdwa v[118:119], v49 src0_sel:WORD_1
	v_cvt_pk_f32_fp8_e32 v[120:121], v50
	v_cvt_pk_f32_fp8_sdwa v[122:123], v50 src0_sel:WORD_1
	v_cvt_pk_f32_fp8_e32 v[124:125], v51
	v_cvt_pk_f32_fp8_sdwa v[126:127], v51 src0_sel:WORD_1
	v_readlane_b32 s2, v146, 0
	s_add_u32 s46, s42, s2
	s_addc_u32 s47, s43, 0
	global_load_dwordx4 v[48:51], v157, s[46:47]
	v_pk_fma_f32 v[0:1], v[112:113], s[4:5], v[0:1] op_sel_hi:[1,0,1]
	v_pk_fma_f32 v[2:3], v[114:115], s[4:5], v[2:3] op_sel_hi:[1,0,1]
	v_pk_fma_f32 v[4:5], v[116:117], s[4:5], v[4:5] op_sel_hi:[1,0,1]
	v_pk_fma_f32 v[6:7], v[118:119], s[4:5], v[6:7] op_sel_hi:[1,0,1]
	v_pk_fma_f32 v[8:9], v[120:121], s[4:5], v[8:9] op_sel_hi:[1,0,1]
	v_pk_fma_f32 v[10:11], v[122:123], s[4:5], v[10:11] op_sel_hi:[1,0,1]
	v_pk_fma_f32 v[12:13], v[124:125], s[4:5], v[12:13] op_sel_hi:[1,0,1]
	v_pk_fma_f32 v[14:15], v[126:127], s[4:5], v[14:15] op_sel_hi:[1,0,1]
	s_waitcnt vmcnt(15)
	v_cvt_pk_f32_fp8_e32 v[112:113], v52
	v_cvt_pk_f32_fp8_sdwa v[114:115], v52 src0_sel:WORD_1
	v_cvt_pk_f32_fp8_e32 v[116:117], v53
	v_cvt_pk_f32_fp8_sdwa v[118:119], v53 src0_sel:WORD_1
	v_cvt_pk_f32_fp8_e32 v[120:121], v54
	v_cvt_pk_f32_fp8_sdwa v[122:123], v54 src0_sel:WORD_1
	v_cvt_pk_f32_fp8_e32 v[124:125], v55
	v_cvt_pk_f32_fp8_sdwa v[126:127], v55 src0_sel:WORD_1
	v_readlane_b32 s2, v146, 1
	s_add_u32 s46, s42, s2
	s_addc_u32 s47, s43, 0
	global_load_dwordx4 v[52:55], v157, s[46:47]
	v_pk_fma_f32 v[0:1], v[112:113], s[6:7], v[0:1] op_sel_hi:[1,0,1]
	v_pk_fma_f32 v[2:3], v[114:115], s[6:7], v[2:3] op_sel_hi:[1,0,1]
	v_pk_fma_f32 v[4:5], v[116:117], s[6:7], v[4:5] op_sel_hi:[1,0,1]
	v_pk_fma_f32 v[6:7], v[118:119], s[6:7], v[6:7] op_sel_hi:[1,0,1]
	v_pk_fma_f32 v[8:9], v[120:121], s[6:7], v[8:9] op_sel_hi:[1,0,1]
	v_pk_fma_f32 v[10:11], v[122:123], s[6:7], v[10:11] op_sel_hi:[1,0,1]
	v_pk_fma_f32 v[12:13], v[124:125], s[6:7], v[12:13] op_sel_hi:[1,0,1]
	v_pk_fma_f32 v[14:15], v[126:127], s[6:7], v[14:15] op_sel_hi:[1,0,1]
	s_waitcnt vmcnt(15)
	v_cvt_pk_f32_fp8_e32 v[112:113], v56
	v_cvt_pk_f32_fp8_sdwa v[114:115], v56 src0_sel:WORD_1
	v_cvt_pk_f32_fp8_e32 v[116:117], v57
	v_cvt_pk_f32_fp8_sdwa v[118:119], v57 src0_sel:WORD_1
	v_cvt_pk_f32_fp8_e32 v[120:121], v58
	v_cvt_pk_f32_fp8_sdwa v[122:123], v58 src0_sel:WORD_1
	v_cvt_pk_f32_fp8_e32 v[124:125], v59
	v_cvt_pk_f32_fp8_sdwa v[126:127], v59 src0_sel:WORD_1
	v_readlane_b32 s2, v146, 2
	s_add_u32 s46, s42, s2
	s_addc_u32 s47, s43, 0
	global_load_dwordx4 v[56:59], v157, s[46:47]
	v_pk_fma_f32 v[0:1], v[112:113], s[8:9], v[0:1] op_sel_hi:[1,0,1]
	v_pk_fma_f32 v[2:3], v[114:115], s[8:9], v[2:3] op_sel_hi:[1,0,1]
	v_pk_fma_f32 v[4:5], v[116:117], s[8:9], v[4:5] op_sel_hi:[1,0,1]
	v_pk_fma_f32 v[6:7], v[118:119], s[8:9], v[6:7] op_sel_hi:[1,0,1]
	v_pk_fma_f32 v[8:9], v[120:121], s[8:9], v[8:9] op_sel_hi:[1,0,1]
	v_pk_fma_f32 v[10:11], v[122:123], s[8:9], v[10:11] op_sel_hi:[1,0,1]
	v_pk_fma_f32 v[12:13], v[124:125], s[8:9], v[12:13] op_sel_hi:[1,0,1]
	v_pk_fma_f32 v[14:15], v[126:127], s[8:9], v[14:15] op_sel_hi:[1,0,1]
	s_waitcnt vmcnt(15)
	v_cvt_pk_f32_fp8_e32 v[112:113], v60
	v_cvt_pk_f32_fp8_sdwa v[114:115], v60 src0_sel:WORD_1
	v_cvt_pk_f32_fp8_e32 v[116:117], v61
	v_cvt_pk_f32_fp8_sdwa v[118:119], v61 src0_sel:WORD_1
	v_cvt_pk_f32_fp8_e32 v[120:121], v62
	v_cvt_pk_f32_fp8_sdwa v[122:123], v62 src0_sel:WORD_1
	v_cvt_pk_f32_fp8_e32 v[124:125], v63
	v_cvt_pk_f32_fp8_sdwa v[126:127], v63 src0_sel:WORD_1
	v_readlane_b32 s2, v146, 3
	s_add_u32 s46, s42, s2
	s_addc_u32 s47, s43, 0
	global_load_dwordx4 v[60:63], v157, s[46:47]
	v_pk_fma_f32 v[0:1], v[112:113], s[10:11], v[0:1] op_sel_hi:[1,0,1]
	v_pk_fma_f32 v[2:3], v[114:115], s[10:11], v[2:3] op_sel_hi:[1,0,1]
	v_pk_fma_f32 v[4:5], v[116:117], s[10:11], v[4:5] op_sel_hi:[1,0,1]
	v_pk_fma_f32 v[6:7], v[118:119], s[10:11], v[6:7] op_sel_hi:[1,0,1]
	v_pk_fma_f32 v[8:9], v[120:121], s[10:11], v[8:9] op_sel_hi:[1,0,1]
	v_pk_fma_f32 v[10:11], v[122:123], s[10:11], v[10:11] op_sel_hi:[1,0,1]
	v_pk_fma_f32 v[12:13], v[124:125], s[10:11], v[12:13] op_sel_hi:[1,0,1]
	v_pk_fma_f32 v[14:15], v[126:127], s[10:11], v[14:15] op_sel_hi:[1,0,1]
	s_waitcnt vmcnt(15)
	v_cvt_pk_f32_fp8_e32 v[112:113], v64
	v_cvt_pk_f32_fp8_sdwa v[114:115], v64 src0_sel:WORD_1
	v_cvt_pk_f32_fp8_e32 v[116:117], v65
	v_cvt_pk_f32_fp8_sdwa v[118:119], v65 src0_sel:WORD_1
	v_cvt_pk_f32_fp8_e32 v[120:121], v66
	v_cvt_pk_f32_fp8_sdwa v[122:123], v66 src0_sel:WORD_1
	v_cvt_pk_f32_fp8_e32 v[124:125], v67
	v_cvt_pk_f32_fp8_sdwa v[126:127], v67 src0_sel:WORD_1
	v_readlane_b32 s2, v146, 4
	s_add_u32 s46, s42, s2
	s_addc_u32 s47, s43, 0
	global_load_dwordx4 v[64:67], v157, s[46:47]
	v_pk_fma_f32 v[0:1], v[112:113], s[12:13], v[0:1] op_sel_hi:[1,0,1]
	v_pk_fma_f32 v[2:3], v[114:115], s[12:13], v[2:3] op_sel_hi:[1,0,1]
	v_pk_fma_f32 v[4:5], v[116:117], s[12:13], v[4:5] op_sel_hi:[1,0,1]
	v_pk_fma_f32 v[6:7], v[118:119], s[12:13], v[6:7] op_sel_hi:[1,0,1]
	v_pk_fma_f32 v[8:9], v[120:121], s[12:13], v[8:9] op_sel_hi:[1,0,1]
	v_pk_fma_f32 v[10:11], v[122:123], s[12:13], v[10:11] op_sel_hi:[1,0,1]
	v_pk_fma_f32 v[12:13], v[124:125], s[12:13], v[12:13] op_sel_hi:[1,0,1]
	v_pk_fma_f32 v[14:15], v[126:127], s[12:13], v[14:15] op_sel_hi:[1,0,1]
	s_waitcnt vmcnt(15)
	v_cvt_pk_f32_fp8_e32 v[112:113], v68
	v_cvt_pk_f32_fp8_sdwa v[114:115], v68 src0_sel:WORD_1
	v_cvt_pk_f32_fp8_e32 v[116:117], v69
	v_cvt_pk_f32_fp8_sdwa v[118:119], v69 src0_sel:WORD_1
	v_cvt_pk_f32_fp8_e32 v[120:121], v70
	v_cvt_pk_f32_fp8_sdwa v[122:123], v70 src0_sel:WORD_1
	v_cvt_pk_f32_fp8_e32 v[124:125], v71
	v_cvt_pk_f32_fp8_sdwa v[126:127], v71 src0_sel:WORD_1
	v_readlane_b32 s2, v146, 5
	s_add_u32 s46, s42, s2
	s_addc_u32 s47, s43, 0
	global_load_dwordx4 v[68:71], v157, s[46:47]
	v_pk_fma_f32 v[0:1], v[112:113], s[14:15], v[0:1] op_sel_hi:[1,0,1]
	v_pk_fma_f32 v[2:3], v[114:115], s[14:15], v[2:3] op_sel_hi:[1,0,1]
	v_pk_fma_f32 v[4:5], v[116:117], s[14:15], v[4:5] op_sel_hi:[1,0,1]
	v_pk_fma_f32 v[6:7], v[118:119], s[14:15], v[6:7] op_sel_hi:[1,0,1]
	v_pk_fma_f32 v[8:9], v[120:121], s[14:15], v[8:9] op_sel_hi:[1,0,1]
	v_pk_fma_f32 v[10:11], v[122:123], s[14:15], v[10:11] op_sel_hi:[1,0,1]
	v_pk_fma_f32 v[12:13], v[124:125], s[14:15], v[12:13] op_sel_hi:[1,0,1]
	v_pk_fma_f32 v[14:15], v[126:127], s[14:15], v[14:15] op_sel_hi:[1,0,1]
	s_waitcnt vmcnt(15)
	v_cvt_pk_f32_fp8_e32 v[112:113], v72
	v_cvt_pk_f32_fp8_sdwa v[114:115], v72 src0_sel:WORD_1
	v_cvt_pk_f32_fp8_e32 v[116:117], v73
	v_cvt_pk_f32_fp8_sdwa v[118:119], v73 src0_sel:WORD_1
	v_cvt_pk_f32_fp8_e32 v[120:121], v74
	v_cvt_pk_f32_fp8_sdwa v[122:123], v74 src0_sel:WORD_1
	v_cvt_pk_f32_fp8_e32 v[124:125], v75
	v_cvt_pk_f32_fp8_sdwa v[126:127], v75 src0_sel:WORD_1
	v_readlane_b32 s2, v146, 6
	s_add_u32 s46, s42, s2
	s_addc_u32 s47, s43, 0
	global_load_dwordx4 v[72:75], v157, s[46:47]
	v_pk_fma_f32 v[0:1], v[112:113], s[16:17], v[0:1] op_sel_hi:[1,0,1]
	v_pk_fma_f32 v[2:3], v[114:115], s[16:17], v[2:3] op_sel_hi:[1,0,1]
	v_pk_fma_f32 v[4:5], v[116:117], s[16:17], v[4:5] op_sel_hi:[1,0,1]
	v_pk_fma_f32 v[6:7], v[118:119], s[16:17], v[6:7] op_sel_hi:[1,0,1]
	v_pk_fma_f32 v[8:9], v[120:121], s[16:17], v[8:9] op_sel_hi:[1,0,1]
	v_pk_fma_f32 v[10:11], v[122:123], s[16:17], v[10:11] op_sel_hi:[1,0,1]
	v_pk_fma_f32 v[12:13], v[124:125], s[16:17], v[12:13] op_sel_hi:[1,0,1]
	v_pk_fma_f32 v[14:15], v[126:127], s[16:17], v[14:15] op_sel_hi:[1,0,1]
	s_waitcnt vmcnt(15)
	v_cvt_pk_f32_fp8_e32 v[112:113], v76
	v_cvt_pk_f32_fp8_sdwa v[114:115], v76 src0_sel:WORD_1
	v_cvt_pk_f32_fp8_e32 v[116:117], v77
	v_cvt_pk_f32_fp8_sdwa v[118:119], v77 src0_sel:WORD_1
	v_cvt_pk_f32_fp8_e32 v[120:121], v78
	v_cvt_pk_f32_fp8_sdwa v[122:123], v78 src0_sel:WORD_1
	v_cvt_pk_f32_fp8_e32 v[124:125], v79
	v_cvt_pk_f32_fp8_sdwa v[126:127], v79 src0_sel:WORD_1
	v_readlane_b32 s2, v146, 7
	s_add_u32 s46, s42, s2
	s_addc_u32 s47, s43, 0
	global_load_dwordx4 v[76:79], v157, s[46:47]
	v_pk_fma_f32 v[0:1], v[112:113], s[18:19], v[0:1] op_sel_hi:[1,0,1]
	v_pk_fma_f32 v[2:3], v[114:115], s[18:19], v[2:3] op_sel_hi:[1,0,1]
	v_pk_fma_f32 v[4:5], v[116:117], s[18:19], v[4:5] op_sel_hi:[1,0,1]
	v_pk_fma_f32 v[6:7], v[118:119], s[18:19], v[6:7] op_sel_hi:[1,0,1]
	v_pk_fma_f32 v[8:9], v[120:121], s[18:19], v[8:9] op_sel_hi:[1,0,1]
	v_pk_fma_f32 v[10:11], v[122:123], s[18:19], v[10:11] op_sel_hi:[1,0,1]
	v_pk_fma_f32 v[12:13], v[124:125], s[18:19], v[12:13] op_sel_hi:[1,0,1]
	v_pk_fma_f32 v[14:15], v[126:127], s[18:19], v[14:15] op_sel_hi:[1,0,1]
	s_branch .Lgx_p2end_18
.Lgx_p2g1_20:
	s_waitcnt vmcnt(15)
	v_cvt_pk_f32_fp8_e32 v[112:113], v48
	v_cvt_pk_f32_fp8_sdwa v[114:115], v48 src0_sel:WORD_1
	v_cvt_pk_f32_fp8_e32 v[116:117], v49
	v_cvt_pk_f32_fp8_sdwa v[118:119], v49 src0_sel:WORD_1
	v_cvt_pk_f32_fp8_e32 v[120:121], v50
	v_cvt_pk_f32_fp8_sdwa v[122:123], v50 src0_sel:WORD_1
	v_cvt_pk_f32_fp8_e32 v[124:125], v51
	v_cvt_pk_f32_fp8_sdwa v[126:127], v51 src0_sel:WORD_1
	v_readlane_b32 s2, v146, 0
	s_add_u32 s46, s42, s2
	s_addc_u32 s47, s43, 0
	global_load_dwordx4 v[48:51], v157, s[46:47]
	v_pk_fma_f32 v[16:17], v[112:113], s[4:5], v[16:17] op_sel_hi:[1,0,1]
	v_pk_fma_f32 v[18:19], v[114:115], s[4:5], v[18:19] op_sel_hi:[1,0,1]
	v_pk_fma_f32 v[20:21], v[116:117], s[4:5], v[20:21] op_sel_hi:[1,0,1]
	v_pk_fma_f32 v[22:23], v[118:119], s[4:5], v[22:23] op_sel_hi:[1,0,1]
	v_pk_fma_f32 v[24:25], v[120:121], s[4:5], v[24:25] op_sel_hi:[1,0,1]
	v_pk_fma_f32 v[26:27], v[122:123], s[4:5], v[26:27] op_sel_hi:[1,0,1]
	v_pk_fma_f32 v[28:29], v[124:125], s[4:5], v[28:29] op_sel_hi:[1,0,1]
	v_pk_fma_f32 v[30:31], v[126:127], s[4:5], v[30:31] op_sel_hi:[1,0,1]
	s_waitcnt vmcnt(15)
	v_cvt_pk_f32_fp8_e32 v[112:113], v52
	v_cvt_pk_f32_fp8_sdwa v[114:115], v52 src0_sel:WORD_1
	v_cvt_pk_f32_fp8_e32 v[116:117], v53
	v_cvt_pk_f32_fp8_sdwa v[118:119], v53 src0_sel:WORD_1
	v_cvt_pk_f32_fp8_e32 v[120:121], v54
	v_cvt_pk_f32_fp8_sdwa v[122:123], v54 src0_sel:WORD_1
	v_cvt_pk_f32_fp8_e32 v[124:125], v55
	v_cvt_pk_f32_fp8_sdwa v[126:127], v55 src0_sel:WORD_1
	v_readlane_b32 s2, v146, 1
	s_add_u32 s46, s42, s2
	s_addc_u32 s47, s43, 0
	global_load_dwordx4 v[52:55], v157, s[46:47]
	v_pk_fma_f32 v[16:17], v[112:113], s[6:7], v[16:17] op_sel_hi:[1,0,1]
	v_pk_fma_f32 v[18:19], v[114:115], s[6:7], v[18:19] op_sel_hi:[1,0,1]
	v_pk_fma_f32 v[20:21], v[116:117], s[6:7], v[20:21] op_sel_hi:[1,0,1]
	v_pk_fma_f32 v[22:23], v[118:119], s[6:7], v[22:23] op_sel_hi:[1,0,1]
	v_pk_fma_f32 v[24:25], v[120:121], s[6:7], v[24:25] op_sel_hi:[1,0,1]
	v_pk_fma_f32 v[26:27], v[122:123], s[6:7], v[26:27] op_sel_hi:[1,0,1]
	v_pk_fma_f32 v[28:29], v[124:125], s[6:7], v[28:29] op_sel_hi:[1,0,1]
	v_pk_fma_f32 v[30:31], v[126:127], s[6:7], v[30:31] op_sel_hi:[1,0,1]
	s_waitcnt vmcnt(15)
	v_cvt_pk_f32_fp8_e32 v[112:113], v56
	v_cvt_pk_f32_fp8_sdwa v[114:115], v56 src0_sel:WORD_1
	v_cvt_pk_f32_fp8_e32 v[116:117], v57
	v_cvt_pk_f32_fp8_sdwa v[118:119], v57 src0_sel:WORD_1
	v_cvt_pk_f32_fp8_e32 v[120:121], v58
	v_cvt_pk_f32_fp8_sdwa v[122:123], v58 src0_sel:WORD_1
	v_cvt_pk_f32_fp8_e32 v[124:125], v59
	v_cvt_pk_f32_fp8_sdwa v[126:127], v59 src0_sel:WORD_1
	v_readlane_b32 s2, v146, 2
	s_add_u32 s46, s42, s2
	s_addc_u32 s47, s43, 0
	global_load_dwordx4 v[56:59], v157, s[46:47]
	v_pk_fma_f32 v[16:17], v[112:113], s[8:9], v[16:17] op_sel_hi:[1,0,1]
	v_pk_fma_f32 v[18:19], v[114:115], s[8:9], v[18:19] op_sel_hi:[1,0,1]
	v_pk_fma_f32 v[20:21], v[116:117], s[8:9], v[20:21] op_sel_hi:[1,0,1]
	v_pk_fma_f32 v[22:23], v[118:119], s[8:9], v[22:23] op_sel_hi:[1,0,1]
	v_pk_fma_f32 v[24:25], v[120:121], s[8:9], v[24:25] op_sel_hi:[1,0,1]
	v_pk_fma_f32 v[26:27], v[122:123], s[8:9], v[26:27] op_sel_hi:[1,0,1]
	v_pk_fma_f32 v[28:29], v[124:125], s[8:9], v[28:29] op_sel_hi:[1,0,1]
	v_pk_fma_f32 v[30:31], v[126:127], s[8:9], v[30:31] op_sel_hi:[1,0,1]
	s_waitcnt vmcnt(15)
	v_cvt_pk_f32_fp8_e32 v[112:113], v60
	v_cvt_pk_f32_fp8_sdwa v[114:115], v60 src0_sel:WORD_1
	v_cvt_pk_f32_fp8_e32 v[116:117], v61
	v_cvt_pk_f32_fp8_sdwa v[118:119], v61 src0_sel:WORD_1
	v_cvt_pk_f32_fp8_e32 v[120:121], v62
	v_cvt_pk_f32_fp8_sdwa v[122:123], v62 src0_sel:WORD_1
	v_cvt_pk_f32_fp8_e32 v[124:125], v63
	v_cvt_pk_f32_fp8_sdwa v[126:127], v63 src0_sel:WORD_1
	v_readlane_b32 s2, v146, 3
	s_add_u32 s46, s42, s2
	s_addc_u32 s47, s43, 0
	global_load_dwordx4 v[60:63], v157, s[46:47]
	v_pk_fma_f32 v[16:17], v[112:113], s[10:11], v[16:17] op_sel_hi:[1,0,1]
	v_pk_fma_f32 v[18:19], v[114:115], s[10:11], v[18:19] op_sel_hi:[1,0,1]
	v_pk_fma_f32 v[20:21], v[116:117], s[10:11], v[20:21] op_sel_hi:[1,0,1]
	v_pk_fma_f32 v[22:23], v[118:119], s[10:11], v[22:23] op_sel_hi:[1,0,1]
	v_pk_fma_f32 v[24:25], v[120:121], s[10:11], v[24:25] op_sel_hi:[1,0,1]
	v_pk_fma_f32 v[26:27], v[122:123], s[10:11], v[26:27] op_sel_hi:[1,0,1]
	v_pk_fma_f32 v[28:29], v[124:125], s[10:11], v[28:29] op_sel_hi:[1,0,1]
	v_pk_fma_f32 v[30:31], v[126:127], s[10:11], v[30:31] op_sel_hi:[1,0,1]
	s_waitcnt vmcnt(15)
	v_cvt_pk_f32_fp8_e32 v[112:113], v64
	v_cvt_pk_f32_fp8_sdwa v[114:115], v64 src0_sel:WORD_1
	v_cvt_pk_f32_fp8_e32 v[116:117], v65
	v_cvt_pk_f32_fp8_sdwa v[118:119], v65 src0_sel:WORD_1
	v_cvt_pk_f32_fp8_e32 v[120:121], v66
	v_cvt_pk_f32_fp8_sdwa v[122:123], v66 src0_sel:WORD_1
	v_cvt_pk_f32_fp8_e32 v[124:125], v67
	v_cvt_pk_f32_fp8_sdwa v[126:127], v67 src0_sel:WORD_1
	v_readlane_b32 s2, v146, 4
	s_add_u32 s46, s42, s2
	s_addc_u32 s47, s43, 0
	global_load_dwordx4 v[64:67], v157, s[46:47]
	v_pk_fma_f32 v[16:17], v[112:113], s[12:13], v[16:17] op_sel_hi:[1,0,1]
	v_pk_fma_f32 v[18:19], v[114:115], s[12:13], v[18:19] op_sel_hi:[1,0,1]
	v_pk_fma_f32 v[20:21], v[116:117], s[12:13], v[20:21] op_sel_hi:[1,0,1]
	v_pk_fma_f32 v[22:23], v[118:119], s[12:13], v[22:23] op_sel_hi:[1,0,1]
	v_pk_fma_f32 v[24:25], v[120:121], s[12:13], v[24:25] op_sel_hi:[1,0,1]
	v_pk_fma_f32 v[26:27], v[122:123], s[12:13], v[26:27] op_sel_hi:[1,0,1]
	v_pk_fma_f32 v[28:29], v[124:125], s[12:13], v[28:29] op_sel_hi:[1,0,1]
	v_pk_fma_f32 v[30:31], v[126:127], s[12:13], v[30:31] op_sel_hi:[1,0,1]
	s_waitcnt vmcnt(15)
	v_cvt_pk_f32_fp8_e32 v[112:113], v68
	v_cvt_pk_f32_fp8_sdwa v[114:115], v68 src0_sel:WORD_1
	v_cvt_pk_f32_fp8_e32 v[116:117], v69
	v_cvt_pk_f32_fp8_sdwa v[118:119], v69 src0_sel:WORD_1
	v_cvt_pk_f32_fp8_e32 v[120:121], v70
	v_cvt_pk_f32_fp8_sdwa v[122:123], v70 src0_sel:WORD_1
	v_cvt_pk_f32_fp8_e32 v[124:125], v71
	v_cvt_pk_f32_fp8_sdwa v[126:127], v71 src0_sel:WORD_1
	v_readlane_b32 s2, v146, 5
	s_add_u32 s46, s42, s2
	s_addc_u32 s47, s43, 0
	global_load_dwordx4 v[68:71], v157, s[46:47]
	v_pk_fma_f32 v[16:17], v[112:113], s[14:15], v[16:17] op_sel_hi:[1,0,1]
	v_pk_fma_f32 v[18:19], v[114:115], s[14:15], v[18:19] op_sel_hi:[1,0,1]
	v_pk_fma_f32 v[20:21], v[116:117], s[14:15], v[20:21] op_sel_hi:[1,0,1]
	v_pk_fma_f32 v[22:23], v[118:119], s[14:15], v[22:23] op_sel_hi:[1,0,1]
	v_pk_fma_f32 v[24:25], v[120:121], s[14:15], v[24:25] op_sel_hi:[1,0,1]
	v_pk_fma_f32 v[26:27], v[122:123], s[14:15], v[26:27] op_sel_hi:[1,0,1]
	v_pk_fma_f32 v[28:29], v[124:125], s[14:15], v[28:29] op_sel_hi:[1,0,1]
	v_pk_fma_f32 v[30:31], v[126:127], s[14:15], v[30:31] op_sel_hi:[1,0,1]
	s_waitcnt vmcnt(15)
	v_cvt_pk_f32_fp8_e32 v[112:113], v72
	v_cvt_pk_f32_fp8_sdwa v[114:115], v72 src0_sel:WORD_1
	v_cvt_pk_f32_fp8_e32 v[116:117], v73
	v_cvt_pk_f32_fp8_sdwa v[118:119], v73 src0_sel:WORD_1
	v_cvt_pk_f32_fp8_e32 v[120:121], v74
	v_cvt_pk_f32_fp8_sdwa v[122:123], v74 src0_sel:WORD_1
	v_cvt_pk_f32_fp8_e32 v[124:125], v75
	v_cvt_pk_f32_fp8_sdwa v[126:127], v75 src0_sel:WORD_1
	v_readlane_b32 s2, v146, 6
	s_add_u32 s46, s42, s2
	s_addc_u32 s47, s43, 0
	global_load_dwordx4 v[72:75], v157, s[46:47]
	v_pk_fma_f32 v[16:17], v[112:113], s[16:17], v[16:17] op_sel_hi:[1,0,1]
	v_pk_fma_f32 v[18:19], v[114:115], s[16:17], v[18:19] op_sel_hi:[1,0,1]
	v_pk_fma_f32 v[20:21], v[116:117], s[16:17], v[20:21] op_sel_hi:[1,0,1]
	v_pk_fma_f32 v[22:23], v[118:119], s[16:17], v[22:23] op_sel_hi:[1,0,1]
	v_pk_fma_f32 v[24:25], v[120:121], s[16:17], v[24:25] op_sel_hi:[1,0,1]
	v_pk_fma_f32 v[26:27], v[122:123], s[16:17], v[26:27] op_sel_hi:[1,0,1]
	v_pk_fma_f32 v[28:29], v[124:125], s[16:17], v[28:29] op_sel_hi:[1,0,1]
	v_pk_fma_f32 v[30:31], v[126:127], s[16:17], v[30:31] op_sel_hi:[1,0,1]
	s_waitcnt vmcnt(15)
	v_cvt_pk_f32_fp8_e32 v[112:113], v76
	v_cvt_pk_f32_fp8_sdwa v[114:115], v76 src0_sel:WORD_1
	v_cvt_pk_f32_fp8_e32 v[116:117], v77
	v_cvt_pk_f32_fp8_sdwa v[118:119], v77 src0_sel:WORD_1
	v_cvt_pk_f32_fp8_e32 v[120:121], v78
	v_cvt_pk_f32_fp8_sdwa v[122:123], v78 src0_sel:WORD_1
	v_cvt_pk_f32_fp8_e32 v[124:125], v79
	v_cvt_pk_f32_fp8_sdwa v[126:127], v79 src0_sel:WORD_1
	v_readlane_b32 s2, v146, 7
	s_add_u32 s46, s42, s2
	s_addc_u32 s47, s43, 0
	global_load_dwordx4 v[76:79], v157, s[46:47]
	v_pk_fma_f32 v[16:17], v[112:113], s[18:19], v[16:17] op_sel_hi:[1,0,1]
	v_pk_fma_f32 v[18:19], v[114:115], s[18:19], v[18:19] op_sel_hi:[1,0,1]
	v_pk_fma_f32 v[20:21], v[116:117], s[18:19], v[20:21] op_sel_hi:[1,0,1]
	v_pk_fma_f32 v[22:23], v[118:119], s[18:19], v[22:23] op_sel_hi:[1,0,1]
	v_pk_fma_f32 v[24:25], v[120:121], s[18:19], v[24:25] op_sel_hi:[1,0,1]
	v_pk_fma_f32 v[26:27], v[122:123], s[18:19], v[26:27] op_sel_hi:[1,0,1]
	v_pk_fma_f32 v[28:29], v[124:125], s[18:19], v[28:29] op_sel_hi:[1,0,1]
	v_pk_fma_f32 v[30:31], v[126:127], s[18:19], v[30:31] op_sel_hi:[1,0,1]
	s_branch .Lgx_p2end_18
.Lgx_p2g2_21:
	s_waitcnt vmcnt(15)
	v_cvt_pk_f32_fp8_e32 v[112:113], v48
	v_cvt_pk_f32_fp8_sdwa v[114:115], v48 src0_sel:WORD_1
	v_cvt_pk_f32_fp8_e32 v[116:117], v49
	v_cvt_pk_f32_fp8_sdwa v[118:119], v49 src0_sel:WORD_1
	v_cvt_pk_f32_fp8_e32 v[120:121], v50
	v_cvt_pk_f32_fp8_sdwa v[122:123], v50 src0_sel:WORD_1
	v_cvt_pk_f32_fp8_e32 v[124:125], v51
	v_cvt_pk_f32_fp8_sdwa v[126:127], v51 src0_sel:WORD_1
	v_readlane_b32 s2, v146, 0
	s_add_u32 s46, s42, s2
	s_addc_u32 s47, s43, 0
	global_load_dwordx4 v[48:51], v157, s[46:47]
	v_pk_fma_f32 v[32:33], v[112:113], s[4:5], v[32:33] op_sel_hi:[1,0,1]
	v_pk_fma_f32 v[34:35], v[114:115], s[4:5], v[34:35] op_sel_hi:[1,0,1]
	v_pk_fma_f32 v[36:37], v[116:117], s[4:5], v[36:37] op_sel_hi:[1,0,1]
	v_pk_fma_f32 v[38:39], v[118:119], s[4:5], v[38:39] op_sel_hi:[1,0,1]
	v_pk_fma_f32 v[40:41], v[120:121], s[4:5], v[40:41] op_sel_hi:[1,0,1]
	v_pk_fma_f32 v[42:43], v[122:123], s[4:5], v[42:43] op_sel_hi:[1,0,1]
	v_pk_fma_f32 v[44:45], v[124:125], s[4:5], v[44:45] op_sel_hi:[1,0,1]
	v_pk_fma_f32 v[46:47], v[126:127], s[4:5], v[46:47] op_sel_hi:[1,0,1]
	s_waitcnt vmcnt(15)
	v_cvt_pk_f32_fp8_e32 v[112:113], v52
	v_cvt_pk_f32_fp8_sdwa v[114:115], v52 src0_sel:WORD_1
	v_cvt_pk_f32_fp8_e32 v[116:117], v53
	v_cvt_pk_f32_fp8_sdwa v[118:119], v53 src0_sel:WORD_1
	v_cvt_pk_f32_fp8_e32 v[120:121], v54
	v_cvt_pk_f32_fp8_sdwa v[122:123], v54 src0_sel:WORD_1
	v_cvt_pk_f32_fp8_e32 v[124:125], v55
	v_cvt_pk_f32_fp8_sdwa v[126:127], v55 src0_sel:WORD_1
	v_readlane_b32 s2, v146, 1
	s_add_u32 s46, s42, s2
	s_addc_u32 s47, s43, 0
	global_load_dwordx4 v[52:55], v157, s[46:47]
	v_pk_fma_f32 v[32:33], v[112:113], s[6:7], v[32:33] op_sel_hi:[1,0,1]
	v_pk_fma_f32 v[34:35], v[114:115], s[6:7], v[34:35] op_sel_hi:[1,0,1]
	v_pk_fma_f32 v[36:37], v[116:117], s[6:7], v[36:37] op_sel_hi:[1,0,1]
	v_pk_fma_f32 v[38:39], v[118:119], s[6:7], v[38:39] op_sel_hi:[1,0,1]
	v_pk_fma_f32 v[40:41], v[120:121], s[6:7], v[40:41] op_sel_hi:[1,0,1]
	v_pk_fma_f32 v[42:43], v[122:123], s[6:7], v[42:43] op_sel_hi:[1,0,1]
	v_pk_fma_f32 v[44:45], v[124:125], s[6:7], v[44:45] op_sel_hi:[1,0,1]
	v_pk_fma_f32 v[46:47], v[126:127], s[6:7], v[46:47] op_sel_hi:[1,0,1]
	s_waitcnt vmcnt(15)
	v_cvt_pk_f32_fp8_e32 v[112:113], v56
	v_cvt_pk_f32_fp8_sdwa v[114:115], v56 src0_sel:WORD_1
	v_cvt_pk_f32_fp8_e32 v[116:117], v57
	v_cvt_pk_f32_fp8_sdwa v[118:119], v57 src0_sel:WORD_1
	v_cvt_pk_f32_fp8_e32 v[120:121], v58
	v_cvt_pk_f32_fp8_sdwa v[122:123], v58 src0_sel:WORD_1
	v_cvt_pk_f32_fp8_e32 v[124:125], v59
	v_cvt_pk_f32_fp8_sdwa v[126:127], v59 src0_sel:WORD_1
	v_readlane_b32 s2, v146, 2
	s_add_u32 s46, s42, s2
	s_addc_u32 s47, s43, 0
	global_load_dwordx4 v[56:59], v157, s[46:47]
	v_pk_fma_f32 v[32:33], v[112:113], s[8:9], v[32:33] op_sel_hi:[1,0,1]
	v_pk_fma_f32 v[34:35], v[114:115], s[8:9], v[34:35] op_sel_hi:[1,0,1]
	v_pk_fma_f32 v[36:37], v[116:117], s[8:9], v[36:37] op_sel_hi:[1,0,1]
	v_pk_fma_f32 v[38:39], v[118:119], s[8:9], v[38:39] op_sel_hi:[1,0,1]
	v_pk_fma_f32 v[40:41], v[120:121], s[8:9], v[40:41] op_sel_hi:[1,0,1]
	v_pk_fma_f32 v[42:43], v[122:123], s[8:9], v[42:43] op_sel_hi:[1,0,1]
	v_pk_fma_f32 v[44:45], v[124:125], s[8:9], v[44:45] op_sel_hi:[1,0,1]
	v_pk_fma_f32 v[46:47], v[126:127], s[8:9], v[46:47] op_sel_hi:[1,0,1]
	s_waitcnt vmcnt(15)
	v_cvt_pk_f32_fp8_e32 v[112:113], v60
	v_cvt_pk_f32_fp8_sdwa v[114:115], v60 src0_sel:WORD_1
	v_cvt_pk_f32_fp8_e32 v[116:117], v61
	v_cvt_pk_f32_fp8_sdwa v[118:119], v61 src0_sel:WORD_1
	v_cvt_pk_f32_fp8_e32 v[120:121], v62
	v_cvt_pk_f32_fp8_sdwa v[122:123], v62 src0_sel:WORD_1
	v_cvt_pk_f32_fp8_e32 v[124:125], v63
	v_cvt_pk_f32_fp8_sdwa v[126:127], v63 src0_sel:WORD_1
	v_readlane_b32 s2, v146, 3
	s_add_u32 s46, s42, s2
	s_addc_u32 s47, s43, 0
	global_load_dwordx4 v[60:63], v157, s[46:47]
	v_pk_fma_f32 v[32:33], v[112:113], s[10:11], v[32:33] op_sel_hi:[1,0,1]
	v_pk_fma_f32 v[34:35], v[114:115], s[10:11], v[34:35] op_sel_hi:[1,0,1]
	v_pk_fma_f32 v[36:37], v[116:117], s[10:11], v[36:37] op_sel_hi:[1,0,1]
	v_pk_fma_f32 v[38:39], v[118:119], s[10:11], v[38:39] op_sel_hi:[1,0,1]
	v_pk_fma_f32 v[40:41], v[120:121], s[10:11], v[40:41] op_sel_hi:[1,0,1]
	v_pk_fma_f32 v[42:43], v[122:123], s[10:11], v[42:43] op_sel_hi:[1,0,1]
	v_pk_fma_f32 v[44:45], v[124:125], s[10:11], v[44:45] op_sel_hi:[1,0,1]
	v_pk_fma_f32 v[46:47], v[126:127], s[10:11], v[46:47] op_sel_hi:[1,0,1]
	s_waitcnt vmcnt(15)
	v_cvt_pk_f32_fp8_e32 v[112:113], v64
	v_cvt_pk_f32_fp8_sdwa v[114:115], v64 src0_sel:WORD_1
	v_cvt_pk_f32_fp8_e32 v[116:117], v65
	v_cvt_pk_f32_fp8_sdwa v[118:119], v65 src0_sel:WORD_1
	v_cvt_pk_f32_fp8_e32 v[120:121], v66
	v_cvt_pk_f32_fp8_sdwa v[122:123], v66 src0_sel:WORD_1
	v_cvt_pk_f32_fp8_e32 v[124:125], v67
	v_cvt_pk_f32_fp8_sdwa v[126:127], v67 src0_sel:WORD_1
	v_readlane_b32 s2, v146, 4
	s_add_u32 s46, s42, s2
	s_addc_u32 s47, s43, 0
	global_load_dwordx4 v[64:67], v157, s[46:47]
	v_pk_fma_f32 v[32:33], v[112:113], s[12:13], v[32:33] op_sel_hi:[1,0,1]
	v_pk_fma_f32 v[34:35], v[114:115], s[12:13], v[34:35] op_sel_hi:[1,0,1]
	v_pk_fma_f32 v[36:37], v[116:117], s[12:13], v[36:37] op_sel_hi:[1,0,1]
	v_pk_fma_f32 v[38:39], v[118:119], s[12:13], v[38:39] op_sel_hi:[1,0,1]
	v_pk_fma_f32 v[40:41], v[120:121], s[12:13], v[40:41] op_sel_hi:[1,0,1]
	v_pk_fma_f32 v[42:43], v[122:123], s[12:13], v[42:43] op_sel_hi:[1,0,1]
	v_pk_fma_f32 v[44:45], v[124:125], s[12:13], v[44:45] op_sel_hi:[1,0,1]
	v_pk_fma_f32 v[46:47], v[126:127], s[12:13], v[46:47] op_sel_hi:[1,0,1]
	s_waitcnt vmcnt(15)
	v_cvt_pk_f32_fp8_e32 v[112:113], v68
	v_cvt_pk_f32_fp8_sdwa v[114:115], v68 src0_sel:WORD_1
	v_cvt_pk_f32_fp8_e32 v[116:117], v69
	v_cvt_pk_f32_fp8_sdwa v[118:119], v69 src0_sel:WORD_1
	v_cvt_pk_f32_fp8_e32 v[120:121], v70
	v_cvt_pk_f32_fp8_sdwa v[122:123], v70 src0_sel:WORD_1
	v_cvt_pk_f32_fp8_e32 v[124:125], v71
	v_cvt_pk_f32_fp8_sdwa v[126:127], v71 src0_sel:WORD_1
	v_readlane_b32 s2, v146, 5
	s_add_u32 s46, s42, s2
	s_addc_u32 s47, s43, 0
	global_load_dwordx4 v[68:71], v157, s[46:47]
	v_pk_fma_f32 v[32:33], v[112:113], s[14:15], v[32:33] op_sel_hi:[1,0,1]
	v_pk_fma_f32 v[34:35], v[114:115], s[14:15], v[34:35] op_sel_hi:[1,0,1]
	v_pk_fma_f32 v[36:37], v[116:117], s[14:15], v[36:37] op_sel_hi:[1,0,1]
	v_pk_fma_f32 v[38:39], v[118:119], s[14:15], v[38:39] op_sel_hi:[1,0,1]
	v_pk_fma_f32 v[40:41], v[120:121], s[14:15], v[40:41] op_sel_hi:[1,0,1]
	v_pk_fma_f32 v[42:43], v[122:123], s[14:15], v[42:43] op_sel_hi:[1,0,1]
	v_pk_fma_f32 v[44:45], v[124:125], s[14:15], v[44:45] op_sel_hi:[1,0,1]
	v_pk_fma_f32 v[46:47], v[126:127], s[14:15], v[46:47] op_sel_hi:[1,0,1]
	s_waitcnt vmcnt(15)
	v_cvt_pk_f32_fp8_e32 v[112:113], v72
	v_cvt_pk_f32_fp8_sdwa v[114:115], v72 src0_sel:WORD_1
	v_cvt_pk_f32_fp8_e32 v[116:117], v73
	v_cvt_pk_f32_fp8_sdwa v[118:119], v73 src0_sel:WORD_1
	v_cvt_pk_f32_fp8_e32 v[120:121], v74
	v_cvt_pk_f32_fp8_sdwa v[122:123], v74 src0_sel:WORD_1
	v_cvt_pk_f32_fp8_e32 v[124:125], v75
	v_cvt_pk_f32_fp8_sdwa v[126:127], v75 src0_sel:WORD_1
	v_readlane_b32 s2, v146, 6
	s_add_u32 s46, s42, s2
	s_addc_u32 s47, s43, 0
	global_load_dwordx4 v[72:75], v157, s[46:47]
	v_pk_fma_f32 v[32:33], v[112:113], s[16:17], v[32:33] op_sel_hi:[1,0,1]
	v_pk_fma_f32 v[34:35], v[114:115], s[16:17], v[34:35] op_sel_hi:[1,0,1]
	v_pk_fma_f32 v[36:37], v[116:117], s[16:17], v[36:37] op_sel_hi:[1,0,1]
	v_pk_fma_f32 v[38:39], v[118:119], s[16:17], v[38:39] op_sel_hi:[1,0,1]
	v_pk_fma_f32 v[40:41], v[120:121], s[16:17], v[40:41] op_sel_hi:[1,0,1]
	v_pk_fma_f32 v[42:43], v[122:123], s[16:17], v[42:43] op_sel_hi:[1,0,1]
	v_pk_fma_f32 v[44:45], v[124:125], s[16:17], v[44:45] op_sel_hi:[1,0,1]
	v_pk_fma_f32 v[46:47], v[126:127], s[16:17], v[46:47] op_sel_hi:[1,0,1]
	s_waitcnt vmcnt(15)
	v_cvt_pk_f32_fp8_e32 v[112:113], v76
	v_cvt_pk_f32_fp8_sdwa v[114:115], v76 src0_sel:WORD_1
	v_cvt_pk_f32_fp8_e32 v[116:117], v77
	v_cvt_pk_f32_fp8_sdwa v[118:119], v77 src0_sel:WORD_1
	v_cvt_pk_f32_fp8_e32 v[120:121], v78
	v_cvt_pk_f32_fp8_sdwa v[122:123], v78 src0_sel:WORD_1
	v_cvt_pk_f32_fp8_e32 v[124:125], v79
	v_cvt_pk_f32_fp8_sdwa v[126:127], v79 src0_sel:WORD_1
	v_readlane_b32 s2, v146, 7
	s_add_u32 s46, s42, s2
	s_addc_u32 s47, s43, 0
	global_load_dwordx4 v[76:79], v157, s[46:47]
	v_pk_fma_f32 v[32:33], v[112:113], s[18:19], v[32:33] op_sel_hi:[1,0,1]
	v_pk_fma_f32 v[34:35], v[114:115], s[18:19], v[34:35] op_sel_hi:[1,0,1]
	v_pk_fma_f32 v[36:37], v[116:117], s[18:19], v[36:37] op_sel_hi:[1,0,1]
	v_pk_fma_f32 v[38:39], v[118:119], s[18:19], v[38:39] op_sel_hi:[1,0,1]
	v_pk_fma_f32 v[40:41], v[120:121], s[18:19], v[40:41] op_sel_hi:[1,0,1]
	v_pk_fma_f32 v[42:43], v[122:123], s[18:19], v[42:43] op_sel_hi:[1,0,1]
	v_pk_fma_f32 v[44:45], v[124:125], s[18:19], v[44:45] op_sel_hi:[1,0,1]
	v_pk_fma_f32 v[46:47], v[126:127], s[18:19], v[46:47] op_sel_hi:[1,0,1]
.Lgx_p2end_18:
	v_add_u32_e32 v154, 32, v154
	v_add_u32_e32 v156, 4, v156
	s_waitcnt lgkmcnt(0)
	v_readfirstlane_b32 s29, v153
	ds_read_b32 v146, v154 offset:96
	ds_read_b32 v148, v154 offset:4768
	ds_read_b32 v152, v156 offset:7108
	v_readlane_b32 s4, v150, 0
	v_readlane_b32 s6, v150, 1
	v_readlane_b32 s8, v150, 2
	v_readlane_b32 s10, v150, 3
	v_readlane_b32 s12, v150, 4
	v_readlane_b32 s14, v150, 5
	v_readlane_b32 s16, v150, 6
	v_readlane_b32 s18, v150, 7
	s_cmp_eq_u32 s29, 1
	s_cbranch_scc1 .Lgx_p2g1_24
	s_cmp_eq_u32 s29, 2
	s_cbranch_scc1 .Lgx_p2g2_25
	s_waitcnt vmcnt(15)
	v_cvt_pk_f32_fp8_e32 v[112:113], v80
	v_cvt_pk_f32_fp8_sdwa v[114:115], v80 src0_sel:WORD_1
	v_cvt_pk_f32_fp8_e32 v[116:117], v81
	v_cvt_pk_f32_fp8_sdwa v[118:119], v81 src0_sel:WORD_1
	v_cvt_pk_f32_fp8_e32 v[120:121], v82
	v_cvt_pk_f32_fp8_sdwa v[122:123], v82 src0_sel:WORD_1
	v_cvt_pk_f32_fp8_e32 v[124:125], v83
	v_cvt_pk_f32_fp8_sdwa v[126:127], v83 src0_sel:WORD_1
	v_readlane_b32 s2, v147, 0
	s_add_u32 s46, s42, s2
	s_addc_u32 s47, s43, 0
	global_load_dwordx4 v[80:83], v157, s[46:47]
	v_pk_fma_f32 v[0:1], v[112:113], s[4:5], v[0:1] op_sel_hi:[1,0,1]
	v_pk_fma_f32 v[2:3], v[114:115], s[4:5], v[2:3] op_sel_hi:[1,0,1]
	v_pk_fma_f32 v[4:5], v[116:117], s[4:5], v[4:5] op_sel_hi:[1,0,1]
	v_pk_fma_f32 v[6:7], v[118:119], s[4:5], v[6:7] op_sel_hi:[1,0,1]
	v_pk_fma_f32 v[8:9], v[120:121], s[4:5], v[8:9] op_sel_hi:[1,0,1]
	v_pk_fma_f32 v[10:11], v[122:123], s[4:5], v[10:11] op_sel_hi:[1,0,1]
	v_pk_fma_f32 v[12:13], v[124:125], s[4:5], v[12:13] op_sel_hi:[1,0,1]
	v_pk_fma_f32 v[14:15], v[126:127], s[4:5], v[14:15] op_sel_hi:[1,0,1]
	s_waitcnt vmcnt(15)
	v_cvt_pk_f32_fp8_e32 v[112:113], v84
	v_cvt_pk_f32_fp8_sdwa v[114:115], v84 src0_sel:WORD_1
	v_cvt_pk_f32_fp8_e32 v[116:117], v85
	v_cvt_pk_f32_fp8_sdwa v[118:119], v85 src0_sel:WORD_1
	v_cvt_pk_f32_fp8_e32 v[120:121], v86
	v_cvt_pk_f32_fp8_sdwa v[122:123], v86 src0_sel:WORD_1
	v_cvt_pk_f32_fp8_e32 v[124:125], v87
	v_cvt_pk_f32_fp8_sdwa v[126:127], v87 src0_sel:WORD_1
	v_readlane_b32 s2, v147, 1
	s_add_u32 s46, s42, s2
	s_addc_u32 s47, s43, 0
	global_load_dwordx4 v[84:87], v157, s[46:47]
	v_pk_fma_f32 v[0:1], v[112:113], s[6:7], v[0:1] op_sel_hi:[1,0,1]
	v_pk_fma_f32 v[2:3], v[114:115], s[6:7], v[2:3] op_sel_hi:[1,0,1]
	v_pk_fma_f32 v[4:5], v[116:117], s[6:7], v[4:5] op_sel_hi:[1,0,1]
	v_pk_fma_f32 v[6:7], v[118:119], s[6:7], v[6:7] op_sel_hi:[1,0,1]
	v_pk_fma_f32 v[8:9], v[120:121], s[6:7], v[8:9] op_sel_hi:[1,0,1]
	v_pk_fma_f32 v[10:11], v[122:123], s[6:7], v[10:11] op_sel_hi:[1,0,1]
	v_pk_fma_f32 v[12:13], v[124:125], s[6:7], v[12:13] op_sel_hi:[1,0,1]
	v_pk_fma_f32 v[14:15], v[126:127], s[6:7], v[14:15] op_sel_hi:[1,0,1]
	s_waitcnt vmcnt(15)
	v_cvt_pk_f32_fp8_e32 v[112:113], v88
	v_cvt_pk_f32_fp8_sdwa v[114:115], v88 src0_sel:WORD_1
	v_cvt_pk_f32_fp8_e32 v[116:117], v89
	v_cvt_pk_f32_fp8_sdwa v[118:119], v89 src0_sel:WORD_1
	v_cvt_pk_f32_fp8_e32 v[120:121], v90
	v_cvt_pk_f32_fp8_sdwa v[122:123], v90 src0_sel:WORD_1
	v_cvt_pk_f32_fp8_e32 v[124:125], v91
	v_cvt_pk_f32_fp8_sdwa v[126:127], v91 src0_sel:WORD_1
	v_readlane_b32 s2, v147, 2
	s_add_u32 s46, s42, s2
	s_addc_u32 s47, s43, 0
	global_load_dwordx4 v[88:91], v157, s[46:47]
	v_pk_fma_f32 v[0:1], v[112:113], s[8:9], v[0:1] op_sel_hi:[1,0,1]
	v_pk_fma_f32 v[2:3], v[114:115], s[8:9], v[2:3] op_sel_hi:[1,0,1]
	v_pk_fma_f32 v[4:5], v[116:117], s[8:9], v[4:5] op_sel_hi:[1,0,1]
	v_pk_fma_f32 v[6:7], v[118:119], s[8:9], v[6:7] op_sel_hi:[1,0,1]
	v_pk_fma_f32 v[8:9], v[120:121], s[8:9], v[8:9] op_sel_hi:[1,0,1]
	v_pk_fma_f32 v[10:11], v[122:123], s[8:9], v[10:11] op_sel_hi:[1,0,1]
	v_pk_fma_f32 v[12:13], v[124:125], s[8:9], v[12:13] op_sel_hi:[1,0,1]
	v_pk_fma_f32 v[14:15], v[126:127], s[8:9], v[14:15] op_sel_hi:[1,0,1]
	s_waitcnt vmcnt(15)
	v_cvt_pk_f32_fp8_e32 v[112:113], v92
	v_cvt_pk_f32_fp8_sdwa v[114:115], v92 src0_sel:WORD_1
	v_cvt_pk_f32_fp8_e32 v[116:117], v93
	v_cvt_pk_f32_fp8_sdwa v[118:119], v93 src0_sel:WORD_1
	v_cvt_pk_f32_fp8_e32 v[120:121], v94
	v_cvt_pk_f32_fp8_sdwa v[122:123], v94 src0_sel:WORD_1
	v_cvt_pk_f32_fp8_e32 v[124:125], v95
	v_cvt_pk_f32_fp8_sdwa v[126:127], v95 src0_sel:WORD_1
	v_readlane_b32 s2, v147, 3
	s_add_u32 s46, s42, s2
	s_addc_u32 s47, s43, 0
	global_load_dwordx4 v[92:95], v157, s[46:47]
	v_pk_fma_f32 v[0:1], v[112:113], s[10:11], v[0:1] op_sel_hi:[1,0,1]
	v_pk_fma_f32 v[2:3], v[114:115], s[10:11], v[2:3] op_sel_hi:[1,0,1]
	v_pk_fma_f32 v[4:5], v[116:117], s[10:11], v[4:5] op_sel_hi:[1,0,1]
	v_pk_fma_f32 v[6:7], v[118:119], s[10:11], v[6:7] op_sel_hi:[1,0,1]
	v_pk_fma_f32 v[8:9], v[120:121], s[10:11], v[8:9] op_sel_hi:[1,0,1]
	v_pk_fma_f32 v[10:11], v[122:123], s[10:11], v[10:11] op_sel_hi:[1,0,1]
	v_pk_fma_f32 v[12:13], v[124:125], s[10:11], v[12:13] op_sel_hi:[1,0,1]
	v_pk_fma_f32 v[14:15], v[126:127], s[10:11], v[14:15] op_sel_hi:[1,0,1]
	s_waitcnt vmcnt(15)
	v_cvt_pk_f32_fp8_e32 v[112:113], v96
	v_cvt_pk_f32_fp8_sdwa v[114:115], v96 src0_sel:WORD_1
	v_cvt_pk_f32_fp8_e32 v[116:117], v97
	v_cvt_pk_f32_fp8_sdwa v[118:119], v97 src0_sel:WORD_1
	v_cvt_pk_f32_fp8_e32 v[120:121], v98
	v_cvt_pk_f32_fp8_sdwa v[122:123], v98 src0_sel:WORD_1
	v_cvt_pk_f32_fp8_e32 v[124:125], v99
	v_cvt_pk_f32_fp8_sdwa v[126:127], v99 src0_sel:WORD_1
	v_readlane_b32 s2, v147, 4
	s_add_u32 s46, s42, s2
	s_addc_u32 s47, s43, 0
	global_load_dwordx4 v[96:99], v157, s[46:47]
	v_pk_fma_f32 v[0:1], v[112:113], s[12:13], v[0:1] op_sel_hi:[1,0,1]
	v_pk_fma_f32 v[2:3], v[114:115], s[12:13], v[2:3] op_sel_hi:[1,0,1]
	v_pk_fma_f32 v[4:5], v[116:117], s[12:13], v[4:5] op_sel_hi:[1,0,1]
	v_pk_fma_f32 v[6:7], v[118:119], s[12:13], v[6:7] op_sel_hi:[1,0,1]
	v_pk_fma_f32 v[8:9], v[120:121], s[12:13], v[8:9] op_sel_hi:[1,0,1]
	v_pk_fma_f32 v[10:11], v[122:123], s[12:13], v[10:11] op_sel_hi:[1,0,1]
	v_pk_fma_f32 v[12:13], v[124:125], s[12:13], v[12:13] op_sel_hi:[1,0,1]
	v_pk_fma_f32 v[14:15], v[126:127], s[12:13], v[14:15] op_sel_hi:[1,0,1]
	s_waitcnt vmcnt(15)
	v_cvt_pk_f32_fp8_e32 v[112:113], v100
	v_cvt_pk_f32_fp8_sdwa v[114:115], v100 src0_sel:WORD_1
	v_cvt_pk_f32_fp8_e32 v[116:117], v101
	v_cvt_pk_f32_fp8_sdwa v[118:119], v101 src0_sel:WORD_1
	v_cvt_pk_f32_fp8_e32 v[120:121], v102
	v_cvt_pk_f32_fp8_sdwa v[122:123], v102 src0_sel:WORD_1
	v_cvt_pk_f32_fp8_e32 v[124:125], v103
	v_cvt_pk_f32_fp8_sdwa v[126:127], v103 src0_sel:WORD_1
	v_readlane_b32 s2, v147, 5
	s_add_u32 s46, s42, s2
	s_addc_u32 s47, s43, 0
	global_load_dwordx4 v[100:103], v157, s[46:47]
	v_pk_fma_f32 v[0:1], v[112:113], s[14:15], v[0:1] op_sel_hi:[1,0,1]
	v_pk_fma_f32 v[2:3], v[114:115], s[14:15], v[2:3] op_sel_hi:[1,0,1]
	v_pk_fma_f32 v[4:5], v[116:117], s[14:15], v[4:5] op_sel_hi:[1,0,1]
	v_pk_fma_f32 v[6:7], v[118:119], s[14:15], v[6:7] op_sel_hi:[1,0,1]
	v_pk_fma_f32 v[8:9], v[120:121], s[14:15], v[8:9] op_sel_hi:[1,0,1]
	v_pk_fma_f32 v[10:11], v[122:123], s[14:15], v[10:11] op_sel_hi:[1,0,1]
	v_pk_fma_f32 v[12:13], v[124:125], s[14:15], v[12:13] op_sel_hi:[1,0,1]
	v_pk_fma_f32 v[14:15], v[126:127], s[14:15], v[14:15] op_sel_hi:[1,0,1]
	s_waitcnt vmcnt(15)
	v_cvt_pk_f32_fp8_e32 v[112:113], v104
	v_cvt_pk_f32_fp8_sdwa v[114:115], v104 src0_sel:WORD_1
	v_cvt_pk_f32_fp8_e32 v[116:117], v105
	v_cvt_pk_f32_fp8_sdwa v[118:119], v105 src0_sel:WORD_1
	v_cvt_pk_f32_fp8_e32 v[120:121], v106
	v_cvt_pk_f32_fp8_sdwa v[122:123], v106 src0_sel:WORD_1
	v_cvt_pk_f32_fp8_e32 v[124:125], v107
	v_cvt_pk_f32_fp8_sdwa v[126:127], v107 src0_sel:WORD_1
	v_readlane_b32 s2, v147, 6
	s_add_u32 s46, s42, s2
	s_addc_u32 s47, s43, 0
	global_load_dwordx4 v[104:107], v157, s[46:47]
	v_pk_fma_f32 v[0:1], v[112:113], s[16:17], v[0:1] op_sel_hi:[1,0,1]
	v_pk_fma_f32 v[2:3], v[114:115], s[16:17], v[2:3] op_sel_hi:[1,0,1]
	v_pk_fma_f32 v[4:5], v[116:117], s[16:17], v[4:5] op_sel_hi:[1,0,1]
	v_pk_fma_f32 v[6:7], v[118:119], s[16:17], v[6:7] op_sel_hi:[1,0,1]
	v_pk_fma_f32 v[8:9], v[120:121], s[16:17], v[8:9] op_sel_hi:[1,0,1]
	v_pk_fma_f32 v[10:11], v[122:123], s[16:17], v[10:11] op_sel_hi:[1,0,1]
	v_pk_fma_f32 v[12:13], v[124:125], s[16:17], v[12:13] op_sel_hi:[1,0,1]
	v_pk_fma_f32 v[14:15], v[126:127], s[16:17], v[14:15] op_sel_hi:[1,0,1]
	s_waitcnt vmcnt(15)
	v_cvt_pk_f32_fp8_e32 v[112:113], v108
	v_cvt_pk_f32_fp8_sdwa v[114:115], v108 src0_sel:WORD_1
	v_cvt_pk_f32_fp8_e32 v[116:117], v109
	v_cvt_pk_f32_fp8_sdwa v[118:119], v109 src0_sel:WORD_1
	v_cvt_pk_f32_fp8_e32 v[120:121], v110
	v_cvt_pk_f32_fp8_sdwa v[122:123], v110 src0_sel:WORD_1
	v_cvt_pk_f32_fp8_e32 v[124:125], v111
	v_cvt_pk_f32_fp8_sdwa v[126:127], v111 src0_sel:WORD_1
	v_readlane_b32 s2, v147, 7
	s_add_u32 s46, s42, s2
	s_addc_u32 s47, s43, 0
	global_load_dwordx4 v[108:111], v157, s[46:47]
	v_pk_fma_f32 v[0:1], v[112:113], s[18:19], v[0:1] op_sel_hi:[1,0,1]
	v_pk_fma_f32 v[2:3], v[114:115], s[18:19], v[2:3] op_sel_hi:[1,0,1]
	v_pk_fma_f32 v[4:5], v[116:117], s[18:19], v[4:5] op_sel_hi:[1,0,1]
	v_pk_fma_f32 v[6:7], v[118:119], s[18:19], v[6:7] op_sel_hi:[1,0,1]
	v_pk_fma_f32 v[8:9], v[120:121], s[18:19], v[8:9] op_sel_hi:[1,0,1]
	v_pk_fma_f32 v[10:11], v[122:123], s[18:19], v[10:11] op_sel_hi:[1,0,1]
	v_pk_fma_f32 v[12:13], v[124:125], s[18:19], v[12:13] op_sel_hi:[1,0,1]
	v_pk_fma_f32 v[14:15], v[126:127], s[18:19], v[14:15] op_sel_hi:[1,0,1]
	s_branch .Lgx_p2end_22
.Lgx_p2g1_24:
	s_waitcnt vmcnt(15)
	v_cvt_pk_f32_fp8_e32 v[112:113], v80
	v_cvt_pk_f32_fp8_sdwa v[114:115], v80 src0_sel:WORD_1
	v_cvt_pk_f32_fp8_e32 v[116:117], v81
	v_cvt_pk_f32_fp8_sdwa v[118:119], v81 src0_sel:WORD_1
	v_cvt_pk_f32_fp8_e32 v[120:121], v82
	v_cvt_pk_f32_fp8_sdwa v[122:123], v82 src0_sel:WORD_1
	v_cvt_pk_f32_fp8_e32 v[124:125], v83
	v_cvt_pk_f32_fp8_sdwa v[126:127], v83 src0_sel:WORD_1
	v_readlane_b32 s2, v147, 0
	s_add_u32 s46, s42, s2
	s_addc_u32 s47, s43, 0
	global_load_dwordx4 v[80:83], v157, s[46:47]
	v_pk_fma_f32 v[16:17], v[112:113], s[4:5], v[16:17] op_sel_hi:[1,0,1]
	v_pk_fma_f32 v[18:19], v[114:115], s[4:5], v[18:19] op_sel_hi:[1,0,1]
	v_pk_fma_f32 v[20:21], v[116:117], s[4:5], v[20:21] op_sel_hi:[1,0,1]
	v_pk_fma_f32 v[22:23], v[118:119], s[4:5], v[22:23] op_sel_hi:[1,0,1]
	v_pk_fma_f32 v[24:25], v[120:121], s[4:5], v[24:25] op_sel_hi:[1,0,1]
	v_pk_fma_f32 v[26:27], v[122:123], s[4:5], v[26:27] op_sel_hi:[1,0,1]
	v_pk_fma_f32 v[28:29], v[124:125], s[4:5], v[28:29] op_sel_hi:[1,0,1]
	v_pk_fma_f32 v[30:31], v[126:127], s[4:5], v[30:31] op_sel_hi:[1,0,1]
	s_waitcnt vmcnt(15)
	v_cvt_pk_f32_fp8_e32 v[112:113], v84
	v_cvt_pk_f32_fp8_sdwa v[114:115], v84 src0_sel:WORD_1
	v_cvt_pk_f32_fp8_e32 v[116:117], v85
	v_cvt_pk_f32_fp8_sdwa v[118:119], v85 src0_sel:WORD_1
	v_cvt_pk_f32_fp8_e32 v[120:121], v86
	v_cvt_pk_f32_fp8_sdwa v[122:123], v86 src0_sel:WORD_1
	v_cvt_pk_f32_fp8_e32 v[124:125], v87
	v_cvt_pk_f32_fp8_sdwa v[126:127], v87 src0_sel:WORD_1
	v_readlane_b32 s2, v147, 1
	s_add_u32 s46, s42, s2
	s_addc_u32 s47, s43, 0
	global_load_dwordx4 v[84:87], v157, s[46:47]
	v_pk_fma_f32 v[16:17], v[112:113], s[6:7], v[16:17] op_sel_hi:[1,0,1]
	v_pk_fma_f32 v[18:19], v[114:115], s[6:7], v[18:19] op_sel_hi:[1,0,1]
	v_pk_fma_f32 v[20:21], v[116:117], s[6:7], v[20:21] op_sel_hi:[1,0,1]
	v_pk_fma_f32 v[22:23], v[118:119], s[6:7], v[22:23] op_sel_hi:[1,0,1]
	v_pk_fma_f32 v[24:25], v[120:121], s[6:7], v[24:25] op_sel_hi:[1,0,1]
	v_pk_fma_f32 v[26:27], v[122:123], s[6:7], v[26:27] op_sel_hi:[1,0,1]
	v_pk_fma_f32 v[28:29], v[124:125], s[6:7], v[28:29] op_sel_hi:[1,0,1]
	v_pk_fma_f32 v[30:31], v[126:127], s[6:7], v[30:31] op_sel_hi:[1,0,1]
	s_waitcnt vmcnt(15)
	v_cvt_pk_f32_fp8_e32 v[112:113], v88
	v_cvt_pk_f32_fp8_sdwa v[114:115], v88 src0_sel:WORD_1
	v_cvt_pk_f32_fp8_e32 v[116:117], v89
	v_cvt_pk_f32_fp8_sdwa v[118:119], v89 src0_sel:WORD_1
	v_cvt_pk_f32_fp8_e32 v[120:121], v90
	v_cvt_pk_f32_fp8_sdwa v[122:123], v90 src0_sel:WORD_1
	v_cvt_pk_f32_fp8_e32 v[124:125], v91
	v_cvt_pk_f32_fp8_sdwa v[126:127], v91 src0_sel:WORD_1
	v_readlane_b32 s2, v147, 2
	s_add_u32 s46, s42, s2
	s_addc_u32 s47, s43, 0
	global_load_dwordx4 v[88:91], v157, s[46:47]
	v_pk_fma_f32 v[16:17], v[112:113], s[8:9], v[16:17] op_sel_hi:[1,0,1]
	v_pk_fma_f32 v[18:19], v[114:115], s[8:9], v[18:19] op_sel_hi:[1,0,1]
	v_pk_fma_f32 v[20:21], v[116:117], s[8:9], v[20:21] op_sel_hi:[1,0,1]
	v_pk_fma_f32 v[22:23], v[118:119], s[8:9], v[22:23] op_sel_hi:[1,0,1]
	v_pk_fma_f32 v[24:25], v[120:121], s[8:9], v[24:25] op_sel_hi:[1,0,1]
	v_pk_fma_f32 v[26:27], v[122:123], s[8:9], v[26:27] op_sel_hi:[1,0,1]
	v_pk_fma_f32 v[28:29], v[124:125], s[8:9], v[28:29] op_sel_hi:[1,0,1]
	v_pk_fma_f32 v[30:31], v[126:127], s[8:9], v[30:31] op_sel_hi:[1,0,1]
	s_waitcnt vmcnt(15)
	v_cvt_pk_f32_fp8_e32 v[112:113], v92
	v_cvt_pk_f32_fp8_sdwa v[114:115], v92 src0_sel:WORD_1
	v_cvt_pk_f32_fp8_e32 v[116:117], v93
	v_cvt_pk_f32_fp8_sdwa v[118:119], v93 src0_sel:WORD_1
	v_cvt_pk_f32_fp8_e32 v[120:121], v94
	v_cvt_pk_f32_fp8_sdwa v[122:123], v94 src0_sel:WORD_1
	v_cvt_pk_f32_fp8_e32 v[124:125], v95
	v_cvt_pk_f32_fp8_sdwa v[126:127], v95 src0_sel:WORD_1
	v_readlane_b32 s2, v147, 3
	s_add_u32 s46, s42, s2
	s_addc_u32 s47, s43, 0
	global_load_dwordx4 v[92:95], v157, s[46:47]
	v_pk_fma_f32 v[16:17], v[112:113], s[10:11], v[16:17] op_sel_hi:[1,0,1]
	v_pk_fma_f32 v[18:19], v[114:115], s[10:11], v[18:19] op_sel_hi:[1,0,1]
	v_pk_fma_f32 v[20:21], v[116:117], s[10:11], v[20:21] op_sel_hi:[1,0,1]
	v_pk_fma_f32 v[22:23], v[118:119], s[10:11], v[22:23] op_sel_hi:[1,0,1]
	v_pk_fma_f32 v[24:25], v[120:121], s[10:11], v[24:25] op_sel_hi:[1,0,1]
	v_pk_fma_f32 v[26:27], v[122:123], s[10:11], v[26:27] op_sel_hi:[1,0,1]
	v_pk_fma_f32 v[28:29], v[124:125], s[10:11], v[28:29] op_sel_hi:[1,0,1]
	v_pk_fma_f32 v[30:31], v[126:127], s[10:11], v[30:31] op_sel_hi:[1,0,1]
	s_waitcnt vmcnt(15)
	v_cvt_pk_f32_fp8_e32 v[112:113], v96
	v_cvt_pk_f32_fp8_sdwa v[114:115], v96 src0_sel:WORD_1
	v_cvt_pk_f32_fp8_e32 v[116:117], v97
	v_cvt_pk_f32_fp8_sdwa v[118:119], v97 src0_sel:WORD_1
	v_cvt_pk_f32_fp8_e32 v[120:121], v98
	v_cvt_pk_f32_fp8_sdwa v[122:123], v98 src0_sel:WORD_1
	v_cvt_pk_f32_fp8_e32 v[124:125], v99
	v_cvt_pk_f32_fp8_sdwa v[126:127], v99 src0_sel:WORD_1
	v_readlane_b32 s2, v147, 4
	s_add_u32 s46, s42, s2
	s_addc_u32 s47, s43, 0
	global_load_dwordx4 v[96:99], v157, s[46:47]
	v_pk_fma_f32 v[16:17], v[112:113], s[12:13], v[16:17] op_sel_hi:[1,0,1]
	v_pk_fma_f32 v[18:19], v[114:115], s[12:13], v[18:19] op_sel_hi:[1,0,1]
	v_pk_fma_f32 v[20:21], v[116:117], s[12:13], v[20:21] op_sel_hi:[1,0,1]
	v_pk_fma_f32 v[22:23], v[118:119], s[12:13], v[22:23] op_sel_hi:[1,0,1]
	v_pk_fma_f32 v[24:25], v[120:121], s[12:13], v[24:25] op_sel_hi:[1,0,1]
	v_pk_fma_f32 v[26:27], v[122:123], s[12:13], v[26:27] op_sel_hi:[1,0,1]
	v_pk_fma_f32 v[28:29], v[124:125], s[12:13], v[28:29] op_sel_hi:[1,0,1]
	v_pk_fma_f32 v[30:31], v[126:127], s[12:13], v[30:31] op_sel_hi:[1,0,1]
	s_waitcnt vmcnt(15)
	v_cvt_pk_f32_fp8_e32 v[112:113], v100
	v_cvt_pk_f32_fp8_sdwa v[114:115], v100 src0_sel:WORD_1
	v_cvt_pk_f32_fp8_e32 v[116:117], v101
	v_cvt_pk_f32_fp8_sdwa v[118:119], v101 src0_sel:WORD_1
	v_cvt_pk_f32_fp8_e32 v[120:121], v102
	v_cvt_pk_f32_fp8_sdwa v[122:123], v102 src0_sel:WORD_1
	v_cvt_pk_f32_fp8_e32 v[124:125], v103
	v_cvt_pk_f32_fp8_sdwa v[126:127], v103 src0_sel:WORD_1
	v_readlane_b32 s2, v147, 5
	s_add_u32 s46, s42, s2
	s_addc_u32 s47, s43, 0
	global_load_dwordx4 v[100:103], v157, s[46:47]
	v_pk_fma_f32 v[16:17], v[112:113], s[14:15], v[16:17] op_sel_hi:[1,0,1]
	v_pk_fma_f32 v[18:19], v[114:115], s[14:15], v[18:19] op_sel_hi:[1,0,1]
	v_pk_fma_f32 v[20:21], v[116:117], s[14:15], v[20:21] op_sel_hi:[1,0,1]
	v_pk_fma_f32 v[22:23], v[118:119], s[14:15], v[22:23] op_sel_hi:[1,0,1]
	v_pk_fma_f32 v[24:25], v[120:121], s[14:15], v[24:25] op_sel_hi:[1,0,1]
	v_pk_fma_f32 v[26:27], v[122:123], s[14:15], v[26:27] op_sel_hi:[1,0,1]
	v_pk_fma_f32 v[28:29], v[124:125], s[14:15], v[28:29] op_sel_hi:[1,0,1]
	v_pk_fma_f32 v[30:31], v[126:127], s[14:15], v[30:31] op_sel_hi:[1,0,1]
	s_waitcnt vmcnt(15)
	v_cvt_pk_f32_fp8_e32 v[112:113], v104
	v_cvt_pk_f32_fp8_sdwa v[114:115], v104 src0_sel:WORD_1
	v_cvt_pk_f32_fp8_e32 v[116:117], v105
	v_cvt_pk_f32_fp8_sdwa v[118:119], v105 src0_sel:WORD_1
	v_cvt_pk_f32_fp8_e32 v[120:121], v106
	v_cvt_pk_f32_fp8_sdwa v[122:123], v106 src0_sel:WORD_1
	v_cvt_pk_f32_fp8_e32 v[124:125], v107
	v_cvt_pk_f32_fp8_sdwa v[126:127], v107 src0_sel:WORD_1
	v_readlane_b32 s2, v147, 6
	s_add_u32 s46, s42, s2
	s_addc_u32 s47, s43, 0
	global_load_dwordx4 v[104:107], v157, s[46:47]
	v_pk_fma_f32 v[16:17], v[112:113], s[16:17], v[16:17] op_sel_hi:[1,0,1]
	v_pk_fma_f32 v[18:19], v[114:115], s[16:17], v[18:19] op_sel_hi:[1,0,1]
	v_pk_fma_f32 v[20:21], v[116:117], s[16:17], v[20:21] op_sel_hi:[1,0,1]
	v_pk_fma_f32 v[22:23], v[118:119], s[16:17], v[22:23] op_sel_hi:[1,0,1]
	v_pk_fma_f32 v[24:25], v[120:121], s[16:17], v[24:25] op_sel_hi:[1,0,1]
	v_pk_fma_f32 v[26:27], v[122:123], s[16:17], v[26:27] op_sel_hi:[1,0,1]
	v_pk_fma_f32 v[28:29], v[124:125], s[16:17], v[28:29] op_sel_hi:[1,0,1]
	v_pk_fma_f32 v[30:31], v[126:127], s[16:17], v[30:31] op_sel_hi:[1,0,1]
	s_waitcnt vmcnt(15)
	v_cvt_pk_f32_fp8_e32 v[112:113], v108
	v_cvt_pk_f32_fp8_sdwa v[114:115], v108 src0_sel:WORD_1
	v_cvt_pk_f32_fp8_e32 v[116:117], v109
	v_cvt_pk_f32_fp8_sdwa v[118:119], v109 src0_sel:WORD_1
	v_cvt_pk_f32_fp8_e32 v[120:121], v110
	v_cvt_pk_f32_fp8_sdwa v[122:123], v110 src0_sel:WORD_1
	v_cvt_pk_f32_fp8_e32 v[124:125], v111
	v_cvt_pk_f32_fp8_sdwa v[126:127], v111 src0_sel:WORD_1
	v_readlane_b32 s2, v147, 7
	s_add_u32 s46, s42, s2
	s_addc_u32 s47, s43, 0
	global_load_dwordx4 v[108:111], v157, s[46:47]
	v_pk_fma_f32 v[16:17], v[112:113], s[18:19], v[16:17] op_sel_hi:[1,0,1]
	v_pk_fma_f32 v[18:19], v[114:115], s[18:19], v[18:19] op_sel_hi:[1,0,1]
	v_pk_fma_f32 v[20:21], v[116:117], s[18:19], v[20:21] op_sel_hi:[1,0,1]
	v_pk_fma_f32 v[22:23], v[118:119], s[18:19], v[22:23] op_sel_hi:[1,0,1]
	v_pk_fma_f32 v[24:25], v[120:121], s[18:19], v[24:25] op_sel_hi:[1,0,1]
	v_pk_fma_f32 v[26:27], v[122:123], s[18:19], v[26:27] op_sel_hi:[1,0,1]
	v_pk_fma_f32 v[28:29], v[124:125], s[18:19], v[28:29] op_sel_hi:[1,0,1]
	v_pk_fma_f32 v[30:31], v[126:127], s[18:19], v[30:31] op_sel_hi:[1,0,1]
	s_branch .Lgx_p2end_22
.Lgx_p2g2_25:
	s_waitcnt vmcnt(15)
	v_cvt_pk_f32_fp8_e32 v[112:113], v80
	v_cvt_pk_f32_fp8_sdwa v[114:115], v80 src0_sel:WORD_1
	v_cvt_pk_f32_fp8_e32 v[116:117], v81
	v_cvt_pk_f32_fp8_sdwa v[118:119], v81 src0_sel:WORD_1
	v_cvt_pk_f32_fp8_e32 v[120:121], v82
	v_cvt_pk_f32_fp8_sdwa v[122:123], v82 src0_sel:WORD_1
	v_cvt_pk_f32_fp8_e32 v[124:125], v83
	v_cvt_pk_f32_fp8_sdwa v[126:127], v83 src0_sel:WORD_1
	v_readlane_b32 s2, v147, 0
	s_add_u32 s46, s42, s2
	s_addc_u32 s47, s43, 0
	global_load_dwordx4 v[80:83], v157, s[46:47]
	v_pk_fma_f32 v[32:33], v[112:113], s[4:5], v[32:33] op_sel_hi:[1,0,1]
	v_pk_fma_f32 v[34:35], v[114:115], s[4:5], v[34:35] op_sel_hi:[1,0,1]
	v_pk_fma_f32 v[36:37], v[116:117], s[4:5], v[36:37] op_sel_hi:[1,0,1]
	v_pk_fma_f32 v[38:39], v[118:119], s[4:5], v[38:39] op_sel_hi:[1,0,1]
	v_pk_fma_f32 v[40:41], v[120:121], s[4:5], v[40:41] op_sel_hi:[1,0,1]
	v_pk_fma_f32 v[42:43], v[122:123], s[4:5], v[42:43] op_sel_hi:[1,0,1]
	v_pk_fma_f32 v[44:45], v[124:125], s[4:5], v[44:45] op_sel_hi:[1,0,1]
	v_pk_fma_f32 v[46:47], v[126:127], s[4:5], v[46:47] op_sel_hi:[1,0,1]
	s_waitcnt vmcnt(15)
	v_cvt_pk_f32_fp8_e32 v[112:113], v84
	v_cvt_pk_f32_fp8_sdwa v[114:115], v84 src0_sel:WORD_1
	v_cvt_pk_f32_fp8_e32 v[116:117], v85
	v_cvt_pk_f32_fp8_sdwa v[118:119], v85 src0_sel:WORD_1
	v_cvt_pk_f32_fp8_e32 v[120:121], v86
	v_cvt_pk_f32_fp8_sdwa v[122:123], v86 src0_sel:WORD_1
	v_cvt_pk_f32_fp8_e32 v[124:125], v87
	v_cvt_pk_f32_fp8_sdwa v[126:127], v87 src0_sel:WORD_1
	v_readlane_b32 s2, v147, 1
	s_add_u32 s46, s42, s2
	s_addc_u32 s47, s43, 0
	global_load_dwordx4 v[84:87], v157, s[46:47]
	v_pk_fma_f32 v[32:33], v[112:113], s[6:7], v[32:33] op_sel_hi:[1,0,1]
	v_pk_fma_f32 v[34:35], v[114:115], s[6:7], v[34:35] op_sel_hi:[1,0,1]
	v_pk_fma_f32 v[36:37], v[116:117], s[6:7], v[36:37] op_sel_hi:[1,0,1]
	v_pk_fma_f32 v[38:39], v[118:119], s[6:7], v[38:39] op_sel_hi:[1,0,1]
	v_pk_fma_f32 v[40:41], v[120:121], s[6:7], v[40:41] op_sel_hi:[1,0,1]
	v_pk_fma_f32 v[42:43], v[122:123], s[6:7], v[42:43] op_sel_hi:[1,0,1]
	v_pk_fma_f32 v[44:45], v[124:125], s[6:7], v[44:45] op_sel_hi:[1,0,1]
	v_pk_fma_f32 v[46:47], v[126:127], s[6:7], v[46:47] op_sel_hi:[1,0,1]
	s_waitcnt vmcnt(15)
	v_cvt_pk_f32_fp8_e32 v[112:113], v88
	v_cvt_pk_f32_fp8_sdwa v[114:115], v88 src0_sel:WORD_1
	v_cvt_pk_f32_fp8_e32 v[116:117], v89
	v_cvt_pk_f32_fp8_sdwa v[118:119], v89 src0_sel:WORD_1
	v_cvt_pk_f32_fp8_e32 v[120:121], v90
	v_cvt_pk_f32_fp8_sdwa v[122:123], v90 src0_sel:WORD_1
	v_cvt_pk_f32_fp8_e32 v[124:125], v91
	v_cvt_pk_f32_fp8_sdwa v[126:127], v91 src0_sel:WORD_1
	v_readlane_b32 s2, v147, 2
	s_add_u32 s46, s42, s2
	s_addc_u32 s47, s43, 0
	global_load_dwordx4 v[88:91], v157, s[46:47]
	v_pk_fma_f32 v[32:33], v[112:113], s[8:9], v[32:33] op_sel_hi:[1,0,1]
	v_pk_fma_f32 v[34:35], v[114:115], s[8:9], v[34:35] op_sel_hi:[1,0,1]
	v_pk_fma_f32 v[36:37], v[116:117], s[8:9], v[36:37] op_sel_hi:[1,0,1]
	v_pk_fma_f32 v[38:39], v[118:119], s[8:9], v[38:39] op_sel_hi:[1,0,1]
	v_pk_fma_f32 v[40:41], v[120:121], s[8:9], v[40:41] op_sel_hi:[1,0,1]
	v_pk_fma_f32 v[42:43], v[122:123], s[8:9], v[42:43] op_sel_hi:[1,0,1]
	v_pk_fma_f32 v[44:45], v[124:125], s[8:9], v[44:45] op_sel_hi:[1,0,1]
	v_pk_fma_f32 v[46:47], v[126:127], s[8:9], v[46:47] op_sel_hi:[1,0,1]
	s_waitcnt vmcnt(15)
	v_cvt_pk_f32_fp8_e32 v[112:113], v92
	v_cvt_pk_f32_fp8_sdwa v[114:115], v92 src0_sel:WORD_1
	v_cvt_pk_f32_fp8_e32 v[116:117], v93
	v_cvt_pk_f32_fp8_sdwa v[118:119], v93 src0_sel:WORD_1
	v_cvt_pk_f32_fp8_e32 v[120:121], v94
	v_cvt_pk_f32_fp8_sdwa v[122:123], v94 src0_sel:WORD_1
	v_cvt_pk_f32_fp8_e32 v[124:125], v95
	v_cvt_pk_f32_fp8_sdwa v[126:127], v95 src0_sel:WORD_1
	v_readlane_b32 s2, v147, 3
	s_add_u32 s46, s42, s2
	s_addc_u32 s47, s43, 0
	global_load_dwordx4 v[92:95], v157, s[46:47]
	v_pk_fma_f32 v[32:33], v[112:113], s[10:11], v[32:33] op_sel_hi:[1,0,1]
	v_pk_fma_f32 v[34:35], v[114:115], s[10:11], v[34:35] op_sel_hi:[1,0,1]
	v_pk_fma_f32 v[36:37], v[116:117], s[10:11], v[36:37] op_sel_hi:[1,0,1]
	v_pk_fma_f32 v[38:39], v[118:119], s[10:11], v[38:39] op_sel_hi:[1,0,1]
	v_pk_fma_f32 v[40:41], v[120:121], s[10:11], v[40:41] op_sel_hi:[1,0,1]
	v_pk_fma_f32 v[42:43], v[122:123], s[10:11], v[42:43] op_sel_hi:[1,0,1]
	v_pk_fma_f32 v[44:45], v[124:125], s[10:11], v[44:45] op_sel_hi:[1,0,1]
	v_pk_fma_f32 v[46:47], v[126:127], s[10:11], v[46:47] op_sel_hi:[1,0,1]
	s_waitcnt vmcnt(15)
	v_cvt_pk_f32_fp8_e32 v[112:113], v96
	v_cvt_pk_f32_fp8_sdwa v[114:115], v96 src0_sel:WORD_1
	v_cvt_pk_f32_fp8_e32 v[116:117], v97
	v_cvt_pk_f32_fp8_sdwa v[118:119], v97 src0_sel:WORD_1
	v_cvt_pk_f32_fp8_e32 v[120:121], v98
	v_cvt_pk_f32_fp8_sdwa v[122:123], v98 src0_sel:WORD_1
	v_cvt_pk_f32_fp8_e32 v[124:125], v99
	v_cvt_pk_f32_fp8_sdwa v[126:127], v99 src0_sel:WORD_1
	v_readlane_b32 s2, v147, 4
	s_add_u32 s46, s42, s2
	s_addc_u32 s47, s43, 0
	global_load_dwordx4 v[96:99], v157, s[46:47]
	v_pk_fma_f32 v[32:33], v[112:113], s[12:13], v[32:33] op_sel_hi:[1,0,1]
	v_pk_fma_f32 v[34:35], v[114:115], s[12:13], v[34:35] op_sel_hi:[1,0,1]
	v_pk_fma_f32 v[36:37], v[116:117], s[12:13], v[36:37] op_sel_hi:[1,0,1]
	v_pk_fma_f32 v[38:39], v[118:119], s[12:13], v[38:39] op_sel_hi:[1,0,1]
	v_pk_fma_f32 v[40:41], v[120:121], s[12:13], v[40:41] op_sel_hi:[1,0,1]
	v_pk_fma_f32 v[42:43], v[122:123], s[12:13], v[42:43] op_sel_hi:[1,0,1]
	v_pk_fma_f32 v[44:45], v[124:125], s[12:13], v[44:45] op_sel_hi:[1,0,1]
	v_pk_fma_f32 v[46:47], v[126:127], s[12:13], v[46:47] op_sel_hi:[1,0,1]
	s_waitcnt vmcnt(15)
	v_cvt_pk_f32_fp8_e32 v[112:113], v100
	v_cvt_pk_f32_fp8_sdwa v[114:115], v100 src0_sel:WORD_1
	v_cvt_pk_f32_fp8_e32 v[116:117], v101
	v_cvt_pk_f32_fp8_sdwa v[118:119], v101 src0_sel:WORD_1
	v_cvt_pk_f32_fp8_e32 v[120:121], v102
	v_cvt_pk_f32_fp8_sdwa v[122:123], v102 src0_sel:WORD_1
	v_cvt_pk_f32_fp8_e32 v[124:125], v103
	v_cvt_pk_f32_fp8_sdwa v[126:127], v103 src0_sel:WORD_1
	v_readlane_b32 s2, v147, 5
	s_add_u32 s46, s42, s2
	s_addc_u32 s47, s43, 0
	global_load_dwordx4 v[100:103], v157, s[46:47]
	v_pk_fma_f32 v[32:33], v[112:113], s[14:15], v[32:33] op_sel_hi:[1,0,1]
	v_pk_fma_f32 v[34:35], v[114:115], s[14:15], v[34:35] op_sel_hi:[1,0,1]
	v_pk_fma_f32 v[36:37], v[116:117], s[14:15], v[36:37] op_sel_hi:[1,0,1]
	v_pk_fma_f32 v[38:39], v[118:119], s[14:15], v[38:39] op_sel_hi:[1,0,1]
	v_pk_fma_f32 v[40:41], v[120:121], s[14:15], v[40:41] op_sel_hi:[1,0,1]
	v_pk_fma_f32 v[42:43], v[122:123], s[14:15], v[42:43] op_sel_hi:[1,0,1]
	v_pk_fma_f32 v[44:45], v[124:125], s[14:15], v[44:45] op_sel_hi:[1,0,1]
	v_pk_fma_f32 v[46:47], v[126:127], s[14:15], v[46:47] op_sel_hi:[1,0,1]
	s_waitcnt vmcnt(15)
	v_cvt_pk_f32_fp8_e32 v[112:113], v104
	v_cvt_pk_f32_fp8_sdwa v[114:115], v104 src0_sel:WORD_1
	v_cvt_pk_f32_fp8_e32 v[116:117], v105
	v_cvt_pk_f32_fp8_sdwa v[118:119], v105 src0_sel:WORD_1
	v_cvt_pk_f32_fp8_e32 v[120:121], v106
	v_cvt_pk_f32_fp8_sdwa v[122:123], v106 src0_sel:WORD_1
	v_cvt_pk_f32_fp8_e32 v[124:125], v107
	v_cvt_pk_f32_fp8_sdwa v[126:127], v107 src0_sel:WORD_1
	v_readlane_b32 s2, v147, 6
	s_add_u32 s46, s42, s2
	s_addc_u32 s47, s43, 0
	global_load_dwordx4 v[104:107], v157, s[46:47]
	v_pk_fma_f32 v[32:33], v[112:113], s[16:17], v[32:33] op_sel_hi:[1,0,1]
	v_pk_fma_f32 v[34:35], v[114:115], s[16:17], v[34:35] op_sel_hi:[1,0,1]
	v_pk_fma_f32 v[36:37], v[116:117], s[16:17], v[36:37] op_sel_hi:[1,0,1]
	v_pk_fma_f32 v[38:39], v[118:119], s[16:17], v[38:39] op_sel_hi:[1,0,1]
	v_pk_fma_f32 v[40:41], v[120:121], s[16:17], v[40:41] op_sel_hi:[1,0,1]
	v_pk_fma_f32 v[42:43], v[122:123], s[16:17], v[42:43] op_sel_hi:[1,0,1]
	v_pk_fma_f32 v[44:45], v[124:125], s[16:17], v[44:45] op_sel_hi:[1,0,1]
	v_pk_fma_f32 v[46:47], v[126:127], s[16:17], v[46:47] op_sel_hi:[1,0,1]
	s_waitcnt vmcnt(15)
	v_cvt_pk_f32_fp8_e32 v[112:113], v108
	v_cvt_pk_f32_fp8_sdwa v[114:115], v108 src0_sel:WORD_1
	v_cvt_pk_f32_fp8_e32 v[116:117], v109
	v_cvt_pk_f32_fp8_sdwa v[118:119], v109 src0_sel:WORD_1
	v_cvt_pk_f32_fp8_e32 v[120:121], v110
	v_cvt_pk_f32_fp8_sdwa v[122:123], v110 src0_sel:WORD_1
	v_cvt_pk_f32_fp8_e32 v[124:125], v111
	v_cvt_pk_f32_fp8_sdwa v[126:127], v111 src0_sel:WORD_1
	v_readlane_b32 s2, v147, 7
	s_add_u32 s46, s42, s2
	s_addc_u32 s47, s43, 0
	global_load_dwordx4 v[108:111], v157, s[46:47]
	v_pk_fma_f32 v[32:33], v[112:113], s[18:19], v[32:33] op_sel_hi:[1,0,1]
	v_pk_fma_f32 v[34:35], v[114:115], s[18:19], v[34:35] op_sel_hi:[1,0,1]
	v_pk_fma_f32 v[36:37], v[116:117], s[18:19], v[36:37] op_sel_hi:[1,0,1]
	v_pk_fma_f32 v[38:39], v[118:119], s[18:19], v[38:39] op_sel_hi:[1,0,1]
	v_pk_fma_f32 v[40:41], v[120:121], s[18:19], v[40:41] op_sel_hi:[1,0,1]
	v_pk_fma_f32 v[42:43], v[122:123], s[18:19], v[42:43] op_sel_hi:[1,0,1]
	v_pk_fma_f32 v[44:45], v[124:125], s[18:19], v[44:45] op_sel_hi:[1,0,1]
	v_pk_fma_f32 v[46:47], v[126:127], s[18:19], v[46:47] op_sel_hi:[1,0,1]
.Lgx_p2end_22:
	v_add_u32_e32 v154, 32, v154
	v_add_u32_e32 v156, 4, v156
	s_add_u32 s96, s96, 2
	s_cmp_lt_u32 s96, s28
	s_cbranch_scc1 .Lgx_p2loop_17
	s_waitcnt lgkmcnt(0)
	s_waitcnt vmcnt(0)
	s_mov_b32 s2, s54
	s_cmp_lt_u32 s2, 0x4200
	s_cbranch_scc0 .Lgx_epidone_26
	v_readlane_b32 s8, v240, 12
	v_readlane_b32 s9, v240, 13
	v_readlane_b32 s10, v240, 14
	v_readlane_b32 s11, v240, 15
	v_readlane_b32 s12, v240, 3
	v_readlane_b32 s13, v240, 5
	s_lshl_b32 s50, s2, 12
	s_add_u32 s52, s70, s50
	s_addc_u32 s53, s71, 0
	global_load_dwordx4 v[48:51], v160, s[52:53] offset:0
	global_load_dwordx4 v[52:55], v160, s[52:53] offset:16
	global_load_dwordx4 v[56:59], v160, s[52:53] offset:32
	global_load_dwordx4 v[60:63], v160, s[52:53] offset:48
	s_cmp_lt_u32 s2, 0x2000
	s_cselect_b32 s14, 0, 1
	s_cmp_lt_u32 s2, 0x4000
	s_cselect_b32 s14, s14, 2
	s_add_u32 s16, s14, s27
	s_mul_i32 s16, s16, 0x6000
	s_add_u32 s46, s94, s16
	s_addc_u32 s47, s95, 0
	s_add_u32 s46, s46, 0x5000
	s_addc_u32 s47, s47, 0
	global_load_dwordx4 v[64:67], v160, s[46:47] offset:0
	global_load_dwordx4 v[68:71], v160, s[46:47] offset:16
	global_load_dwordx4 v[72:75], v160, s[46:47] offset:32
	global_load_dwordx4 v[76:79], v160, s[46:47] offset:48
	global_load_dwordx4 v[80:83], v160, s[8:9] offset:0
	global_load_dwordx4 v[84:87], v160, s[8:9] offset:16
	global_load_dwordx4 v[88:91], v160, s[8:9] offset:32
	global_load_dwordx4 v[92:95], v160, s[8:9] offset:48
	global_load_dwordx4 v[96:99], v160, s[10:11] offset:0
	global_load_dwordx4 v[100:103], v160, s[10:11] offset:16
	global_load_dwordx4 v[104:107], v160, s[10:11] offset:32
	global_load_dwordx4 v[108:111], v160, s[10:11] offset:48
	s_cmp_lg_u32 s12, 0
	s_cbranch_scc0 .Lgx_nomod_27
	s_add_u32 s16, s14, s13
	s_mul_i32 s16, s16, 0x6000
	s_add_u32 s46, s94, s16
	s_addc_u32 s47, s95, 0
	global_load_dwordx4 v[112:115], v160, s[46:47] offset:0
	global_load_dwordx4 v[116:119], v160, s[46:47] offset:16
	global_load_dwordx4 v[120:123], v160, s[46:47] offset:32
	global_load_dwordx4 v[124:127], v160, s[46:47] offset:48
	s_add_u32 s46, s46, 0x1000
	s_addc_u32 s47, s47, 0
	global_load_dwordx4 v[130:133], v160, s[46:47] offset:0
	global_load_dwordx4 v[134:137], v160, s[46:47] offset:16
	global_load_dwordx4 v[138:141], v160, s[46:47] offset:32
	global_load_dwordx4 v[142:145], v160, s[46:47] offset:48
.Lgx_nomod_27:
	s_mov_b32 s16, 0x3fd744fd
	s_waitcnt vmcnt(0)
	v_mul_f32_e32 v64, v0, v64
	v_mul_f32_e32 v65, v1, v65
	v_mul_f32_e32 v66, v2, v66
	v_mul_f32_e32 v67, v3, v67
	v_mul_f32_e32 v68, v4, v68
	v_mul_f32_e32 v69, v5, v69
	v_mul_f32_e32 v70, v6, v70
	v_mul_f32_e32 v71, v7, v71
	v_mul_f32_e32 v72, v8, v72
	v_mul_f32_e32 v73, v9, v73
	v_mul_f32_e32 v74, v10, v74
	v_mul_f32_e32 v75, v11, v75
	v_mul_f32_e32 v76, v12, v76
	v_mul_f32_e32 v77, v13, v77
	v_mul_f32_e32 v78, v14, v78
	v_mul_f32_e32 v79, v15, v79
	v_fma_f32 v48, v48, s16, v64
	v_fma_f32 v49, v49, s16, v65
	v_fma_f32 v50, v50, s16, v66
	v_fma_f32 v51, v51, s16, v67
	v_fma_f32 v52, v52, s16, v68
	v_fma_f32 v53, v53, s16, v69
	v_fma_f32 v54, v54, s16, v70
	v_fma_f32 v55, v55, s16, v71
	v_fma_f32 v56, v56, s16, v72
	v_fma_f32 v57, v57, s16, v73
	v_fma_f32 v58, v58, s16, v74
	v_fma_f32 v59, v59, s16, v75
	v_fma_f32 v60, v60, s16, v76
	v_fma_f32 v61, v61, s16, v77
	v_fma_f32 v62, v62, s16, v78
	v_fma_f32 v63, v63, s16, v79
	v_add_f32_e32 v146, v48, v49
	v_add_f32_e32 v146, v146, v50
	v_add_f32_e32 v146, v146, v51
	v_add_f32_e32 v146, v146, v52
	v_add_f32_e32 v146, v146, v53
	v_add_f32_e32 v146, v146, v54
	v_add_f32_e32 v146, v146, v55
	v_add_f32_e32 v146, v146, v56
	v_add_f32_e32 v146, v146, v57
	v_add_f32_e32 v146, v146, v58
	v_add_f32_e32 v146, v146, v59
	v_add_f32_e32 v146, v146, v60
	v_add_f32_e32 v146, v146, v61
	v_add_f32_e32 v146, v146, v62
	v_add_f32_e32 v146, v146, v63
	s_nop 1
	v_add_f32_dpp v146, v146, v146 quad_perm:[1,0,3,2] row_mask:0xf bank_mask:0xf
	s_nop 1
	v_add_f32_dpp v146, v146, v146 quad_perm:[2,3,0,1] row_mask:0xf bank_mask:0xf
	s_nop 1
	v_add_f32_dpp v146, v146, v146 row_half_mirror row_mask:0xf bank_mask:0xf
	s_nop 1
	v_add_f32_dpp v146, v146, v146 row_mirror row_mask:0xf bank_mask:0xf
	s_nop 1
	v_readlane_b32 s4, v146, 0
	v_readlane_b32 s5, v146, 16
	v_readlane_b32 s6, v146, 32
	v_readlane_b32 s7, v146, 48
	s_nop 1
	v_mov_b32_e32 v147, s4
	v_add_f32_e32 v147, s5, v147
	v_add_f32_e32 v147, s6, v147
	v_add_f32_e32 v147, s7, v147
	v_mul_f32_e32 v147, 0x3a800000, v147
	v_sub_f32_e32 v48, v48, v147
	v_sub_f32_e32 v49, v49, v147
	v_sub_f32_e32 v50, v50, v147
	v_sub_f32_e32 v51, v51, v147
	v_sub_f32_e32 v52, v52, v147
	v_sub_f32_e32 v53, v53, v147
	v_sub_f32_e32 v54, v54, v147
	v_sub_f32_e32 v55, v55, v147
	v_sub_f32_e32 v56, v56, v147
	v_sub_f32_e32 v57, v57, v147
	v_sub_f32_e32 v58, v58, v147
	v_sub_f32_e32 v59, v59, v147
	v_sub_f32_e32 v60, v60, v147
	v_sub_f32_e32 v61, v61, v147
	v_sub_f32_e32 v62, v62, v147
	v_sub_f32_e32 v63, v63, v147
	v_mul_f32_e32 v146, v48, v48
	v_mul_f32_e32 v148, v49, v49
	v_add_f32_e32 v146, v146, v148
	v_mul_f32_e32 v148, v50, v50
	v_add_f32_e32 v146, v146, v148
	v_mul_f32_e32 v148, v51, v51
	v_add_f32_e32 v146, v146, v148
	v_mul_f32_e32 v148, v52, v52
	v_add_f32_e32 v146, v146, v148
	v_mul_f32_e32 v148, v53, v53
	v_add_f32_e32 v146, v146, v148
	v_mul_f32_e32 v148, v54, v54
	v_add_f32_e32 v146, v146, v148
	v_mul_f32_e32 v148, v55, v55
	v_add_f32_e32 v146, v146, v148
	v_mul_f32_e32 v148, v56, v56
	v_add_f32_e32 v146, v146, v148
	v_mul_f32_e32 v148, v57, v57
	v_add_f32_e32 v146, v146, v148
	v_mul_f32_e32 v148, v58, v58
	v_add_f32_e32 v146, v146, v148
	v_mul_f32_e32 v148, v59, v59
	v_add_f32_e32 v146, v146, v148
	v_mul_f32_e32 v148, v60, v60
	v_add_f32_e32 v146, v146, v148
	v_mul_f32_e32 v148, v61, v61
	v_add_f32_e32 v146, v146, v148
	v_mul_f32_e32 v148, v62, v62
	v_add_f32_e32 v146, v146, v148
	v_mul_f32_e32 v148, v63, v63
	v_add_f32_e32 v146, v146, v148
	s_nop 1
	v_add_f32_dpp v146, v146, v146 quad_perm:[1,0,3,2] row_mask:0xf bank_mask:0xf
	s_nop 1
	v_add_f32_dpp v146, v146, v146 quad_perm:[2,3,0,1] row_mask:0xf bank_mask:0xf
	s_nop 1
	v_add_f32_dpp v146, v146, v146 row_half_mirror row_mask:0xf bank_mask:0xf
	s_nop 1
	v_add_f32_dpp v146, v146, v146 row_mirror row_mask:0xf bank_mask:0xf
	s_nop 1
	v_readlane_b32 s4, v146, 0
	v_readlane_b32 s5, v146, 16
	v_readlane_b32 s6, v146, 32
	v_readlane_b32 s7, v146, 48
	s_nop 1
	v_mov_b32_e32 v147, s4
	v_add_f32_e32 v147, s5, v147
	v_add_f32_e32 v147, s6, v147
	v_add_f32_e32 v147, s7, v147
	v_fmamk_f32 v147, v147, 0x3a800000, v163
	s_mov_b32 s4, 0x800000
	v_cmp_gt_f32_e32 vcc, s4, v147
	v_mul_f32_e32 v148, 0x4b800000, v147
	s_nop 1
	v_cndmask_b32_e32 v147, v147, v148, vcc
	v_rsq_f32_e32 v147, v147
	s_nop 0
	v_mul_f32_e32 v148, 0x45800000, v147
	v_cndmask_b32_e32 v147, v147, v148, vcc
	v_mul_f32_e32 v48, v48, v147
	v_mul_f32_e32 v49, v49, v147
	v_mul_f32_e32 v50, v50, v147
	v_mul_f32_e32 v51, v51, v147
	v_mul_f32_e32 v52, v52, v147
	v_mul_f32_e32 v53, v53, v147
	v_mul_f32_e32 v54, v54, v147
	v_mul_f32_e32 v55, v55, v147
	v_mul_f32_e32 v56, v56, v147
	v_mul_f32_e32 v57, v57, v147
	v_mul_f32_e32 v58, v58, v147
	v_mul_f32_e32 v59, v59, v147
	v_mul_f32_e32 v60, v60, v147
	v_mul_f32_e32 v61, v61, v147
	v_mul_f32_e32 v62, v62, v147
	v_mul_f32_e32 v63, v63, v147
	v_fma_f32 v48, v80, v48, v96
	v_fma_f32 v49, v81, v49, v97
	v_fma_f32 v50, v82, v50, v98
	v_fma_f32 v51, v83, v51, v99
	v_fma_f32 v52, v84, v52, v100
	v_fma_f32 v53, v85, v53, v101
	v_fma_f32 v54, v86, v54, v102
	v_fma_f32 v55, v87, v55, v103
	v_fma_f32 v56, v88, v56, v104
	v_fma_f32 v57, v89, v57, v105
	v_fma_f32 v58, v90, v58, v106
	v_fma_f32 v59, v91, v59, v107
	v_fma_f32 v60, v92, v60, v108
	v_fma_f32 v61, v93, v61, v109
	v_fma_f32 v62, v94, v62, v110
	v_fma_f32 v63, v95, v63, v111
	s_cmp_lg_u32 s12, 0
	s_cbranch_scc0 .Lgx_lastlayer_28
	global_store_dwordx4 v160, v[48:51], s[52:53] offset:0
	global_store_dwordx4 v160, v[52:55], s[52:53] offset:16
	global_store_dwordx4 v160, v[56:59], s[52:53] offset:32
	global_store_dwordx4 v160, v[60:63], s[52:53] offset:48
	v_add_f32_e32 v130, 1.0, v130
	v_add_f32_e32 v131, 1.0, v131
	v_add_f32_e32 v132, 1.0, v132
	v_add_f32_e32 v133, 1.0, v133
	v_add_f32_e32 v134, 1.0, v134
	v_add_f32_e32 v135, 1.0, v135
	v_add_f32_e32 v136, 1.0, v136
	v_add_f32_e32 v137, 1.0, v137
	v_add_f32_e32 v138, 1.0, v138
	v_add_f32_e32 v139, 1.0, v139
	v_add_f32_e32 v140, 1.0, v140
	v_add_f32_e32 v141, 1.0, v141
	v_add_f32_e32 v142, 1.0, v142
	v_add_f32_e32 v143, 1.0, v143
	v_add_f32_e32 v144, 1.0, v144
	v_add_f32_e32 v145, 1.0, v145
	v_fma_f32 v112, v48, v130, v112
	v_fma_f32 v113, v49, v131, v113
	v_fma_f32 v114, v50, v132, v114
	v_fma_f32 v115, v51, v133, v115
	v_fma_f32 v116, v52, v134, v116
	v_fma_f32 v117, v53, v135, v117
	v_fma_f32 v118, v54, v136, v118
	v_fma_f32 v119, v55, v137, v119
	v_fma_f32 v120, v56, v138, v120
	v_fma_f32 v121, v57, v139, v121
	v_fma_f32 v122, v58, v140, v122
	v_fma_f32 v123, v59, v141, v123
	v_fma_f32 v124, v60, v142, v124
	v_fma_f32 v125, v61, v143, v125
	v_fma_f32 v126, v62, v144, v126
	v_fma_f32 v127, v63, v145, v127
	v_cvt_pk_bf16_f32 v64, v112, v113
	v_cvt_pk_bf16_f32 v65, v114, v115
	v_cvt_pk_bf16_f32 v66, v116, v117
	v_cvt_pk_bf16_f32 v67, v118, v119
	v_cvt_pk_bf16_f32 v68, v120, v121
	v_cvt_pk_bf16_f32 v69, v122, v123
	v_cvt_pk_bf16_f32 v70, v124, v125
	v_cvt_pk_bf16_f32 v71, v126, v127
	s_lshl_b32 s50, s2, 11
	s_add_u32 s46, s74, s50
	s_addc_u32 s47, s75, 0
	global_store_dwordx4 v159, v[64:67], s[46:47]
	global_store_dwordx4 v159, v[68:71], s[46:47] offset:16
	s_branch .Lgx_stdone_29

.Lgx_epidone_26:
	s_add_u32 s2, s54, s59
	s_cmp_lt_u32 s2, 0x4200
	s_cbranch_scc0 .Lgx_epidone_30
	v_readlane_b32 s8, v240, 12
	v_readlane_b32 s9, v240, 13
	v_readlane_b32 s10, v240, 14
	v_readlane_b32 s11, v240, 15
	v_readlane_b32 s12, v240, 3
	v_readlane_b32 s13, v240, 5
	s_lshl_b32 s50, s2, 12
	s_add_u32 s52, s70, s50
	s_addc_u32 s53, s71, 0
	global_load_dwordx4 v[48:51], v160, s[52:53] offset:0
	global_load_dwordx4 v[52:55], v160, s[52:53] offset:16
	global_load_dwordx4 v[56:59], v160, s[52:53] offset:32
	global_load_dwordx4 v[60:63], v160, s[52:53] offset:48
	s_cmp_lt_u32 s2, 0x2000
	s_cselect_b32 s14, 0, 1
	s_cmp_lt_u32 s2, 0x4000
	s_cselect_b32 s14, s14, 2
	s_add_u32 s16, s14, s27
	s_mul_i32 s16, s16, 0x6000
	s_add_u32 s46, s94, s16
	s_addc_u32 s47, s95, 0
	s_add_u32 s46, s46, 0x5000
	s_addc_u32 s47, s47, 0
	global_load_dwordx4 v[64:67], v160, s[46:47] offset:0
	global_load_dwordx4 v[68:71], v160, s[46:47] offset:16
	global_load_dwordx4 v[72:75], v160, s[46:47] offset:32
	global_load_dwordx4 v[76:79], v160, s[46:47] offset:48
	global_load_dwordx4 v[80:83], v160, s[8:9] offset:0
	global_load_dwordx4 v[84:87], v160, s[8:9] offset:16
	global_load_dwordx4 v[88:91], v160, s[8:9] offset:32
	global_load_dwordx4 v[92:95], v160, s[8:9] offset:48
	global_load_dwordx4 v[96:99], v160, s[10:11] offset:0
	global_load_dwordx4 v[100:103], v160, s[10:11] offset:16
	global_load_dwordx4 v[104:107], v160, s[10:11] offset:32
	global_load_dwordx4 v[108:111], v160, s[10:11] offset:48
	s_cmp_lg_u32 s12, 0
	s_cbranch_scc0 .Lgx_nomod_31
	s_add_u32 s16, s14, s13
	s_mul_i32 s16, s16, 0x6000
	s_add_u32 s46, s94, s16
	s_addc_u32 s47, s95, 0
	global_load_dwordx4 v[112:115], v160, s[46:47] offset:0
	global_load_dwordx4 v[116:119], v160, s[46:47] offset:16
	global_load_dwordx4 v[120:123], v160, s[46:47] offset:32
	global_load_dwordx4 v[124:127], v160, s[46:47] offset:48
	s_add_u32 s46, s46, 0x1000
	s_addc_u32 s47, s47, 0
	global_load_dwordx4 v[130:133], v160, s[46:47] offset:0
	global_load_dwordx4 v[134:137], v160, s[46:47] offset:16
	global_load_dwordx4 v[138:141], v160, s[46:47] offset:32
	global_load_dwordx4 v[142:145], v160, s[46:47] offset:48
.Lgx_nomod_31:
	s_mov_b32 s16, 0x3fd744fd
	s_waitcnt vmcnt(0)
	v_mul_f32_e32 v64, v16, v64
	v_mul_f32_e32 v65, v17, v65
	v_mul_f32_e32 v66, v18, v66
	v_mul_f32_e32 v67, v19, v67
	v_mul_f32_e32 v68, v20, v68
	v_mul_f32_e32 v69, v21, v69
	v_mul_f32_e32 v70, v22, v70
	v_mul_f32_e32 v71, v23, v71
	v_mul_f32_e32 v72, v24, v72
	v_mul_f32_e32 v73, v25, v73
	v_mul_f32_e32 v74, v26, v74
	v_mul_f32_e32 v75, v27, v75
	v_mul_f32_e32 v76, v28, v76
	v_mul_f32_e32 v77, v29, v77
	v_mul_f32_e32 v78, v30, v78
	v_mul_f32_e32 v79, v31, v79
	v_fma_f32 v48, v48, s16, v64
	v_fma_f32 v49, v49, s16, v65
	v_fma_f32 v50, v50, s16, v66
	v_fma_f32 v51, v51, s16, v67
	v_fma_f32 v52, v52, s16, v68
	v_fma_f32 v53, v53, s16, v69
	v_fma_f32 v54, v54, s16, v70
	v_fma_f32 v55, v55, s16, v71
	v_fma_f32 v56, v56, s16, v72
	v_fma_f32 v57, v57, s16, v73
	v_fma_f32 v58, v58, s16, v74
	v_fma_f32 v59, v59, s16, v75
	v_fma_f32 v60, v60, s16, v76
	v_fma_f32 v61, v61, s16, v77
	v_fma_f32 v62, v62, s16, v78
	v_fma_f32 v63, v63, s16, v79
	v_add_f32_e32 v146, v48, v49
	v_add_f32_e32 v146, v146, v50
	v_add_f32_e32 v146, v146, v51
	v_add_f32_e32 v146, v146, v52
	v_add_f32_e32 v146, v146, v53
	v_add_f32_e32 v146, v146, v54
	v_add_f32_e32 v146, v146, v55
	v_add_f32_e32 v146, v146, v56
	v_add_f32_e32 v146, v146, v57
	v_add_f32_e32 v146, v146, v58
	v_add_f32_e32 v146, v146, v59
	v_add_f32_e32 v146, v146, v60
	v_add_f32_e32 v146, v146, v61
	v_add_f32_e32 v146, v146, v62
	v_add_f32_e32 v146, v146, v63
	s_nop 1
	v_add_f32_dpp v146, v146, v146 quad_perm:[1,0,3,2] row_mask:0xf bank_mask:0xf
	s_nop 1
	v_add_f32_dpp v146, v146, v146 quad_perm:[2,3,0,1] row_mask:0xf bank_mask:0xf
	s_nop 1
	v_add_f32_dpp v146, v146, v146 row_half_mirror row_mask:0xf bank_mask:0xf
	s_nop 1
	v_add_f32_dpp v146, v146, v146 row_mirror row_mask:0xf bank_mask:0xf
	s_nop 1
	v_readlane_b32 s4, v146, 0
	v_readlane_b32 s5, v146, 16
	v_readlane_b32 s6, v146, 32
	v_readlane_b32 s7, v146, 48
	s_nop 1
	v_mov_b32_e32 v147, s4
	v_add_f32_e32 v147, s5, v147
	v_add_f32_e32 v147, s6, v147
	v_add_f32_e32 v147, s7, v147
	v_mul_f32_e32 v147, 0x3a800000, v147
	v_sub_f32_e32 v48, v48, v147
	v_sub_f32_e32 v49, v49, v147
	v_sub_f32_e32 v50, v50, v147
	v_sub_f32_e32 v51, v51, v147
	v_sub_f32_e32 v52, v52, v147
	v_sub_f32_e32 v53, v53, v147
	v_sub_f32_e32 v54, v54, v147
	v_sub_f32_e32 v55, v55, v147
	v_sub_f32_e32 v56, v56, v147
	v_sub_f32_e32 v57, v57, v147
	v_sub_f32_e32 v58, v58, v147
	v_sub_f32_e32 v59, v59, v147
	v_sub_f32_e32 v60, v60, v147
	v_sub_f32_e32 v61, v61, v147
	v_sub_f32_e32 v62, v62, v147
	v_sub_f32_e32 v63, v63, v147
	v_mul_f32_e32 v146, v48, v48
	v_mul_f32_e32 v148, v49, v49
	v_add_f32_e32 v146, v146, v148
	v_mul_f32_e32 v148, v50, v50
	v_add_f32_e32 v146, v146, v148
	v_mul_f32_e32 v148, v51, v51
	v_add_f32_e32 v146, v146, v148
	v_mul_f32_e32 v148, v52, v52
	v_add_f32_e32 v146, v146, v148
	v_mul_f32_e32 v148, v53, v53
	v_add_f32_e32 v146, v146, v148
	v_mul_f32_e32 v148, v54, v54
	v_add_f32_e32 v146, v146, v148
	v_mul_f32_e32 v148, v55, v55
	v_add_f32_e32 v146, v146, v148
	v_mul_f32_e32 v148, v56, v56
	v_add_f32_e32 v146, v146, v148
	v_mul_f32_e32 v148, v57, v57
	v_add_f32_e32 v146, v146, v148
	v_mul_f32_e32 v148, v58, v58
	v_add_f32_e32 v146, v146, v148
	v_mul_f32_e32 v148, v59, v59
	v_add_f32_e32 v146, v146, v148
	v_mul_f32_e32 v148, v60, v60
	v_add_f32_e32 v146, v146, v148
	v_mul_f32_e32 v148, v61, v61
	v_add_f32_e32 v146, v146, v148
	v_mul_f32_e32 v148, v62, v62
	v_add_f32_e32 v146, v146, v148
	v_mul_f32_e32 v148, v63, v63
	v_add_f32_e32 v146, v146, v148
	s_nop 1
	v_add_f32_dpp v146, v146, v146 quad_perm:[1,0,3,2] row_mask:0xf bank_mask:0xf
	s_nop 1
	v_add_f32_dpp v146, v146, v146 quad_perm:[2,3,0,1] row_mask:0xf bank_mask:0xf
	s_nop 1
	v_add_f32_dpp v146, v146, v146 row_half_mirror row_mask:0xf bank_mask:0xf
	s_nop 1
	v_add_f32_dpp v146, v146, v146 row_mirror row_mask:0xf bank_mask:0xf
	s_nop 1
	v_readlane_b32 s4, v146, 0
	v_readlane_b32 s5, v146, 16
	v_readlane_b32 s6, v146, 32
	v_readlane_b32 s7, v146, 48
	s_nop 1
	v_mov_b32_e32 v147, s4
	v_add_f32_e32 v147, s5, v147
	v_add_f32_e32 v147, s6, v147
	v_add_f32_e32 v147, s7, v147
	v_fmamk_f32 v147, v147, 0x3a800000, v163
	s_mov_b32 s4, 0x800000
	v_cmp_gt_f32_e32 vcc, s4, v147
	v_mul_f32_e32 v148, 0x4b800000, v147
	s_nop 1
	v_cndmask_b32_e32 v147, v147, v148, vcc
	v_rsq_f32_e32 v147, v147
	s_nop 0
	v_mul_f32_e32 v148, 0x45800000, v147
	v_cndmask_b32_e32 v147, v147, v148, vcc
	v_mul_f32_e32 v48, v48, v147
	v_mul_f32_e32 v49, v49, v147
	v_mul_f32_e32 v50, v50, v147
	v_mul_f32_e32 v51, v51, v147
	v_mul_f32_e32 v52, v52, v147
	v_mul_f32_e32 v53, v53, v147
	v_mul_f32_e32 v54, v54, v147
	v_mul_f32_e32 v55, v55, v147
	v_mul_f32_e32 v56, v56, v147
	v_mul_f32_e32 v57, v57, v147
	v_mul_f32_e32 v58, v58, v147
	v_mul_f32_e32 v59, v59, v147
	v_mul_f32_e32 v60, v60, v147
	v_mul_f32_e32 v61, v61, v147
	v_mul_f32_e32 v62, v62, v147
	v_mul_f32_e32 v63, v63, v147
	v_fma_f32 v48, v80, v48, v96
	v_fma_f32 v49, v81, v49, v97
	v_fma_f32 v50, v82, v50, v98
	v_fma_f32 v51, v83, v51, v99
	v_fma_f32 v52, v84, v52, v100
	v_fma_f32 v53, v85, v53, v101
	v_fma_f32 v54, v86, v54, v102
	v_fma_f32 v55, v87, v55, v103
	v_fma_f32 v56, v88, v56, v104
	v_fma_f32 v57, v89, v57, v105
	v_fma_f32 v58, v90, v58, v106
	v_fma_f32 v59, v91, v59, v107
	v_fma_f32 v60, v92, v60, v108
	v_fma_f32 v61, v93, v61, v109
	v_fma_f32 v62, v94, v62, v110
	v_fma_f32 v63, v95, v63, v111
	s_cmp_lg_u32 s12, 0
	s_cbranch_scc0 .Lgx_lastlayer_32
	global_store_dwordx4 v160, v[48:51], s[52:53] offset:0
	global_store_dwordx4 v160, v[52:55], s[52:53] offset:16
	global_store_dwordx4 v160, v[56:59], s[52:53] offset:32
	global_store_dwordx4 v160, v[60:63], s[52:53] offset:48
	v_add_f32_e32 v130, 1.0, v130
	v_add_f32_e32 v131, 1.0, v131
	v_add_f32_e32 v132, 1.0, v132
	v_add_f32_e32 v133, 1.0, v133
	v_add_f32_e32 v134, 1.0, v134
	v_add_f32_e32 v135, 1.0, v135
	v_add_f32_e32 v136, 1.0, v136
	v_add_f32_e32 v137, 1.0, v137
	v_add_f32_e32 v138, 1.0, v138
	v_add_f32_e32 v139, 1.0, v139
	v_add_f32_e32 v140, 1.0, v140
	v_add_f32_e32 v141, 1.0, v141
	v_add_f32_e32 v142, 1.0, v142
	v_add_f32_e32 v143, 1.0, v143
	v_add_f32_e32 v144, 1.0, v144
	v_add_f32_e32 v145, 1.0, v145
	v_fma_f32 v112, v48, v130, v112
	v_fma_f32 v113, v49, v131, v113
	v_fma_f32 v114, v50, v132, v114
	v_fma_f32 v115, v51, v133, v115
	v_fma_f32 v116, v52, v134, v116
	v_fma_f32 v117, v53, v135, v117
	v_fma_f32 v118, v54, v136, v118
	v_fma_f32 v119, v55, v137, v119
	v_fma_f32 v120, v56, v138, v120
	v_fma_f32 v121, v57, v139, v121
	v_fma_f32 v122, v58, v140, v122
	v_fma_f32 v123, v59, v141, v123
	v_fma_f32 v124, v60, v142, v124
	v_fma_f32 v125, v61, v143, v125
	v_fma_f32 v126, v62, v144, v126
	v_fma_f32 v127, v63, v145, v127
	v_cvt_pk_bf16_f32 v64, v112, v113
	v_cvt_pk_bf16_f32 v65, v114, v115
	v_cvt_pk_bf16_f32 v66, v116, v117
	v_cvt_pk_bf16_f32 v67, v118, v119
	v_cvt_pk_bf16_f32 v68, v120, v121
	v_cvt_pk_bf16_f32 v69, v122, v123
	v_cvt_pk_bf16_f32 v70, v124, v125
	v_cvt_pk_bf16_f32 v71, v126, v127
	s_lshl_b32 s50, s2, 11
	s_add_u32 s46, s74, s50
	s_addc_u32 s47, s75, 0
	global_store_dwordx4 v159, v[64:67], s[46:47]
	global_store_dwordx4 v159, v[68:71], s[46:47] offset:16
	s_branch .Lgx_stdone_33

.Lgx_epidone_30:
	s_add_u32 s2, s54, s59
	s_add_u32 s2, s2, s59
	s_cmp_lt_u32 s2, 0x4200
	s_cbranch_scc0 .Lgx_epidone_34
	v_readlane_b32 s8, v240, 12
	v_readlane_b32 s9, v240, 13
	v_readlane_b32 s10, v240, 14
	v_readlane_b32 s11, v240, 15
	v_readlane_b32 s12, v240, 3
	v_readlane_b32 s13, v240, 5
	s_lshl_b32 s50, s2, 12
	s_add_u32 s52, s70, s50
	s_addc_u32 s53, s71, 0
	global_load_dwordx4 v[48:51], v160, s[52:53] offset:0
	global_load_dwordx4 v[52:55], v160, s[52:53] offset:16
	global_load_dwordx4 v[56:59], v160, s[52:53] offset:32
	global_load_dwordx4 v[60:63], v160, s[52:53] offset:48
	s_cmp_lt_u32 s2, 0x2000
	s_cselect_b32 s14, 0, 1
	s_cmp_lt_u32 s2, 0x4000
	s_cselect_b32 s14, s14, 2
	s_add_u32 s16, s14, s27
	s_mul_i32 s16, s16, 0x6000
	s_add_u32 s46, s94, s16
	s_addc_u32 s47, s95, 0
	s_add_u32 s46, s46, 0x5000
	s_addc_u32 s47, s47, 0
	global_load_dwordx4 v[64:67], v160, s[46:47] offset:0
	global_load_dwordx4 v[68:71], v160, s[46:47] offset:16
	global_load_dwordx4 v[72:75], v160, s[46:47] offset:32
	global_load_dwordx4 v[76:79], v160, s[46:47] offset:48
	global_load_dwordx4 v[80:83], v160, s[8:9] offset:0
	global_load_dwordx4 v[84:87], v160, s[8:9] offset:16
	global_load_dwordx4 v[88:91], v160, s[8:9] offset:32
	global_load_dwordx4 v[92:95], v160, s[8:9] offset:48
	global_load_dwordx4 v[96:99], v160, s[10:11] offset:0
	global_load_dwordx4 v[100:103], v160, s[10:11] offset:16
	global_load_dwordx4 v[104:107], v160, s[10:11] offset:32
	global_load_dwordx4 v[108:111], v160, s[10:11] offset:48
	s_cmp_lg_u32 s12, 0
	s_cbranch_scc0 .Lgx_nomod_35
	s_add_u32 s16, s14, s13
	s_mul_i32 s16, s16, 0x6000
	s_add_u32 s46, s94, s16
	s_addc_u32 s47, s95, 0
	global_load_dwordx4 v[112:115], v160, s[46:47] offset:0
	global_load_dwordx4 v[116:119], v160, s[46:47] offset:16
	global_load_dwordx4 v[120:123], v160, s[46:47] offset:32
	global_load_dwordx4 v[124:127], v160, s[46:47] offset:48
	s_add_u32 s46, s46, 0x1000
	s_addc_u32 s47, s47, 0
	global_load_dwordx4 v[130:133], v160, s[46:47] offset:0
	global_load_dwordx4 v[134:137], v160, s[46:47] offset:16
	global_load_dwordx4 v[138:141], v160, s[46:47] offset:32
	global_load_dwordx4 v[142:145], v160, s[46:47] offset:48
.Lgx_nomod_35:
	s_mov_b32 s16, 0x3fd744fd
	s_waitcnt vmcnt(0)
	v_mul_f32_e32 v64, v32, v64
	v_mul_f32_e32 v65, v33, v65
	v_mul_f32_e32 v66, v34, v66
	v_mul_f32_e32 v67, v35, v67
	v_mul_f32_e32 v68, v36, v68
	v_mul_f32_e32 v69, v37, v69
	v_mul_f32_e32 v70, v38, v70
	v_mul_f32_e32 v71, v39, v71
	v_mul_f32_e32 v72, v40, v72
	v_mul_f32_e32 v73, v41, v73
	v_mul_f32_e32 v74, v42, v74
	v_mul_f32_e32 v75, v43, v75
	v_mul_f32_e32 v76, v44, v76
	v_mul_f32_e32 v77, v45, v77
	v_mul_f32_e32 v78, v46, v78
	v_mul_f32_e32 v79, v47, v79
	v_fma_f32 v48, v48, s16, v64
	v_fma_f32 v49, v49, s16, v65
	v_fma_f32 v50, v50, s16, v66
	v_fma_f32 v51, v51, s16, v67
	v_fma_f32 v52, v52, s16, v68
	v_fma_f32 v53, v53, s16, v69
	v_fma_f32 v54, v54, s16, v70
	v_fma_f32 v55, v55, s16, v71
	v_fma_f32 v56, v56, s16, v72
	v_fma_f32 v57, v57, s16, v73
	v_fma_f32 v58, v58, s16, v74
	v_fma_f32 v59, v59, s16, v75
	v_fma_f32 v60, v60, s16, v76
	v_fma_f32 v61, v61, s16, v77
	v_fma_f32 v62, v62, s16, v78
	v_fma_f32 v63, v63, s16, v79
	v_add_f32_e32 v146, v48, v49
	v_add_f32_e32 v146, v146, v50
	v_add_f32_e32 v146, v146, v51
	v_add_f32_e32 v146, v146, v52
	v_add_f32_e32 v146, v146, v53
	v_add_f32_e32 v146, v146, v54
	v_add_f32_e32 v146, v146, v55
	v_add_f32_e32 v146, v146, v56
	v_add_f32_e32 v146, v146, v57
	v_add_f32_e32 v146, v146, v58
	v_add_f32_e32 v146, v146, v59
	v_add_f32_e32 v146, v146, v60
	v_add_f32_e32 v146, v146, v61
	v_add_f32_e32 v146, v146, v62
	v_add_f32_e32 v146, v146, v63
	s_nop 1
	v_add_f32_dpp v146, v146, v146 quad_perm:[1,0,3,2] row_mask:0xf bank_mask:0xf
	s_nop 1
	v_add_f32_dpp v146, v146, v146 quad_perm:[2,3,0,1] row_mask:0xf bank_mask:0xf
	s_nop 1
	v_add_f32_dpp v146, v146, v146 row_half_mirror row_mask:0xf bank_mask:0xf
	s_nop 1
	v_add_f32_dpp v146, v146, v146 row_mirror row_mask:0xf bank_mask:0xf
	s_nop 1
	v_readlane_b32 s4, v146, 0
	v_readlane_b32 s5, v146, 16
	v_readlane_b32 s6, v146, 32
	v_readlane_b32 s7, v146, 48
	s_nop 1
	v_mov_b32_e32 v147, s4
	v_add_f32_e32 v147, s5, v147
	v_add_f32_e32 v147, s6, v147
	v_add_f32_e32 v147, s7, v147
	v_mul_f32_e32 v147, 0x3a800000, v147
	v_sub_f32_e32 v48, v48, v147
	v_sub_f32_e32 v49, v49, v147
	v_sub_f32_e32 v50, v50, v147
	v_sub_f32_e32 v51, v51, v147
	v_sub_f32_e32 v52, v52, v147
	v_sub_f32_e32 v53, v53, v147
	v_sub_f32_e32 v54, v54, v147
	v_sub_f32_e32 v55, v55, v147
	v_sub_f32_e32 v56, v56, v147
	v_sub_f32_e32 v57, v57, v147
	v_sub_f32_e32 v58, v58, v147
	v_sub_f32_e32 v59, v59, v147
	v_sub_f32_e32 v60, v60, v147
	v_sub_f32_e32 v61, v61, v147
	v_sub_f32_e32 v62, v62, v147
	v_sub_f32_e32 v63, v63, v147
	v_mul_f32_e32 v146, v48, v48
	v_mul_f32_e32 v148, v49, v49
	v_add_f32_e32 v146, v146, v148
	v_mul_f32_e32 v148, v50, v50
	v_add_f32_e32 v146, v146, v148
	v_mul_f32_e32 v148, v51, v51
	v_add_f32_e32 v146, v146, v148
	v_mul_f32_e32 v148, v52, v52
	v_add_f32_e32 v146, v146, v148
	v_mul_f32_e32 v148, v53, v53
	v_add_f32_e32 v146, v146, v148
	v_mul_f32_e32 v148, v54, v54
	v_add_f32_e32 v146, v146, v148
	v_mul_f32_e32 v148, v55, v55
	v_add_f32_e32 v146, v146, v148
	v_mul_f32_e32 v148, v56, v56
	v_add_f32_e32 v146, v146, v148
	v_mul_f32_e32 v148, v57, v57
	v_add_f32_e32 v146, v146, v148
	v_mul_f32_e32 v148, v58, v58
	v_add_f32_e32 v146, v146, v148
	v_mul_f32_e32 v148, v59, v59
	v_add_f32_e32 v146, v146, v148
	v_mul_f32_e32 v148, v60, v60
	v_add_f32_e32 v146, v146, v148
	v_mul_f32_e32 v148, v61, v61
	v_add_f32_e32 v146, v146, v148
	v_mul_f32_e32 v148, v62, v62
	v_add_f32_e32 v146, v146, v148
	v_mul_f32_e32 v148, v63, v63
	v_add_f32_e32 v146, v146, v148
	s_nop 1
	v_add_f32_dpp v146, v146, v146 quad_perm:[1,0,3,2] row_mask:0xf bank_mask:0xf
	s_nop 1
	v_add_f32_dpp v146, v146, v146 quad_perm:[2,3,0,1] row_mask:0xf bank_mask:0xf
	s_nop 1
	v_add_f32_dpp v146, v146, v146 row_half_mirror row_mask:0xf bank_mask:0xf
	s_nop 1
	v_add_f32_dpp v146, v146, v146 row_mirror row_mask:0xf bank_mask:0xf
	s_nop 1
	v_readlane_b32 s4, v146, 0
	v_readlane_b32 s5, v146, 16
	v_readlane_b32 s6, v146, 32
	v_readlane_b32 s7, v146, 48
	s_nop 1
	v_mov_b32_e32 v147, s4
	v_add_f32_e32 v147, s5, v147
	v_add_f32_e32 v147, s6, v147
	v_add_f32_e32 v147, s7, v147
	v_fmamk_f32 v147, v147, 0x3a800000, v163
	s_mov_b32 s4, 0x800000
	v_cmp_gt_f32_e32 vcc, s4, v147
	v_mul_f32_e32 v148, 0x4b800000, v147
	s_nop 1
	v_cndmask_b32_e32 v147, v147, v148, vcc
	v_rsq_f32_e32 v147, v147
	s_nop 0
	v_mul_f32_e32 v148, 0x45800000, v147
	v_cndmask_b32_e32 v147, v147, v148, vcc
	v_mul_f32_e32 v48, v48, v147
	v_mul_f32_e32 v49, v49, v147
	v_mul_f32_e32 v50, v50, v147
	v_mul_f32_e32 v51, v51, v147
	v_mul_f32_e32 v52, v52, v147
	v_mul_f32_e32 v53, v53, v147
	v_mul_f32_e32 v54, v54, v147
	v_mul_f32_e32 v55, v55, v147
	v_mul_f32_e32 v56, v56, v147
	v_mul_f32_e32 v57, v57, v147
	v_mul_f32_e32 v58, v58, v147
	v_mul_f32_e32 v59, v59, v147
	v_mul_f32_e32 v60, v60, v147
	v_mul_f32_e32 v61, v61, v147
	v_mul_f32_e32 v62, v62, v147
	v_mul_f32_e32 v63, v63, v147
	v_fma_f32 v48, v80, v48, v96
	v_fma_f32 v49, v81, v49, v97
	v_fma_f32 v50, v82, v50, v98
	v_fma_f32 v51, v83, v51, v99
	v_fma_f32 v52, v84, v52, v100
	v_fma_f32 v53, v85, v53, v101
	v_fma_f32 v54, v86, v54, v102
	v_fma_f32 v55, v87, v55, v103
	v_fma_f32 v56, v88, v56, v104
	v_fma_f32 v57, v89, v57, v105
	v_fma_f32 v58, v90, v58, v106
	v_fma_f32 v59, v91, v59, v107
	v_fma_f32 v60, v92, v60, v108
	v_fma_f32 v61, v93, v61, v109
	v_fma_f32 v62, v94, v62, v110
	v_fma_f32 v63, v95, v63, v111
	s_cmp_lg_u32 s12, 0
	s_cbranch_scc0 .Lgx_lastlayer_36
	global_store_dwordx4 v160, v[48:51], s[52:53] offset:0
	global_store_dwordx4 v160, v[52:55], s[52:53] offset:16
	global_store_dwordx4 v160, v[56:59], s[52:53] offset:32
	global_store_dwordx4 v160, v[60:63], s[52:53] offset:48
	v_add_f32_e32 v130, 1.0, v130
	v_add_f32_e32 v131, 1.0, v131
	v_add_f32_e32 v132, 1.0, v132
	v_add_f32_e32 v133, 1.0, v133
	v_add_f32_e32 v134, 1.0, v134
	v_add_f32_e32 v135, 1.0, v135
	v_add_f32_e32 v136, 1.0, v136
	v_add_f32_e32 v137, 1.0, v137
	v_add_f32_e32 v138, 1.0, v138
	v_add_f32_e32 v139, 1.0, v139
	v_add_f32_e32 v140, 1.0, v140
	v_add_f32_e32 v141, 1.0, v141
	v_add_f32_e32 v142, 1.0, v142
	v_add_f32_e32 v143, 1.0, v143
	v_add_f32_e32 v144, 1.0, v144
	v_add_f32_e32 v145, 1.0, v145
	v_fma_f32 v112, v48, v130, v112
	v_fma_f32 v113, v49, v131, v113
	v_fma_f32 v114, v50, v132, v114
	v_fma_f32 v115, v51, v133, v115
	v_fma_f32 v116, v52, v134, v116
	v_fma_f32 v117, v53, v135, v117
	v_fma_f32 v118, v54, v136, v118
	v_fma_f32 v119, v55, v137, v119
	v_fma_f32 v120, v56, v138, v120
	v_fma_f32 v121, v57, v139, v121
	v_fma_f32 v122, v58, v140, v122
	v_fma_f32 v123, v59, v141, v123
	v_fma_f32 v124, v60, v142, v124
	v_fma_f32 v125, v61, v143, v125
	v_fma_f32 v126, v62, v144, v126
	v_fma_f32 v127, v63, v145, v127
	v_cvt_pk_bf16_f32 v64, v112, v113
	v_cvt_pk_bf16_f32 v65, v114, v115
	v_cvt_pk_bf16_f32 v66, v116, v117
	v_cvt_pk_bf16_f32 v67, v118, v119
	v_cvt_pk_bf16_f32 v68, v120, v121
	v_cvt_pk_bf16_f32 v69, v122, v123
	v_cvt_pk_bf16_f32 v70, v124, v125
	v_cvt_pk_bf16_f32 v71, v126, v127
	s_lshl_b32 s50, s2, 11
	s_add_u32 s46, s74, s50
	s_addc_u32 s47, s75, 0
	global_store_dwordx4 v159, v[64:67], s[46:47]
	global_store_dwordx4 v159, v[68:71], s[46:47] offset:16
	s_branch .Lgx_stdone_37

.Lgx_epidone_34:
	s_add_u32 s54, s54, s59
	s_add_u32 s54, s54, s59
	s_add_u32 s54, s54, s59
	s_cmp_lt_u32 s54, 0x4200
	s_cbranch_scc1 .Lgx_round_1
	s_waitcnt vmcnt(0)
	s_mov_b64 s[30:31], -1
	s_branch .LBB1_48
